# on top of v5: first K-iteration of each unit peeled with srcC=0 on first-touch MFMAs; header accumulator zeroing (128 v_mov per unit) removed; trampolines for far branches
# speedup vs baseline: 1.0044x; 1.0044x over previous
;     __host__ __device__ bool next(int i, Unit& u) const { const bool ok = StaticOrder::next(i, u); u.lm = 0; u.ln = 0; return ok; }
; #define PG8_STAGE(bufoff, gbase, voff) do { _Pragma("unroll") for (int _i = 0; _i < 2; ++_i) \
;         __builtin_amdgcn_global_load_lds((const unsigned*)((const char*)(gbase) + (voff)[_i]), (PG8_LAS unsigned*)(lds + (bufoff) + ldsw + _i * 8192), 16, 0, 0); } while (0)
; #define PG8_LDA(dst, b, h) do { _Pragma("unroll") for (int m = 0; m < 4; ++m) _Pragma("unroll") for (int k = 0; k < 2; ++k) dst[m][k] = *(const PG8_LAS bf16x8*)(lds + PG8_SA(b, h) + aoff + m * 2048 + k * 1024); } while (0)
; #define PG8_LDB(dst, b, h) do { _Pragma("unroll") for (int n = 0; n < 2; ++n) _Pragma("unroll") for (int k = 0; k < 2; ++k) dst[n][k] = *(const PG8_LAS bf16x8*)(lds + PG8_SB(b, h) + boff + n * 2048 + k * 1024); } while (0)
; #define PG8_WAIT_V(n) asm volatile("s_waitcnt vmcnt(" #n ")" ::: "memory")
; #define PG8_BAR __builtin_amdgcn_s_barrier()
; template <class Epi, class Sched, bool ALIGN_EPI = false, bool SP2 = false>
; __device__ __forceinline__ void gemm_phase(PG8_LAS unsigned char* lds, const Gemm g, const Sched& S, const Epi& E, const int wave_id) {
;     ...
;         const bool has_next = S.next(ui + 1, nxt);
;         const char* nA = has_next ? (const char*)g.A + (size_t)nxt.lm * tstep : cA; const char* nB = has_next ? (const char*)g.Bt + (size_t)nxt.ln * tstep : cB;
; #pragma unroll 1
;         for (int t = 0; t < nt; t += 2) {
;             const bool last = (t == nt - 2);
;             const char* a1 = cA + (size_t)(t + 1) * kstep;
;             const char* a2 = last ? nA : cA + (size_t)(t + 2) * kstep; const char* b2 = last ? nB : cB + (size_t)(t + 2) * kstep;
;             const char* a3 = a2 + kstep; const char* b3 = b2 + kstep;
;             if (last && has_next) S.a_ready(nxt);
;             if constexpr (SP2) {
;             PG8_LDB(B0, 0, 0); PG8_LDB(B1, 0, 1); PG8_SCHED; PG8_LDA(At, 0, 0); PG8_STAGE(PG8_SA(1, 1), a1 + hstep, voffA);
;             PG8_WAIT_V(8); PG8_WAIT_L(0); PG8_BAR; PG8_MMA(0, 0, At, B0); PG8_MMA(0, 1, At, B1); PG8_BAR; PG8_SCHED;
;             PG8_LDA(At, 0, 1); PG8_STAGE(PG8_SB(0, 0), b2, voffB); PG8_STAGE(PG8_SB(0, 1), b2 + hstep, voffB); PG8_STAGE(PG8_SA(0, 0), a2, voffA);
;             PG8_WAIT_V(8); PG8_WAIT_L(0); PG8_BAR; PG8_MMA(1, 0, At, B0); PG8_MMA(1, 1, At, B1); PG8_BAR; PG8_SCHED;
.LBB0_173:
	s_ashr_i32 s15, s14, 31
	s_lshl_b64 s[16:17], s[14:15], 20
	s_add_u32 s16, s49, s16
	s_addc_u32 s17, s52, s17
	s_and_b64 s[18:19], s[38:39], exec
	s_cselect_b32 s15, s17, s21
	s_cselect_b32 s41, s16, s20
	s_ashr_i32 s13, s12, 31
	s_lshl_b64 s[18:19], s[12:13], 20
	s_add_u32 s18, s47, s18
	s_addc_u32 s19, s48, s19
	s_and_b64 s[44:45], s[38:39], exec
	s_cselect_b32 s13, s19, s43
	s_cselect_b32 s72, s18, s42
	s_add_u32 s20, s20, 0x80080
	s_addc_u32 s21, s21, 0
	s_add_u32 s73, s42, 0x100
	s_addc_u32 s74, s43, 0
	s_mov_b32 s75, -2
	v_add_u32_e32 v230, 0x10000, v171
	s_add_u32 s42, s20, 0xfff80080
	s_addc_u32 s43, s21, -1
	s_add_i32 s76, 0, 0x10000
	s_cmp_eq_u32 s75, 28
	s_cselect_b32 s45, s15, s43
	s_cselect_b32 s44, s41, s42
	s_cselect_b32 s43, s13, s74
	s_cselect_b32 s42, s72, s73
	s_add_i32 s79, 0, 0x14000
	s_add_i32 m0, s56, 0xc000
	s_nop 0
	global_load_lds_dwordx4 v138, s[20:21]
	ds_read_b128 v[142:145], v230
	ds_read_b128 v[146:149], v230 offset:1024
	ds_read_b128 v[150:153], v230 offset:2048
	ds_read_b128 v[154:157], v230 offset:3072
	ds_read_b128 v[158:161], v230 offset:16384
	ds_read_b128 v[162:165], v230 offset:17408
	ds_read_b128 v[166:169], v230 offset:18432
	ds_read_b128 v[178:181], v230 offset:19456
	s_add_i32 m0, s56, 0xe000
	s_nop 0
	global_load_lds_dwordx4 v140, s[20:21]
	ds_read_b128 v[182:185], v175
	ds_read_b128 v[186:189], v175 offset:1024
	ds_read_b128 v[190:193], v175 offset:2048
	ds_read_b128 v[206:209], v175 offset:3072
	ds_read_b128 v[210:213], v175 offset:4096
	ds_read_b128 v[214:217], v175 offset:5120
	ds_read_b128 v[226:229], v175 offset:6144
	ds_read_b128 v[234:237], v175 offset:7168
	s_waitcnt vmcnt(8)
	s_waitcnt lgkmcnt(0)
	s_barrier
	s_setprio 1
	s_waitcnt lgkmcnt(0)
	v_mfma_f32_16x16x32_bf16 v[126:129], v[142:145], v[182:185], 0
	v_mfma_f32_16x16x32_bf16 v[118:121], v[150:153], v[182:185], 0
	v_mfma_f32_16x16x32_bf16 v[110:113], v[142:145], v[190:193], 0
	v_mfma_f32_16x16x32_bf16 v[102:105], v[150:153], v[190:193], 0
	v_mfma_f32_16x16x32_bf16 v[94:97], v[142:145], v[210:213], 0
	v_mfma_f32_16x16x32_bf16 v[86:89], v[150:153], v[210:213], 0
	v_mfma_f32_16x16x32_bf16 v[78:81], v[142:145], v[226:229], 0
	v_mfma_f32_16x16x32_bf16 v[70:73], v[150:153], v[226:229], 0
	v_mfma_f32_16x16x32_bf16 v[126:129], v[146:149], v[186:189], v[126:129]
	v_mfma_f32_16x16x32_bf16 v[118:121], v[154:157], v[186:189], v[118:121]
	v_mfma_f32_16x16x32_bf16 v[110:113], v[146:149], v[206:209], v[110:113]
	v_mfma_f32_16x16x32_bf16 v[102:105], v[154:157], v[206:209], v[102:105]
	v_mfma_f32_16x16x32_bf16 v[94:97], v[146:149], v[214:217], v[94:97]
	v_mfma_f32_16x16x32_bf16 v[86:89], v[154:157], v[214:217], v[86:89]
	v_mfma_f32_16x16x32_bf16 v[78:81], v[146:149], v[234:237], v[78:81]
	v_mfma_f32_16x16x32_bf16 v[70:73], v[154:157], v[234:237], v[70:73]
	s_setprio 0
	s_setprio 1
	v_mfma_f32_16x16x32_bf16 v[122:125], v[158:161], v[182:185], 0
	v_mfma_f32_16x16x32_bf16 v[114:117], v[166:169], v[182:185], 0
	v_mfma_f32_16x16x32_bf16 v[106:109], v[158:161], v[190:193], 0
	v_mfma_f32_16x16x32_bf16 v[98:101], v[166:169], v[190:193], 0
	v_mfma_f32_16x16x32_bf16 v[90:93], v[158:161], v[210:213], 0
	v_mfma_f32_16x16x32_bf16 v[82:85], v[166:169], v[210:213], 0
	v_mfma_f32_16x16x32_bf16 v[74:77], v[158:161], v[226:229], 0
	v_mfma_f32_16x16x32_bf16 v[66:69], v[166:169], v[226:229], 0
	v_mfma_f32_16x16x32_bf16 v[122:125], v[162:165], v[186:189], v[122:125]
	v_mfma_f32_16x16x32_bf16 v[114:117], v[178:181], v[186:189], v[114:117]
	v_mfma_f32_16x16x32_bf16 v[106:109], v[162:165], v[206:209], v[106:109]
	v_mfma_f32_16x16x32_bf16 v[98:101], v[178:181], v[206:209], v[98:101]
	v_mfma_f32_16x16x32_bf16 v[90:93], v[162:165], v[214:217], v[90:93]
	v_mfma_f32_16x16x32_bf16 v[82:85], v[178:181], v[214:217], v[82:85]
	v_mfma_f32_16x16x32_bf16 v[74:77], v[162:165], v[234:237], v[74:77]
	v_mfma_f32_16x16x32_bf16 v[66:69], v[178:181], v[234:237], v[66:69]
	s_setprio 0
	s_barrier
	s_add_i32 s76, s76, s53
	s_mov_b32 m0, s76
	s_nop 0
	global_load_lds_dwordx4 v132, s[42:43]
	ds_read_b128 v[182:185], v175 offset:16384
	ds_read_b128 v[186:189], v175 offset:17408
	s_add_i32 m0, s76, 0x2000
	s_add_u32 s76, s42, 0x80000
	s_addc_u32 s77, s43, 0
	s_add_i32 s79, s79, s53
	global_load_lds_dwordx4 v136, s[42:43]
	ds_read_b128 v[190:193], v175 offset:18432
	ds_read_b128 v[206:209], v175 offset:19456
	s_mov_b32 m0, s79
	s_nop 0
	global_load_lds_dwordx4 v132, s[76:77]
	ds_read_b128 v[210:213], v175 offset:20480
	ds_read_b128 v[214:217], v175 offset:21504
	s_add_i32 m0, s79, 0x2000
	s_nop 0
	global_load_lds_dwordx4 v136, s[76:77]
	ds_read_b128 v[226:229], v175 offset:22528
	ds_read_b128 v[234:237], v175 offset:23552
	s_mov_b32 m0, s56
	s_nop 0
	global_load_lds_dwordx4 v130, s[44:45]
	s_mov_b32 m0, s57
	s_nop 0
	global_load_lds_dwordx4 v134, s[44:45]
	s_waitcnt vmcnt(8)
	s_waitcnt lgkmcnt(0)
	s_barrier
; #define PG8_STAGE(bufoff, gbase, voff) do { _Pragma("unroll") for (int _i = 0; _i < 2; ++_i) \
;         __builtin_amdgcn_global_load_lds((const unsigned*)((const char*)(gbase) + (voff)[_i]), (PG8_LAS unsigned*)(lds + (bufoff) + ldsw + _i * 8192), 16, 0, 0); } while (0)
; #define PG8_LDA(dst, b, h) do { _Pragma("unroll") for (int m = 0; m < 4; ++m) _Pragma("unroll") for (int k = 0; k < 2; ++k) dst[m][k] = *(const PG8_LAS bf16x8*)(lds + PG8_SA(b, h) + aoff + m * 2048 + k * 1024); } while (0)
; #define PG8_LDB(dst, b, h) do { _Pragma("unroll") for (int n = 0; n < 2; ++n) _Pragma("unroll") for (int k = 0; k < 2; ++k) dst[n][k] = *(const PG8_LAS bf16x8*)(lds + PG8_SB(b, h) + boff + n * 2048 + k * 1024); } while (0)
; #define PG8_MMA(ai, bj, At, Bt) do { __builtin_amdgcn_s_setprio(1); _Pragma("unroll") for (int m = 0; m < 4; ++m) _Pragma("unroll") for (int n = 0; n < 2; ++n) _Pragma("unroll") for (int k = 0; k < 2; ++k) \
;         acc[ai][bj][m][n] = __builtin_amdgcn_mfma_f32_16x16x32_bf16(Bt[n][k], At[m][k], acc[ai][bj][m][n], 0, 0, 0); __builtin_amdgcn_s_setprio(0); } while (0)
; #define PG8_WAIT_V(n) asm volatile("s_waitcnt vmcnt(" #n ")" ::: "memory")
; #define PG8_WAIT_L(n) asm volatile("s_waitcnt lgkmcnt(" #n ")" ::: "memory")
; #define PG8_BAR __builtin_amdgcn_s_barrier()
; #define PG8_SCHED __builtin_amdgcn_sched_barrier(0)
; template <class Epi, class Sched, bool ALIGN_EPI = false, bool SP2 = false>
; __device__ __forceinline__ void gemm_phase(PG8_LAS unsigned char* lds, const Gemm g, const Sched& S, const Epi& E, const int wave_id) {
;     ...
;             PG8_WAIT_V(8); PG8_WAIT_L(0); PG8_BAR; PG8_MMA(1, 0, At, B0); PG8_MMA(1, 1, At, B1); PG8_BAR; PG8_SCHED;
;             PG8_LDB(B0, 1, 0); PG8_LDB(B1, 1, 1); PG8_SCHED; PG8_LDA(At, 1, 0); PG8_STAGE(PG8_SA(0, 1), a2 + hstep, voffA);
;             PG8_WAIT_V(8); PG8_WAIT_L(0); PG8_BAR; PG8_MMA(0, 0, At, B0); PG8_MMA(0, 1, At, B1); PG8_BAR; PG8_SCHED;
	s_setprio 1
	s_waitcnt lgkmcnt(0)
	v_mfma_f32_16x16x32_bf16 v[62:65], v[142:145], v[182:185], 0
	v_mfma_f32_16x16x32_bf16 v[54:57], v[150:153], v[182:185], 0
	v_mfma_f32_16x16x32_bf16 v[46:49], v[142:145], v[190:193], 0
	v_mfma_f32_16x16x32_bf16 v[38:41], v[150:153], v[190:193], 0
	v_mfma_f32_16x16x32_bf16 v[30:33], v[142:145], v[210:213], 0
	v_mfma_f32_16x16x32_bf16 v[22:25], v[150:153], v[210:213], 0
	v_mfma_f32_16x16x32_bf16 v[14:17], v[142:145], v[226:229], 0
	v_mfma_f32_16x16x32_bf16 v[6:9], v[150:153], v[226:229], 0
	v_mfma_f32_16x16x32_bf16 v[62:65], v[146:149], v[186:189], v[62:65]
	v_mfma_f32_16x16x32_bf16 v[54:57], v[154:157], v[186:189], v[54:57]
	v_mfma_f32_16x16x32_bf16 v[46:49], v[146:149], v[206:209], v[46:49]
	v_mfma_f32_16x16x32_bf16 v[38:41], v[154:157], v[206:209], v[38:41]
	v_mfma_f32_16x16x32_bf16 v[30:33], v[146:149], v[214:217], v[30:33]
	v_mfma_f32_16x16x32_bf16 v[22:25], v[154:157], v[214:217], v[22:25]
	v_mfma_f32_16x16x32_bf16 v[14:17], v[146:149], v[234:237], v[14:17]
	v_mfma_f32_16x16x32_bf16 v[6:9], v[154:157], v[234:237], v[6:9]
	s_setprio 0
	s_setprio 1
	v_mfma_f32_16x16x32_bf16 v[58:61], v[158:161], v[182:185], 0
	v_mfma_f32_16x16x32_bf16 v[50:53], v[166:169], v[182:185], 0
	v_mfma_f32_16x16x32_bf16 v[42:45], v[158:161], v[190:193], 0
	v_mfma_f32_16x16x32_bf16 v[34:37], v[166:169], v[190:193], 0
	v_mfma_f32_16x16x32_bf16 v[26:29], v[158:161], v[210:213], 0
	v_mfma_f32_16x16x32_bf16 v[18:21], v[166:169], v[210:213], 0
	v_mfma_f32_16x16x32_bf16 v[10:13], v[158:161], v[226:229], 0
	v_mfma_f32_16x16x32_bf16 v[2:5], v[166:169], v[226:229], 0
	v_mfma_f32_16x16x32_bf16 v[58:61], v[162:165], v[186:189], v[58:61]
	v_mfma_f32_16x16x32_bf16 v[50:53], v[178:181], v[186:189], v[50:53]
	v_mfma_f32_16x16x32_bf16 v[42:45], v[162:165], v[206:209], v[42:45]
	v_mfma_f32_16x16x32_bf16 v[34:37], v[178:181], v[206:209], v[34:37]
	v_mfma_f32_16x16x32_bf16 v[26:29], v[162:165], v[214:217], v[26:29]
	v_mfma_f32_16x16x32_bf16 v[18:21], v[178:181], v[214:217], v[18:21]
	v_mfma_f32_16x16x32_bf16 v[10:13], v[162:165], v[234:237], v[10:13]
	v_mfma_f32_16x16x32_bf16 v[2:5], v[178:181], v[234:237], v[2:5]
	s_setprio 0
	s_barrier
	s_add_i32 s76, 0, 0x18000
	s_add_i32 s77, 0, 0x1c000
	s_add_u32 s44, s44, 0x80000
	s_addc_u32 s45, s45, 0
	s_mov_b32 m0, s64
	s_nop 0
	global_load_lds_dwordx4 v130, s[44:45]
	ds_read_b128 v[142:145], v230 offset:32768
	ds_read_b128 v[146:149], v230 offset:33792
	ds_read_b128 v[150:153], v230 offset:34816
	ds_read_b128 v[154:157], v230 offset:35840
	ds_read_b128 v[158:161], v230 offset:49152
	ds_read_b128 v[162:165], v230 offset:50176
	ds_read_b128 v[166:169], v230 offset:51200
	ds_read_b128 v[178:181], v230 offset:52224
	s_mov_b32 m0, s65
	s_nop 0
	global_load_lds_dwordx4 v134, s[44:45]
	ds_read_b128 v[182:185], v175 offset:32768
	ds_read_b128 v[186:189], v175 offset:33792
	ds_read_b128 v[190:193], v175 offset:34816
	ds_read_b128 v[206:209], v175 offset:35840
	ds_read_b128 v[210:213], v175 offset:36864
	ds_read_b128 v[214:217], v175 offset:37888
	ds_read_b128 v[226:229], v175 offset:38912
	ds_read_b128 v[234:237], v175 offset:39936
	s_waitcnt vmcnt(8)
	s_waitcnt lgkmcnt(0)
	s_barrier
	s_setprio 1
	s_waitcnt lgkmcnt(0)
	v_mfma_f32_16x16x32_bf16 v[126:129], v[142:145], v[182:185], v[126:129]
	v_mfma_f32_16x16x32_bf16 v[118:121], v[150:153], v[182:185], v[118:121]
	v_mfma_f32_16x16x32_bf16 v[110:113], v[142:145], v[190:193], v[110:113]
	v_mfma_f32_16x16x32_bf16 v[102:105], v[150:153], v[190:193], v[102:105]
	v_mfma_f32_16x16x32_bf16 v[94:97], v[142:145], v[210:213], v[94:97]
	v_mfma_f32_16x16x32_bf16 v[86:89], v[150:153], v[210:213], v[86:89]
	v_mfma_f32_16x16x32_bf16 v[78:81], v[142:145], v[226:229], v[78:81]
	v_mfma_f32_16x16x32_bf16 v[70:73], v[150:153], v[226:229], v[70:73]
	v_mfma_f32_16x16x32_bf16 v[126:129], v[146:149], v[186:189], v[126:129]
	v_mfma_f32_16x16x32_bf16 v[118:121], v[154:157], v[186:189], v[118:121]
	v_mfma_f32_16x16x32_bf16 v[110:113], v[146:149], v[206:209], v[110:113]
	v_mfma_f32_16x16x32_bf16 v[102:105], v[154:157], v[206:209], v[102:105]
	v_mfma_f32_16x16x32_bf16 v[94:97], v[146:149], v[214:217], v[94:97]
	v_mfma_f32_16x16x32_bf16 v[86:89], v[154:157], v[214:217], v[86:89]
	v_mfma_f32_16x16x32_bf16 v[78:81], v[146:149], v[234:237], v[78:81]
	v_mfma_f32_16x16x32_bf16 v[70:73], v[154:157], v[234:237], v[70:73]
	s_setprio 0
	s_setprio 1
	v_mfma_f32_16x16x32_bf16 v[122:125], v[158:161], v[182:185], v[122:125]
	v_mfma_f32_16x16x32_bf16 v[114:117], v[166:169], v[182:185], v[114:117]
	v_mfma_f32_16x16x32_bf16 v[106:109], v[158:161], v[190:193], v[106:109]
	v_mfma_f32_16x16x32_bf16 v[98:101], v[166:169], v[190:193], v[98:101]
	v_mfma_f32_16x16x32_bf16 v[90:93], v[158:161], v[210:213], v[90:93]
	v_mfma_f32_16x16x32_bf16 v[82:85], v[166:169], v[210:213], v[82:85]
	v_mfma_f32_16x16x32_bf16 v[74:77], v[158:161], v[226:229], v[74:77]
	v_mfma_f32_16x16x32_bf16 v[66:69], v[166:169], v[226:229], v[66:69]
	v_mfma_f32_16x16x32_bf16 v[122:125], v[162:165], v[186:189], v[122:125]
	v_mfma_f32_16x16x32_bf16 v[114:117], v[178:181], v[186:189], v[114:117]
	v_mfma_f32_16x16x32_bf16 v[106:109], v[162:165], v[206:209], v[106:109]
	v_mfma_f32_16x16x32_bf16 v[98:101], v[178:181], v[206:209], v[98:101]
	v_mfma_f32_16x16x32_bf16 v[90:93], v[162:165], v[214:217], v[90:93]
	v_mfma_f32_16x16x32_bf16 v[82:85], v[178:181], v[214:217], v[82:85]
	v_mfma_f32_16x16x32_bf16 v[74:77], v[162:165], v[234:237], v[74:77]
	v_mfma_f32_16x16x32_bf16 v[66:69], v[178:181], v[234:237], v[66:69]
	s_setprio 0
	s_barrier
; #define PG8_STAGE(bufoff, gbase, voff) do { _Pragma("unroll") for (int _i = 0; _i < 2; ++_i) \
;         __builtin_amdgcn_global_load_lds((const unsigned*)((const char*)(gbase) + (voff)[_i]), (PG8_LAS unsigned*)(lds + (bufoff) + ldsw + _i * 8192), 16, 0, 0); } while (0)
; #define PG8_LDA(dst, b, h) do { _Pragma("unroll") for (int m = 0; m < 4; ++m) _Pragma("unroll") for (int k = 0; k < 2; ++k) dst[m][k] = *(const PG8_LAS bf16x8*)(lds + PG8_SA(b, h) + aoff + m * 2048 + k * 1024); } while (0)
; #define PG8_LDB(dst, b, h) do { _Pragma("unroll") for (int n = 0; n < 2; ++n) _Pragma("unroll") for (int k = 0; k < 2; ++k) dst[n][k] = *(const PG8_LAS bf16x8*)(lds + PG8_SB(b, h) + boff + n * 2048 + k * 1024); } while (0)
; #define PG8_MMA(ai, bj, At, Bt) do { __builtin_amdgcn_s_setprio(1); _Pragma("unroll") for (int m = 0; m < 4; ++m) _Pragma("unroll") for (int n = 0; n < 2; ++n) _Pragma("unroll") for (int k = 0; k < 2; ++k) \
;         acc[ai][bj][m][n] = __builtin_amdgcn_mfma_f32_16x16x32_bf16(Bt[n][k], At[m][k], acc[ai][bj][m][n], 0, 0, 0); __builtin_amdgcn_s_setprio(0); } while (0)
; #define PG8_WAIT_V(n) asm volatile("s_waitcnt vmcnt(" #n ")" ::: "memory")
; #define PG8_WAIT_L(n) asm volatile("s_waitcnt lgkmcnt(" #n ")" ::: "memory")
; #define PG8_BAR __builtin_amdgcn_s_barrier()
; template <class Epi, class Sched, bool ALIGN_EPI = false, bool SP2 = false>
; __device__ __forceinline__ void gemm_phase(PG8_LAS unsigned char* lds, const Gemm g, const Sched& S, const Epi& E, const int wave_id) {
;     ...
;         for (int t = 0; t < nt; t += 2) {
;             const bool last = (t == nt - 2);
;             const char* a1 = cA + (size_t)(t + 1) * kstep;
;             const char* a2 = last ? nA : cA + (size_t)(t + 2) * kstep; const char* b2 = last ? nB : cB + (size_t)(t + 2) * kstep;
;             const char* a3 = a2 + kstep; const char* b3 = b2 + kstep;
;             if (last && has_next) S.a_ready(nxt);
;             if constexpr (SP2) {
;             PG8_LDB(B0, 0, 0); PG8_LDB(B1, 0, 1); PG8_SCHED; PG8_LDA(At, 0, 0); PG8_STAGE(PG8_SA(1, 1), a1 + hstep, voffA);
;     ...
;             PG8_LDA(At, 1, 1); PG8_STAGE(PG8_SB(1, 0), b3, voffB); PG8_STAGE(PG8_SB(1, 1), b3 + hstep, voffB); PG8_STAGE(PG8_SA(1, 0), a3, voffA);
;             PG8_WAIT_V(8); PG8_WAIT_L(0); PG8_BAR; PG8_MMA(1, 0, At, B0); PG8_MMA(1, 1, At, B1); PG8_BAR; PG8_SCHED;
	s_add_u32 vcc_lo, s44, 0xfff80080
	s_addc_u32 vcc_hi, s45, -1
	s_mov_b32 m0, s68
	s_nop 0
	global_load_lds_dwordx4 v130, vcc
	ds_read_b128 v[182:185], v175 offset:49152
	ds_read_b128 v[186:189], v175 offset:50176
	s_mov_b32 m0, s69
	s_add_i32 s44, s76, s53
	global_load_lds_dwordx4 v134, vcc
	ds_read_b128 v[190:193], v175 offset:51200
	ds_read_b128 v[206:209], v175 offset:52224
	s_add_u32 vcc_lo, s42, 0x80
	s_addc_u32 vcc_hi, s43, 0
	s_mov_b32 m0, s44
	s_nop 0
	global_load_lds_dwordx4 v132, vcc
	ds_read_b128 v[210:213], v175 offset:53248
	ds_read_b128 v[214:217], v175 offset:54272
	s_add_i32 m0, s44, 0x2000
	s_add_u32 s42, s42, 0x80080
	s_addc_u32 s43, s43, 0
	global_load_lds_dwordx4 v136, vcc
	ds_read_b128 v[226:229], v175 offset:55296
	ds_read_b128 v[234:237], v175 offset:56320
	s_add_i32 s44, s77, s53
	s_mov_b32 m0, s44
	s_nop 0
	global_load_lds_dwordx4 v132, s[42:43]
	s_add_i32 m0, s44, 0x2000
	s_nop 0
	global_load_lds_dwordx4 v136, s[42:43]
	s_waitcnt vmcnt(8)
	s_waitcnt lgkmcnt(0)
	s_barrier
	s_setprio 1
	s_waitcnt lgkmcnt(0)
	v_mfma_f32_16x16x32_bf16 v[62:65], v[142:145], v[182:185], v[62:65]
	v_mfma_f32_16x16x32_bf16 v[54:57], v[150:153], v[182:185], v[54:57]
	v_mfma_f32_16x16x32_bf16 v[46:49], v[142:145], v[190:193], v[46:49]
	v_mfma_f32_16x16x32_bf16 v[38:41], v[150:153], v[190:193], v[38:41]
	v_mfma_f32_16x16x32_bf16 v[30:33], v[142:145], v[210:213], v[30:33]
	v_mfma_f32_16x16x32_bf16 v[22:25], v[150:153], v[210:213], v[22:25]
	v_mfma_f32_16x16x32_bf16 v[14:17], v[142:145], v[226:229], v[14:17]
	v_mfma_f32_16x16x32_bf16 v[6:9], v[150:153], v[226:229], v[6:9]
	v_mfma_f32_16x16x32_bf16 v[62:65], v[146:149], v[186:189], v[62:65]
	v_mfma_f32_16x16x32_bf16 v[54:57], v[154:157], v[186:189], v[54:57]
	v_mfma_f32_16x16x32_bf16 v[46:49], v[146:149], v[206:209], v[46:49]
	v_mfma_f32_16x16x32_bf16 v[38:41], v[154:157], v[206:209], v[38:41]
	v_mfma_f32_16x16x32_bf16 v[30:33], v[146:149], v[214:217], v[30:33]
	v_mfma_f32_16x16x32_bf16 v[22:25], v[154:157], v[214:217], v[22:25]
	v_mfma_f32_16x16x32_bf16 v[14:17], v[146:149], v[234:237], v[14:17]
	v_mfma_f32_16x16x32_bf16 v[6:9], v[154:157], v[234:237], v[6:9]
	s_setprio 0
	s_setprio 1
	v_mfma_f32_16x16x32_bf16 v[58:61], v[158:161], v[182:185], v[58:61]
	v_mfma_f32_16x16x32_bf16 v[50:53], v[166:169], v[182:185], v[50:53]
	v_mfma_f32_16x16x32_bf16 v[42:45], v[158:161], v[190:193], v[42:45]
	v_mfma_f32_16x16x32_bf16 v[34:37], v[166:169], v[190:193], v[34:37]
	v_mfma_f32_16x16x32_bf16 v[26:29], v[158:161], v[210:213], v[26:29]
	v_mfma_f32_16x16x32_bf16 v[18:21], v[166:169], v[210:213], v[18:21]
	v_mfma_f32_16x16x32_bf16 v[10:13], v[158:161], v[226:229], v[10:13]
	v_mfma_f32_16x16x32_bf16 v[2:5], v[166:169], v[226:229], v[2:5]
	v_mfma_f32_16x16x32_bf16 v[58:61], v[162:165], v[186:189], v[58:61]
	v_mfma_f32_16x16x32_bf16 v[50:53], v[178:181], v[186:189], v[50:53]
	v_mfma_f32_16x16x32_bf16 v[42:45], v[162:165], v[206:209], v[42:45]
	v_mfma_f32_16x16x32_bf16 v[34:37], v[178:181], v[206:209], v[34:37]
	v_mfma_f32_16x16x32_bf16 v[26:29], v[162:165], v[214:217], v[26:29]
	v_mfma_f32_16x16x32_bf16 v[18:21], v[178:181], v[214:217], v[18:21]
	v_mfma_f32_16x16x32_bf16 v[10:13], v[162:165], v[234:237], v[10:13]
	v_mfma_f32_16x16x32_bf16 v[2:5], v[178:181], v[234:237], v[2:5]
	s_setprio 0
	s_barrier
	s_add_i32 s75, s75, 2
	s_add_u32 s20, s20, 0x100
	s_addc_u32 s21, s21, 0
	s_add_u32 s73, s73, 0x100
	s_addc_u32 s74, s74, 0
	s_cmp_gt_u32 s75, 29
	s_cbranch_scc1 .Lpeel_exit_g1
.LBB0_174:
	s_add_u32 s42, s20, 0xfff80080
	s_addc_u32 s43, s21, -1
	s_add_i32 s76, 0, 0x10000
	s_cmp_eq_u32 s75, 28
	s_cselect_b32 s45, s15, s43
	s_cselect_b32 s44, s41, s42
	s_cselect_b32 s43, s13, s74
	s_cselect_b32 s42, s72, s73
	s_add_i32 s79, 0, 0x14000
	s_add_i32 m0, s56, 0xc000
	s_nop 0
	global_load_lds_dwordx4 v138, s[20:21]
	ds_read_b128 v[142:145], v230
	ds_read_b128 v[146:149], v230 offset:1024
	ds_read_b128 v[150:153], v230 offset:2048
	ds_read_b128 v[154:157], v230 offset:3072
	ds_read_b128 v[158:161], v230 offset:16384
	ds_read_b128 v[162:165], v230 offset:17408
	ds_read_b128 v[166:169], v230 offset:18432
	ds_read_b128 v[178:181], v230 offset:19456
	s_add_i32 m0, s56, 0xe000
	s_nop 0
	global_load_lds_dwordx4 v140, s[20:21]
	ds_read_b128 v[182:185], v175
	ds_read_b128 v[186:189], v175 offset:1024
	ds_read_b128 v[190:193], v175 offset:2048
	ds_read_b128 v[206:209], v175 offset:3072
	ds_read_b128 v[210:213], v175 offset:4096
	ds_read_b128 v[214:217], v175 offset:5120
	ds_read_b128 v[226:229], v175 offset:6144
	ds_read_b128 v[234:237], v175 offset:7168
	s_waitcnt vmcnt(8)
	s_waitcnt lgkmcnt(0)
	s_barrier
; #define PG8_STAGE(bufoff, gbase, voff) do { _Pragma("unroll") for (int _i = 0; _i < 2; ++_i) \
;         __builtin_amdgcn_global_load_lds((const unsigned*)((const char*)(gbase) + (voff)[_i]), (PG8_LAS unsigned*)(lds + (bufoff) + ldsw + _i * 8192), 16, 0, 0); } while (0)
; #define PG8_LDA(dst, b, h) do { _Pragma("unroll") for (int m = 0; m < 4; ++m) _Pragma("unroll") for (int k = 0; k < 2; ++k) dst[m][k] = *(const PG8_LAS bf16x8*)(lds + PG8_SA(b, h) + aoff + m * 2048 + k * 1024); } while (0)
; #define PG8_LDB(dst, b, h) do { _Pragma("unroll") for (int n = 0; n < 2; ++n) _Pragma("unroll") for (int k = 0; k < 2; ++k) dst[n][k] = *(const PG8_LAS bf16x8*)(lds + PG8_SB(b, h) + boff + n * 2048 + k * 1024); } while (0)
; #define PG8_MMA(ai, bj, At, Bt) do { __builtin_amdgcn_s_setprio(1); _Pragma("unroll") for (int m = 0; m < 4; ++m) _Pragma("unroll") for (int n = 0; n < 2; ++n) _Pragma("unroll") for (int k = 0; k < 2; ++k) \
;         acc[ai][bj][m][n] = __builtin_amdgcn_mfma_f32_16x16x32_bf16(Bt[n][k], At[m][k], acc[ai][bj][m][n], 0, 0, 0); __builtin_amdgcn_s_setprio(0); } while (0)
; #define PG8_WAIT_V(n) asm volatile("s_waitcnt vmcnt(" #n ")" ::: "memory")
; #define PG8_WAIT_L(n) asm volatile("s_waitcnt lgkmcnt(" #n ")" ::: "memory")
; #define PG8_BAR __builtin_amdgcn_s_barrier()
; #define PG8_SCHED __builtin_amdgcn_sched_barrier(0)
; template <class Epi, class Sched, bool ALIGN_EPI = false, bool SP2 = false>
; __device__ __forceinline__ void gemm_phase(PG8_LAS unsigned char* lds, const Gemm g, const Sched& S, const Epi& E, const int wave_id) {
;     ...
;             PG8_LDB(B0, 0, 0); PG8_LDB(B1, 0, 1); PG8_SCHED; PG8_LDA(At, 0, 0); PG8_STAGE(PG8_SA(1, 1), a1 + hstep, voffA);
;             PG8_WAIT_V(8); PG8_WAIT_L(0); PG8_BAR; PG8_MMA(0, 0, At, B0); PG8_MMA(0, 1, At, B1); PG8_BAR; PG8_SCHED;
;             PG8_LDA(At, 0, 1); PG8_STAGE(PG8_SB(0, 0), b2, voffB); PG8_STAGE(PG8_SB(0, 1), b2 + hstep, voffB); PG8_STAGE(PG8_SA(0, 0), a2, voffA);
;             PG8_WAIT_V(8); PG8_WAIT_L(0); PG8_BAR; PG8_MMA(1, 0, At, B0); PG8_MMA(1, 1, At, B1); PG8_BAR; PG8_SCHED;
;             PG8_LDB(B0, 1, 0); PG8_LDB(B1, 1, 1); PG8_SCHED; PG8_LDA(At, 1, 0); PG8_STAGE(PG8_SA(0, 1), a2 + hstep, voffA);
	s_setprio 1
	s_waitcnt lgkmcnt(0)
	v_mfma_f32_16x16x32_bf16 v[126:129], v[142:145], v[182:185], v[126:129]
	v_mfma_f32_16x16x32_bf16 v[118:121], v[150:153], v[182:185], v[118:121]
	v_mfma_f32_16x16x32_bf16 v[110:113], v[142:145], v[190:193], v[110:113]
	v_mfma_f32_16x16x32_bf16 v[102:105], v[150:153], v[190:193], v[102:105]
	v_mfma_f32_16x16x32_bf16 v[94:97], v[142:145], v[210:213], v[94:97]
	v_mfma_f32_16x16x32_bf16 v[86:89], v[150:153], v[210:213], v[86:89]
	v_mfma_f32_16x16x32_bf16 v[78:81], v[142:145], v[226:229], v[78:81]
	v_mfma_f32_16x16x32_bf16 v[70:73], v[150:153], v[226:229], v[70:73]
	v_mfma_f32_16x16x32_bf16 v[126:129], v[146:149], v[186:189], v[126:129]
	v_mfma_f32_16x16x32_bf16 v[118:121], v[154:157], v[186:189], v[118:121]
	v_mfma_f32_16x16x32_bf16 v[110:113], v[146:149], v[206:209], v[110:113]
	v_mfma_f32_16x16x32_bf16 v[102:105], v[154:157], v[206:209], v[102:105]
	v_mfma_f32_16x16x32_bf16 v[94:97], v[146:149], v[214:217], v[94:97]
	v_mfma_f32_16x16x32_bf16 v[86:89], v[154:157], v[214:217], v[86:89]
	v_mfma_f32_16x16x32_bf16 v[78:81], v[146:149], v[234:237], v[78:81]
	v_mfma_f32_16x16x32_bf16 v[70:73], v[154:157], v[234:237], v[70:73]
	s_setprio 0
	s_setprio 1
	v_mfma_f32_16x16x32_bf16 v[122:125], v[158:161], v[182:185], v[122:125]
	v_mfma_f32_16x16x32_bf16 v[114:117], v[166:169], v[182:185], v[114:117]
	v_mfma_f32_16x16x32_bf16 v[106:109], v[158:161], v[190:193], v[106:109]
	v_mfma_f32_16x16x32_bf16 v[98:101], v[166:169], v[190:193], v[98:101]
	v_mfma_f32_16x16x32_bf16 v[90:93], v[158:161], v[210:213], v[90:93]
	v_mfma_f32_16x16x32_bf16 v[82:85], v[166:169], v[210:213], v[82:85]
	v_mfma_f32_16x16x32_bf16 v[74:77], v[158:161], v[226:229], v[74:77]
	v_mfma_f32_16x16x32_bf16 v[66:69], v[166:169], v[226:229], v[66:69]
	v_mfma_f32_16x16x32_bf16 v[122:125], v[162:165], v[186:189], v[122:125]
	v_mfma_f32_16x16x32_bf16 v[114:117], v[178:181], v[186:189], v[114:117]
	v_mfma_f32_16x16x32_bf16 v[106:109], v[162:165], v[206:209], v[106:109]
	v_mfma_f32_16x16x32_bf16 v[98:101], v[178:181], v[206:209], v[98:101]
	v_mfma_f32_16x16x32_bf16 v[90:93], v[162:165], v[214:217], v[90:93]
	v_mfma_f32_16x16x32_bf16 v[82:85], v[178:181], v[214:217], v[82:85]
	v_mfma_f32_16x16x32_bf16 v[74:77], v[162:165], v[234:237], v[74:77]
	v_mfma_f32_16x16x32_bf16 v[66:69], v[178:181], v[234:237], v[66:69]
	s_setprio 0
	s_barrier
	s_add_i32 s76, s76, s53
	s_mov_b32 m0, s76
	s_nop 0
	global_load_lds_dwordx4 v132, s[42:43]
	ds_read_b128 v[182:185], v175 offset:16384
	ds_read_b128 v[186:189], v175 offset:17408
	s_add_i32 m0, s76, 0x2000
	s_add_u32 s76, s42, 0x80000
	s_addc_u32 s77, s43, 0
	s_add_i32 s79, s79, s53
	global_load_lds_dwordx4 v136, s[42:43]
	ds_read_b128 v[190:193], v175 offset:18432
	ds_read_b128 v[206:209], v175 offset:19456
	s_mov_b32 m0, s79
	s_nop 0
	global_load_lds_dwordx4 v132, s[76:77]
	ds_read_b128 v[210:213], v175 offset:20480
	ds_read_b128 v[214:217], v175 offset:21504
	s_add_i32 m0, s79, 0x2000
	s_nop 0
	global_load_lds_dwordx4 v136, s[76:77]
	ds_read_b128 v[226:229], v175 offset:22528
	ds_read_b128 v[234:237], v175 offset:23552
	s_mov_b32 m0, s56
	s_nop 0
	global_load_lds_dwordx4 v130, s[44:45]
	s_mov_b32 m0, s57
	s_nop 0
	global_load_lds_dwordx4 v134, s[44:45]
	s_waitcnt vmcnt(8)
	s_waitcnt lgkmcnt(0)
	s_barrier
	s_setprio 1
	s_waitcnt lgkmcnt(0)
	v_mfma_f32_16x16x32_bf16 v[62:65], v[142:145], v[182:185], v[62:65]
	v_mfma_f32_16x16x32_bf16 v[54:57], v[150:153], v[182:185], v[54:57]
	v_mfma_f32_16x16x32_bf16 v[46:49], v[142:145], v[190:193], v[46:49]
	v_mfma_f32_16x16x32_bf16 v[38:41], v[150:153], v[190:193], v[38:41]
	v_mfma_f32_16x16x32_bf16 v[30:33], v[142:145], v[210:213], v[30:33]
	v_mfma_f32_16x16x32_bf16 v[22:25], v[150:153], v[210:213], v[22:25]
	v_mfma_f32_16x16x32_bf16 v[14:17], v[142:145], v[226:229], v[14:17]
	v_mfma_f32_16x16x32_bf16 v[6:9], v[150:153], v[226:229], v[6:9]
	v_mfma_f32_16x16x32_bf16 v[62:65], v[146:149], v[186:189], v[62:65]
	v_mfma_f32_16x16x32_bf16 v[54:57], v[154:157], v[186:189], v[54:57]
	v_mfma_f32_16x16x32_bf16 v[46:49], v[146:149], v[206:209], v[46:49]
	v_mfma_f32_16x16x32_bf16 v[38:41], v[154:157], v[206:209], v[38:41]
	v_mfma_f32_16x16x32_bf16 v[30:33], v[146:149], v[214:217], v[30:33]
	v_mfma_f32_16x16x32_bf16 v[22:25], v[154:157], v[214:217], v[22:25]
	v_mfma_f32_16x16x32_bf16 v[14:17], v[146:149], v[234:237], v[14:17]
	v_mfma_f32_16x16x32_bf16 v[6:9], v[154:157], v[234:237], v[6:9]
	s_setprio 0
	s_setprio 1
	v_mfma_f32_16x16x32_bf16 v[58:61], v[158:161], v[182:185], v[58:61]
	v_mfma_f32_16x16x32_bf16 v[50:53], v[166:169], v[182:185], v[50:53]
	v_mfma_f32_16x16x32_bf16 v[42:45], v[158:161], v[190:193], v[42:45]
	v_mfma_f32_16x16x32_bf16 v[34:37], v[166:169], v[190:193], v[34:37]
	v_mfma_f32_16x16x32_bf16 v[26:29], v[158:161], v[210:213], v[26:29]
	v_mfma_f32_16x16x32_bf16 v[18:21], v[166:169], v[210:213], v[18:21]
	v_mfma_f32_16x16x32_bf16 v[10:13], v[158:161], v[226:229], v[10:13]
	v_mfma_f32_16x16x32_bf16 v[2:5], v[166:169], v[226:229], v[2:5]
	v_mfma_f32_16x16x32_bf16 v[58:61], v[162:165], v[186:189], v[58:61]
	v_mfma_f32_16x16x32_bf16 v[50:53], v[178:181], v[186:189], v[50:53]
	v_mfma_f32_16x16x32_bf16 v[42:45], v[162:165], v[206:209], v[42:45]
	v_mfma_f32_16x16x32_bf16 v[34:37], v[178:181], v[206:209], v[34:37]
	v_mfma_f32_16x16x32_bf16 v[26:29], v[162:165], v[214:217], v[26:29]
	v_mfma_f32_16x16x32_bf16 v[18:21], v[178:181], v[214:217], v[18:21]
	v_mfma_f32_16x16x32_bf16 v[10:13], v[162:165], v[234:237], v[10:13]
	v_mfma_f32_16x16x32_bf16 v[2:5], v[178:181], v[234:237], v[2:5]
	s_setprio 0
	s_barrier
; #define PG8_STAGE(bufoff, gbase, voff) do { _Pragma("unroll") for (int _i = 0; _i < 2; ++_i) \
;         __builtin_amdgcn_global_load_lds((const unsigned*)((const char*)(gbase) + (voff)[_i]), (PG8_LAS unsigned*)(lds + (bufoff) + ldsw + _i * 8192), 16, 0, 0); } while (0)
; #define PG8_LDA(dst, b, h) do { _Pragma("unroll") for (int m = 0; m < 4; ++m) _Pragma("unroll") for (int k = 0; k < 2; ++k) dst[m][k] = *(const PG8_LAS bf16x8*)(lds + PG8_SA(b, h) + aoff + m * 2048 + k * 1024); } while (0)
; #define PG8_LDB(dst, b, h) do { _Pragma("unroll") for (int n = 0; n < 2; ++n) _Pragma("unroll") for (int k = 0; k < 2; ++k) dst[n][k] = *(const PG8_LAS bf16x8*)(lds + PG8_SB(b, h) + boff + n * 2048 + k * 1024); } while (0)
; #define PG8_MMA(ai, bj, At, Bt) do { __builtin_amdgcn_s_setprio(1); _Pragma("unroll") for (int m = 0; m < 4; ++m) _Pragma("unroll") for (int n = 0; n < 2; ++n) _Pragma("unroll") for (int k = 0; k < 2; ++k) \
;         acc[ai][bj][m][n] = __builtin_amdgcn_mfma_f32_16x16x32_bf16(Bt[n][k], At[m][k], acc[ai][bj][m][n], 0, 0, 0); __builtin_amdgcn_s_setprio(0); } while (0)
; #define PG8_WAIT_V(n) asm volatile("s_waitcnt vmcnt(" #n ")" ::: "memory")
; #define PG8_WAIT_L(n) asm volatile("s_waitcnt lgkmcnt(" #n ")" ::: "memory")
; #define PG8_BAR __builtin_amdgcn_s_barrier()
; #define PG8_SCHED __builtin_amdgcn_sched_barrier(0)
; template <class Epi, class Sched, bool ALIGN_EPI = false, bool SP2 = false>
; __device__ __forceinline__ void gemm_phase(PG8_LAS unsigned char* lds, const Gemm g, const Sched& S, const Epi& E, const int wave_id) {
;     ...
;             PG8_LDB(B0, 1, 0); PG8_LDB(B1, 1, 1); PG8_SCHED; PG8_LDA(At, 1, 0); PG8_STAGE(PG8_SA(0, 1), a2 + hstep, voffA);
;             PG8_WAIT_V(8); PG8_WAIT_L(0); PG8_BAR; PG8_MMA(0, 0, At, B0); PG8_MMA(0, 1, At, B1); PG8_BAR; PG8_SCHED;
;             PG8_LDA(At, 1, 1); PG8_STAGE(PG8_SB(1, 0), b3, voffB); PG8_STAGE(PG8_SB(1, 1), b3 + hstep, voffB); PG8_STAGE(PG8_SA(1, 0), a3, voffA);
;             PG8_WAIT_V(8); PG8_WAIT_L(0); PG8_BAR; PG8_MMA(1, 0, At, B0); PG8_MMA(1, 1, At, B1); PG8_BAR; PG8_SCHED;
;     ...
;         if constexpr (ALIGN_EPI) { if (wr == 0) PG8_BAR; }
	s_add_i32 s76, 0, 0x18000
	s_add_i32 s77, 0, 0x1c000
	s_add_u32 s44, s44, 0x80000
	s_addc_u32 s45, s45, 0
	s_mov_b32 m0, s64
	s_nop 0
	global_load_lds_dwordx4 v130, s[44:45]
	ds_read_b128 v[142:145], v230 offset:32768
	ds_read_b128 v[146:149], v230 offset:33792
	ds_read_b128 v[150:153], v230 offset:34816
	ds_read_b128 v[154:157], v230 offset:35840
	ds_read_b128 v[158:161], v230 offset:49152
	ds_read_b128 v[162:165], v230 offset:50176
	ds_read_b128 v[166:169], v230 offset:51200
	ds_read_b128 v[178:181], v230 offset:52224
	s_mov_b32 m0, s65
	s_nop 0
	global_load_lds_dwordx4 v134, s[44:45]
	ds_read_b128 v[182:185], v175 offset:32768
	ds_read_b128 v[186:189], v175 offset:33792
	ds_read_b128 v[190:193], v175 offset:34816
	ds_read_b128 v[206:209], v175 offset:35840
	ds_read_b128 v[210:213], v175 offset:36864
	ds_read_b128 v[214:217], v175 offset:37888
	ds_read_b128 v[226:229], v175 offset:38912
	ds_read_b128 v[234:237], v175 offset:39936
	s_waitcnt vmcnt(8)
	s_waitcnt lgkmcnt(0)
	s_barrier
	s_setprio 1
	s_waitcnt lgkmcnt(0)
	v_mfma_f32_16x16x32_bf16 v[126:129], v[142:145], v[182:185], v[126:129]
	v_mfma_f32_16x16x32_bf16 v[118:121], v[150:153], v[182:185], v[118:121]
	v_mfma_f32_16x16x32_bf16 v[110:113], v[142:145], v[190:193], v[110:113]
	v_mfma_f32_16x16x32_bf16 v[102:105], v[150:153], v[190:193], v[102:105]
	v_mfma_f32_16x16x32_bf16 v[94:97], v[142:145], v[210:213], v[94:97]
	v_mfma_f32_16x16x32_bf16 v[86:89], v[150:153], v[210:213], v[86:89]
	v_mfma_f32_16x16x32_bf16 v[78:81], v[142:145], v[226:229], v[78:81]
	v_mfma_f32_16x16x32_bf16 v[70:73], v[150:153], v[226:229], v[70:73]
	v_mfma_f32_16x16x32_bf16 v[126:129], v[146:149], v[186:189], v[126:129]
	v_mfma_f32_16x16x32_bf16 v[118:121], v[154:157], v[186:189], v[118:121]
	v_mfma_f32_16x16x32_bf16 v[110:113], v[146:149], v[206:209], v[110:113]
	v_mfma_f32_16x16x32_bf16 v[102:105], v[154:157], v[206:209], v[102:105]
	v_mfma_f32_16x16x32_bf16 v[94:97], v[146:149], v[214:217], v[94:97]
	v_mfma_f32_16x16x32_bf16 v[86:89], v[154:157], v[214:217], v[86:89]
	v_mfma_f32_16x16x32_bf16 v[78:81], v[146:149], v[234:237], v[78:81]
	v_mfma_f32_16x16x32_bf16 v[70:73], v[154:157], v[234:237], v[70:73]
	s_setprio 0
	s_setprio 1
	v_mfma_f32_16x16x32_bf16 v[122:125], v[158:161], v[182:185], v[122:125]
	v_mfma_f32_16x16x32_bf16 v[114:117], v[166:169], v[182:185], v[114:117]
	v_mfma_f32_16x16x32_bf16 v[106:109], v[158:161], v[190:193], v[106:109]
	v_mfma_f32_16x16x32_bf16 v[98:101], v[166:169], v[190:193], v[98:101]
	v_mfma_f32_16x16x32_bf16 v[90:93], v[158:161], v[210:213], v[90:93]
	v_mfma_f32_16x16x32_bf16 v[82:85], v[166:169], v[210:213], v[82:85]
	v_mfma_f32_16x16x32_bf16 v[74:77], v[158:161], v[226:229], v[74:77]
	v_mfma_f32_16x16x32_bf16 v[66:69], v[166:169], v[226:229], v[66:69]
	v_mfma_f32_16x16x32_bf16 v[122:125], v[162:165], v[186:189], v[122:125]
	v_mfma_f32_16x16x32_bf16 v[114:117], v[178:181], v[186:189], v[114:117]
	v_mfma_f32_16x16x32_bf16 v[106:109], v[162:165], v[206:209], v[106:109]
	v_mfma_f32_16x16x32_bf16 v[98:101], v[178:181], v[206:209], v[98:101]
	v_mfma_f32_16x16x32_bf16 v[90:93], v[162:165], v[214:217], v[90:93]
	v_mfma_f32_16x16x32_bf16 v[82:85], v[178:181], v[214:217], v[82:85]
	v_mfma_f32_16x16x32_bf16 v[74:77], v[162:165], v[234:237], v[74:77]
	v_mfma_f32_16x16x32_bf16 v[66:69], v[178:181], v[234:237], v[66:69]
	s_setprio 0
	s_barrier
	s_add_u32 vcc_lo, s44, 0xfff80080
	s_addc_u32 vcc_hi, s45, -1
	s_mov_b32 m0, s68
	s_nop 0
	global_load_lds_dwordx4 v130, vcc
	ds_read_b128 v[182:185], v175 offset:49152
	ds_read_b128 v[186:189], v175 offset:50176
	s_mov_b32 m0, s69
	s_add_i32 s44, s76, s53
	global_load_lds_dwordx4 v134, vcc
	ds_read_b128 v[190:193], v175 offset:51200
	ds_read_b128 v[206:209], v175 offset:52224
	s_add_u32 vcc_lo, s42, 0x80
	s_addc_u32 vcc_hi, s43, 0
	s_mov_b32 m0, s44
	s_nop 0
	global_load_lds_dwordx4 v132, vcc
	ds_read_b128 v[210:213], v175 offset:53248
	ds_read_b128 v[214:217], v175 offset:54272
	s_add_i32 m0, s44, 0x2000
	s_add_u32 s42, s42, 0x80080
	s_addc_u32 s43, s43, 0
	global_load_lds_dwordx4 v136, vcc
	ds_read_b128 v[226:229], v175 offset:55296
	ds_read_b128 v[234:237], v175 offset:56320
	s_add_i32 s44, s77, s53
	s_mov_b32 m0, s44
	s_nop 0
	global_load_lds_dwordx4 v132, s[42:43]
	s_add_i32 m0, s44, 0x2000
	s_nop 0
	global_load_lds_dwordx4 v136, s[42:43]
	s_waitcnt vmcnt(8)
	s_waitcnt lgkmcnt(0)
	s_barrier
	s_setprio 1
	s_waitcnt lgkmcnt(0)
	v_mfma_f32_16x16x32_bf16 v[62:65], v[142:145], v[182:185], v[62:65]
	v_mfma_f32_16x16x32_bf16 v[54:57], v[150:153], v[182:185], v[54:57]
	v_mfma_f32_16x16x32_bf16 v[46:49], v[142:145], v[190:193], v[46:49]
	v_mfma_f32_16x16x32_bf16 v[38:41], v[150:153], v[190:193], v[38:41]
	v_mfma_f32_16x16x32_bf16 v[30:33], v[142:145], v[210:213], v[30:33]
	v_mfma_f32_16x16x32_bf16 v[22:25], v[150:153], v[210:213], v[22:25]
	v_mfma_f32_16x16x32_bf16 v[14:17], v[142:145], v[226:229], v[14:17]
	v_mfma_f32_16x16x32_bf16 v[6:9], v[150:153], v[226:229], v[6:9]
	v_mfma_f32_16x16x32_bf16 v[62:65], v[146:149], v[186:189], v[62:65]
	v_mfma_f32_16x16x32_bf16 v[54:57], v[154:157], v[186:189], v[54:57]
	v_mfma_f32_16x16x32_bf16 v[46:49], v[146:149], v[206:209], v[46:49]
	v_mfma_f32_16x16x32_bf16 v[38:41], v[154:157], v[206:209], v[38:41]
	v_mfma_f32_16x16x32_bf16 v[30:33], v[146:149], v[214:217], v[30:33]
	v_mfma_f32_16x16x32_bf16 v[22:25], v[154:157], v[214:217], v[22:25]
	v_mfma_f32_16x16x32_bf16 v[14:17], v[146:149], v[234:237], v[14:17]
	v_mfma_f32_16x16x32_bf16 v[6:9], v[154:157], v[234:237], v[6:9]
	s_setprio 0
	s_setprio 1
	v_mfma_f32_16x16x32_bf16 v[58:61], v[158:161], v[182:185], v[58:61]
	v_mfma_f32_16x16x32_bf16 v[50:53], v[166:169], v[182:185], v[50:53]
	v_mfma_f32_16x16x32_bf16 v[42:45], v[158:161], v[190:193], v[42:45]
	v_mfma_f32_16x16x32_bf16 v[34:37], v[166:169], v[190:193], v[34:37]
	v_mfma_f32_16x16x32_bf16 v[26:29], v[158:161], v[210:213], v[26:29]
	v_mfma_f32_16x16x32_bf16 v[18:21], v[166:169], v[210:213], v[18:21]
	v_mfma_f32_16x16x32_bf16 v[10:13], v[158:161], v[226:229], v[10:13]
	v_mfma_f32_16x16x32_bf16 v[2:5], v[166:169], v[226:229], v[2:5]
	v_mfma_f32_16x16x32_bf16 v[58:61], v[162:165], v[186:189], v[58:61]
	v_mfma_f32_16x16x32_bf16 v[50:53], v[178:181], v[186:189], v[50:53]
	v_mfma_f32_16x16x32_bf16 v[42:45], v[162:165], v[206:209], v[42:45]
	v_mfma_f32_16x16x32_bf16 v[34:37], v[178:181], v[206:209], v[34:37]
	v_mfma_f32_16x16x32_bf16 v[26:29], v[162:165], v[214:217], v[26:29]
	v_mfma_f32_16x16x32_bf16 v[18:21], v[178:181], v[214:217], v[18:21]
	v_mfma_f32_16x16x32_bf16 v[10:13], v[162:165], v[234:237], v[10:13]
	v_mfma_f32_16x16x32_bf16 v[2:5], v[178:181], v[234:237], v[2:5]
	s_setprio 0
	s_barrier
	s_add_i32 s75, s75, 2
	s_add_u32 s20, s20, 0x100
	s_addc_u32 s21, s21, 0
	s_add_u32 s73, s73, 0x100
	s_addc_u32 s74, s74, 0
	s_cmp_gt_u32 s75, 29
	s_cbranch_scc0 .LBB0_174
.Lpeel_exit_g1:
	s_and_b64 vcc, exec, s[10:11]
	s_cbranch_vccz .LBB0_177
	s_barrier

;     __host__ __device__ bool next(int i, Unit& u) const { const bool ok = StaticOrder::next(i, u); u.lm = 0; u.ln = 0; return ok; }
; template <class Epi, class Sched, bool ALIGN_EPI = false, bool SP2 = false>
; __device__ __forceinline__ void gemm_phase(PG8_LAS unsigned char* lds, const Gemm g, const Sched& S, const Epi& E, const int wave_id) {
;     ...
;     for (;;) {
;         const bool has_next = S.next(ui + 1, nxt);
;         const char* nA = has_next ? (const char*)g.A + (size_t)nxt.lm * tstep : cA; const char* nB = has_next ? (const char*)g.Bt + (size_t)nxt.ln * tstep : cB;
.Ltramp_150:
	s_branch .LBB0_150

;     __host__ __device__ bool next(int i, Unit& u) const { const bool ok = StaticOrder::next(i, u); u.lm = 0; u.ln = 0; return ok; }
; #define PG8_STAGE(bufoff, gbase, voff) do { _Pragma("unroll") for (int _i = 0; _i < 2; ++_i) \
;         __builtin_amdgcn_global_load_lds((const unsigned*)((const char*)(gbase) + (voff)[_i]), (PG8_LAS unsigned*)(lds + (bufoff) + ldsw + _i * 8192), 16, 0, 0); } while (0)
; #define PG8_LDA(dst, b, h) do { _Pragma("unroll") for (int m = 0; m < 4; ++m) _Pragma("unroll") for (int k = 0; k < 2; ++k) dst[m][k] = *(const PG8_LAS bf16x8*)(lds + PG8_SA(b, h) + aoff + m * 2048 + k * 1024); } while (0)
; #define PG8_LDB(dst, b, h) do { _Pragma("unroll") for (int n = 0; n < 2; ++n) _Pragma("unroll") for (int k = 0; k < 2; ++k) dst[n][k] = *(const PG8_LAS bf16x8*)(lds + PG8_SB(b, h) + boff + n * 2048 + k * 1024); } while (0)
; #define PG8_WAIT_V(n) asm volatile("s_waitcnt vmcnt(" #n ")" ::: "memory")
; #define PG8_BAR __builtin_amdgcn_s_barrier()
; template <class Epi, class Sched, bool ALIGN_EPI = false, bool SP2 = false>
; __device__ __forceinline__ void gemm_phase(PG8_LAS unsigned char* lds, const Gemm g, const Sched& S, const Epi& E, const int wave_id) {
;     ...
;         const bool has_next = S.next(ui + 1, nxt);
;         const char* nA = has_next ? (const char*)g.A + (size_t)nxt.lm * tstep : cA; const char* nB = has_next ? (const char*)g.Bt + (size_t)nxt.ln * tstep : cB;
; #pragma unroll 1
;         for (int t = 0; t < nt; t += 2) {
;             const bool last = (t == nt - 2);
;             const char* a1 = cA + (size_t)(t + 1) * kstep;
;             const char* a2 = last ? nA : cA + (size_t)(t + 2) * kstep; const char* b2 = last ? nB : cB + (size_t)(t + 2) * kstep;
;             const char* a3 = a2 + kstep; const char* b3 = b2 + kstep;
;             if (last && has_next) S.a_ready(nxt);
;             if constexpr (SP2) {
;             PG8_LDB(B0, 0, 0); PG8_LDB(B1, 0, 1); PG8_SCHED; PG8_LDA(At, 0, 0); PG8_STAGE(PG8_SA(1, 1), a1 + hstep, voffA);
;             PG8_WAIT_V(8); PG8_WAIT_L(0); PG8_BAR; PG8_MMA(0, 0, At, B0); PG8_MMA(0, 1, At, B1); PG8_BAR; PG8_SCHED;
;             PG8_LDA(At, 0, 1); PG8_STAGE(PG8_SB(0, 0), b2, voffB); PG8_STAGE(PG8_SB(0, 1), b2 + hstep, voffB); PG8_STAGE(PG8_SA(0, 0), a2, voffA);
;             PG8_WAIT_V(8); PG8_WAIT_L(0); PG8_BAR; PG8_MMA(1, 0, At, B0); PG8_MMA(1, 1, At, B1); PG8_BAR; PG8_SCHED;
.LBB0_523:
	s_ashr_i32 s15, s14, 31
	s_lshl_b64 s[16:17], s[14:15], 20
	s_add_u32 s16, s47, s16
	s_addc_u32 s17, s48, s17
	s_and_b64 s[18:19], s[38:39], exec
	s_cselect_b32 s15, s17, s41
	s_cselect_b32 s21, s16, s40
	s_ashr_i32 s13, s12, 31
	s_lshl_b64 s[18:19], s[12:13], 20
	s_add_u32 s18, s49, s18
	s_addc_u32 s19, s52, s19
	s_and_b64 s[44:45], s[38:39], exec
	s_cselect_b32 s13, s19, s43
	s_cselect_b32 s73, s18, s42
	s_add_u32 s40, s40, 0x80080
	s_addc_u32 s41, s41, 0
	s_add_u32 s74, s42, 0x100
	s_addc_u32 s75, s43, 0
	s_mov_b32 s76, -2
	v_add_u32_e32 v226, 0x10000, v218
	s_add_u32 s42, s40, 0xfff80080
	s_addc_u32 s43, s41, -1
	s_add_i32 s77, 0, 0x10000
	s_cmp_eq_u32 s76, 28
	s_cselect_b32 s45, s15, s43
	s_cselect_b32 s44, s21, s42
	s_cselect_b32 s43, s13, s75
	s_cselect_b32 s42, s73, s74
	s_add_i32 s79, 0, 0x14000
	s_add_i32 m0, s56, 0xc000
	s_nop 0
	global_load_lds_dwordx4 v210, s[40:41]
	ds_read_b128 v[118:121], v226
	ds_read_b128 v[122:125], v226 offset:1024
	ds_read_b128 v[130:133], v226 offset:2048
	ds_read_b128 v[134:137], v226 offset:3072
	ds_read_b128 v[146:149], v226 offset:16384
	ds_read_b128 v[150:153], v226 offset:17408
	ds_read_b128 v[154:157], v226 offset:18432
	ds_read_b128 v[158:161], v226 offset:19456
	s_add_i32 m0, s56, 0xe000
	s_nop 0
	global_load_lds_dwordx4 v212, s[40:41]
	ds_read_b128 v[162:165], v222
	ds_read_b128 v[166:169], v222 offset:1024
	ds_read_b128 v[170:173], v222 offset:2048
	ds_read_b128 v[174:177], v222 offset:3072
	ds_read_b128 v[178:181], v222 offset:4096
	ds_read_b128 v[182:185], v222 offset:5120
	ds_read_b128 v[186:189], v222 offset:6144
	ds_read_b128 v[214:217], v222 offset:7168
	s_waitcnt vmcnt(8)
	s_waitcnt lgkmcnt(0)
	s_barrier
	s_setprio 1
	s_waitcnt lgkmcnt(0)
	v_mfma_f32_16x16x32_bf16 v[142:145], v[118:121], v[162:165], 0
	v_mfma_f32_16x16x32_bf16 v[138:141], v[130:133], v[162:165], 0
	v_mfma_f32_16x16x32_bf16 v[110:113], v[118:121], v[170:173], 0
	v_mfma_f32_16x16x32_bf16 v[106:109], v[130:133], v[170:173], 0
	v_mfma_f32_16x16x32_bf16 v[94:97], v[118:121], v[178:181], 0
	v_mfma_f32_16x16x32_bf16 v[90:93], v[130:133], v[178:181], 0
	v_mfma_f32_16x16x32_bf16 v[78:81], v[118:121], v[186:189], 0
	v_mfma_f32_16x16x32_bf16 v[74:77], v[130:133], v[186:189], 0
	v_mfma_f32_16x16x32_bf16 v[142:145], v[122:125], v[166:169], v[142:145]
	v_mfma_f32_16x16x32_bf16 v[138:141], v[134:137], v[166:169], v[138:141]
	v_mfma_f32_16x16x32_bf16 v[110:113], v[122:125], v[174:177], v[110:113]
	v_mfma_f32_16x16x32_bf16 v[106:109], v[134:137], v[174:177], v[106:109]
	v_mfma_f32_16x16x32_bf16 v[94:97], v[122:125], v[182:185], v[94:97]
	v_mfma_f32_16x16x32_bf16 v[90:93], v[134:137], v[182:185], v[90:93]
	v_mfma_f32_16x16x32_bf16 v[78:81], v[122:125], v[214:217], v[78:81]
	v_mfma_f32_16x16x32_bf16 v[74:77], v[134:137], v[214:217], v[74:77]
	s_setprio 0
	s_setprio 1
	v_mfma_f32_16x16x32_bf16 v[126:129], v[146:149], v[162:165], 0
	v_mfma_f32_16x16x32_bf16 v[114:117], v[154:157], v[162:165], 0
	v_mfma_f32_16x16x32_bf16 v[102:105], v[146:149], v[170:173], 0
	v_mfma_f32_16x16x32_bf16 v[98:101], v[154:157], v[170:173], 0
	v_mfma_f32_16x16x32_bf16 v[86:89], v[146:149], v[178:181], 0
	v_mfma_f32_16x16x32_bf16 v[82:85], v[154:157], v[178:181], 0
	v_mfma_f32_16x16x32_bf16 v[70:73], v[146:149], v[186:189], 0
	v_mfma_f32_16x16x32_bf16 v[66:69], v[154:157], v[186:189], 0
	v_mfma_f32_16x16x32_bf16 v[126:129], v[150:153], v[166:169], v[126:129]
	v_mfma_f32_16x16x32_bf16 v[114:117], v[158:161], v[166:169], v[114:117]
	v_mfma_f32_16x16x32_bf16 v[102:105], v[150:153], v[174:177], v[102:105]
	v_mfma_f32_16x16x32_bf16 v[98:101], v[158:161], v[174:177], v[98:101]
	v_mfma_f32_16x16x32_bf16 v[86:89], v[150:153], v[182:185], v[86:89]
	v_mfma_f32_16x16x32_bf16 v[82:85], v[158:161], v[182:185], v[82:85]
	v_mfma_f32_16x16x32_bf16 v[70:73], v[150:153], v[214:217], v[70:73]
	v_mfma_f32_16x16x32_bf16 v[66:69], v[158:161], v[214:217], v[66:69]
	s_setprio 0
	s_barrier
	s_add_i32 s77, s77, s53
	s_mov_b32 m0, s77
	s_nop 0
	global_load_lds_dwordx4 v192, s[42:43]
	ds_read_b128 v[162:165], v222 offset:16384
	ds_read_b128 v[166:169], v222 offset:17408
	s_add_i32 m0, s77, 0x2000
	s_add_u32 s80, s42, 0x80000
	s_addc_u32 s81, s43, 0
	s_add_i32 s77, s79, s53
	global_load_lds_dwordx4 v208, s[42:43]
	ds_read_b128 v[170:173], v222 offset:18432
	ds_read_b128 v[174:177], v222 offset:19456
	s_mov_b32 m0, s77
	s_nop 0
	global_load_lds_dwordx4 v192, s[80:81]
	ds_read_b128 v[178:181], v222 offset:20480
	ds_read_b128 v[182:185], v222 offset:21504
	s_add_i32 m0, s77, 0x2000
	s_nop 0
	global_load_lds_dwordx4 v208, s[80:81]
	ds_read_b128 v[186:189], v222 offset:22528
	ds_read_b128 v[214:217], v222 offset:23552
	s_mov_b32 m0, s56
	s_nop 0
	global_load_lds_dwordx4 v190, s[44:45]
	s_mov_b32 m0, s57
	s_nop 0
	global_load_lds_dwordx4 v206, s[44:45]
	s_waitcnt vmcnt(8)
	s_waitcnt lgkmcnt(0)
	s_barrier
; #define PG8_STAGE(bufoff, gbase, voff) do { _Pragma("unroll") for (int _i = 0; _i < 2; ++_i) \
;         __builtin_amdgcn_global_load_lds((const unsigned*)((const char*)(gbase) + (voff)[_i]), (PG8_LAS unsigned*)(lds + (bufoff) + ldsw + _i * 8192), 16, 0, 0); } while (0)
; #define PG8_LDA(dst, b, h) do { _Pragma("unroll") for (int m = 0; m < 4; ++m) _Pragma("unroll") for (int k = 0; k < 2; ++k) dst[m][k] = *(const PG8_LAS bf16x8*)(lds + PG8_SA(b, h) + aoff + m * 2048 + k * 1024); } while (0)
; #define PG8_WAIT_V(n) asm volatile("s_waitcnt vmcnt(" #n ")" ::: "memory")
; #define PG8_WAIT_L(n) asm volatile("s_waitcnt lgkmcnt(" #n ")" ::: "memory")
; #define PG8_BAR __builtin_amdgcn_s_barrier()
; template <class Epi, class Sched, bool ALIGN_EPI = false, bool SP2 = false>
; __device__ __forceinline__ void gemm_phase(PG8_LAS unsigned char* lds, const Gemm g, const Sched& S, const Epi& E, const int wave_id) {
;     ...
;         for (int t = 0; t < nt; t += 2) {
;             const bool last = (t == nt - 2);
;             const char* a1 = cA + (size_t)(t + 1) * kstep;
;             const char* a2 = last ? nA : cA + (size_t)(t + 2) * kstep; const char* b2 = last ? nB : cB + (size_t)(t + 2) * kstep;
;             const char* a3 = a2 + kstep; const char* b3 = b2 + kstep;
;             if (last && has_next) S.a_ready(nxt);
;             if constexpr (SP2) {
;             PG8_LDB(B0, 0, 0); PG8_LDB(B1, 0, 1); PG8_SCHED; PG8_LDA(At, 0, 0); PG8_STAGE(PG8_SA(1, 1), a1 + hstep, voffA);
;             PG8_WAIT_V(8); PG8_WAIT_L(0); PG8_BAR; PG8_MMA(0, 0, At, B0); PG8_MMA(0, 1, At, B1); PG8_BAR; PG8_SCHED;
;             PG8_LDA(At, 0, 1); PG8_STAGE(PG8_SB(0, 0), b2, voffB); PG8_STAGE(PG8_SB(0, 1), b2 + hstep, voffB); PG8_STAGE(PG8_SA(0, 0), a2, voffA);
;             PG8_WAIT_V(8); PG8_WAIT_L(0); PG8_BAR; PG8_MMA(1, 0, At, B0); PG8_MMA(1, 1, At, B1); PG8_BAR; PG8_SCHED;
;             PG8_LDB(B0, 1, 0); PG8_LDB(B1, 1, 1); PG8_SCHED; PG8_LDA(At, 1, 0); PG8_STAGE(PG8_SA(0, 1), a2 + hstep, voffA);
;             PG8_WAIT_V(8); PG8_WAIT_L(0); PG8_BAR; PG8_MMA(0, 0, At, B0); PG8_MMA(0, 1, At, B1); PG8_BAR; PG8_SCHED;
;             PG8_LDA(At, 1, 1); PG8_STAGE(PG8_SB(1, 0), b3, voffB); PG8_STAGE(PG8_SB(1, 1), b3 + hstep, voffB); PG8_STAGE(PG8_SA(1, 0), a3, voffA);
;             PG8_WAIT_V(8); PG8_WAIT_L(0); PG8_BAR; PG8_MMA(1, 0, At, B0); PG8_MMA(1, 1, At, B1); PG8_BAR; PG8_SCHED;
	s_setprio 1
	s_waitcnt lgkmcnt(0)
	v_mfma_f32_16x16x32_bf16 v[62:65], v[118:121], v[162:165], 0
	v_mfma_f32_16x16x32_bf16 v[58:61], v[130:133], v[162:165], 0
	v_mfma_f32_16x16x32_bf16 v[46:49], v[118:121], v[170:173], 0
	v_mfma_f32_16x16x32_bf16 v[42:45], v[130:133], v[170:173], 0
	v_mfma_f32_16x16x32_bf16 v[30:33], v[118:121], v[178:181], 0
	v_mfma_f32_16x16x32_bf16 v[26:29], v[130:133], v[178:181], 0
	v_mfma_f32_16x16x32_bf16 v[14:17], v[118:121], v[186:189], 0
	v_mfma_f32_16x16x32_bf16 v[10:13], v[130:133], v[186:189], 0
	v_mfma_f32_16x16x32_bf16 v[62:65], v[122:125], v[166:169], v[62:65]
	v_mfma_f32_16x16x32_bf16 v[58:61], v[134:137], v[166:169], v[58:61]
	v_mfma_f32_16x16x32_bf16 v[46:49], v[122:125], v[174:177], v[46:49]
	v_mfma_f32_16x16x32_bf16 v[42:45], v[134:137], v[174:177], v[42:45]
	v_mfma_f32_16x16x32_bf16 v[30:33], v[122:125], v[182:185], v[30:33]
	v_mfma_f32_16x16x32_bf16 v[26:29], v[134:137], v[182:185], v[26:29]
	v_mfma_f32_16x16x32_bf16 v[14:17], v[122:125], v[214:217], v[14:17]
	v_mfma_f32_16x16x32_bf16 v[10:13], v[134:137], v[214:217], v[10:13]
	s_setprio 0
	s_setprio 1
	v_mfma_f32_16x16x32_bf16 v[54:57], v[146:149], v[162:165], 0
	v_mfma_f32_16x16x32_bf16 v[50:53], v[154:157], v[162:165], 0
	v_mfma_f32_16x16x32_bf16 v[38:41], v[146:149], v[170:173], 0
	v_mfma_f32_16x16x32_bf16 v[34:37], v[154:157], v[170:173], 0
	v_mfma_f32_16x16x32_bf16 v[22:25], v[146:149], v[178:181], 0
	v_mfma_f32_16x16x32_bf16 v[18:21], v[154:157], v[178:181], 0
	v_mfma_f32_16x16x32_bf16 v[6:9], v[146:149], v[186:189], 0
	v_mfma_f32_16x16x32_bf16 v[2:5], v[154:157], v[186:189], 0
	v_mfma_f32_16x16x32_bf16 v[54:57], v[150:153], v[166:169], v[54:57]
	v_mfma_f32_16x16x32_bf16 v[50:53], v[158:161], v[166:169], v[50:53]
	v_mfma_f32_16x16x32_bf16 v[38:41], v[150:153], v[174:177], v[38:41]
	v_mfma_f32_16x16x32_bf16 v[34:37], v[158:161], v[174:177], v[34:37]
	v_mfma_f32_16x16x32_bf16 v[22:25], v[150:153], v[182:185], v[22:25]
	v_mfma_f32_16x16x32_bf16 v[18:21], v[158:161], v[182:185], v[18:21]
	v_mfma_f32_16x16x32_bf16 v[6:9], v[150:153], v[214:217], v[6:9]
	v_mfma_f32_16x16x32_bf16 v[2:5], v[158:161], v[214:217], v[2:5]
	s_setprio 0
	s_barrier
	s_add_i32 s77, 0, 0x18000
	s_add_i32 s79, 0, 0x1c000
	s_add_u32 s44, s44, 0x80000
	s_addc_u32 s45, s45, 0
	s_mov_b32 m0, s64
	s_nop 0
	global_load_lds_dwordx4 v190, s[44:45]
	ds_read_b128 v[118:121], v226 offset:32768
	ds_read_b128 v[122:125], v226 offset:33792
	ds_read_b128 v[130:133], v226 offset:34816
	ds_read_b128 v[134:137], v226 offset:35840
	ds_read_b128 v[146:149], v226 offset:49152
	ds_read_b128 v[150:153], v226 offset:50176
	ds_read_b128 v[154:157], v226 offset:51200
	ds_read_b128 v[158:161], v226 offset:52224
	s_mov_b32 m0, s65
	s_nop 0
	global_load_lds_dwordx4 v206, s[44:45]
	ds_read_b128 v[162:165], v222 offset:32768
	ds_read_b128 v[166:169], v222 offset:33792
	ds_read_b128 v[170:173], v222 offset:34816
	ds_read_b128 v[174:177], v222 offset:35840
	ds_read_b128 v[178:181], v222 offset:36864
	ds_read_b128 v[182:185], v222 offset:37888
	ds_read_b128 v[186:189], v222 offset:38912
	ds_read_b128 v[214:217], v222 offset:39936
	s_waitcnt vmcnt(8)
	s_waitcnt lgkmcnt(0)
	s_barrier
	s_setprio 1
	s_waitcnt lgkmcnt(0)
	v_mfma_f32_16x16x32_bf16 v[142:145], v[118:121], v[162:165], v[142:145]
	v_mfma_f32_16x16x32_bf16 v[138:141], v[130:133], v[162:165], v[138:141]
	v_mfma_f32_16x16x32_bf16 v[110:113], v[118:121], v[170:173], v[110:113]
	v_mfma_f32_16x16x32_bf16 v[106:109], v[130:133], v[170:173], v[106:109]
	v_mfma_f32_16x16x32_bf16 v[94:97], v[118:121], v[178:181], v[94:97]
	v_mfma_f32_16x16x32_bf16 v[90:93], v[130:133], v[178:181], v[90:93]
	v_mfma_f32_16x16x32_bf16 v[78:81], v[118:121], v[186:189], v[78:81]
	v_mfma_f32_16x16x32_bf16 v[74:77], v[130:133], v[186:189], v[74:77]
	v_mfma_f32_16x16x32_bf16 v[142:145], v[122:125], v[166:169], v[142:145]
	v_mfma_f32_16x16x32_bf16 v[138:141], v[134:137], v[166:169], v[138:141]
	v_mfma_f32_16x16x32_bf16 v[110:113], v[122:125], v[174:177], v[110:113]
	v_mfma_f32_16x16x32_bf16 v[106:109], v[134:137], v[174:177], v[106:109]
	v_mfma_f32_16x16x32_bf16 v[94:97], v[122:125], v[182:185], v[94:97]
	v_mfma_f32_16x16x32_bf16 v[90:93], v[134:137], v[182:185], v[90:93]
	v_mfma_f32_16x16x32_bf16 v[78:81], v[122:125], v[214:217], v[78:81]
	v_mfma_f32_16x16x32_bf16 v[74:77], v[134:137], v[214:217], v[74:77]
	s_setprio 0
	s_setprio 1
	v_mfma_f32_16x16x32_bf16 v[126:129], v[146:149], v[162:165], v[126:129]
	v_mfma_f32_16x16x32_bf16 v[114:117], v[154:157], v[162:165], v[114:117]
	v_mfma_f32_16x16x32_bf16 v[102:105], v[146:149], v[170:173], v[102:105]
	v_mfma_f32_16x16x32_bf16 v[98:101], v[154:157], v[170:173], v[98:101]
	v_mfma_f32_16x16x32_bf16 v[86:89], v[146:149], v[178:181], v[86:89]
	v_mfma_f32_16x16x32_bf16 v[82:85], v[154:157], v[178:181], v[82:85]
	v_mfma_f32_16x16x32_bf16 v[70:73], v[146:149], v[186:189], v[70:73]
	v_mfma_f32_16x16x32_bf16 v[66:69], v[154:157], v[186:189], v[66:69]
	v_mfma_f32_16x16x32_bf16 v[126:129], v[150:153], v[166:169], v[126:129]
	v_mfma_f32_16x16x32_bf16 v[114:117], v[158:161], v[166:169], v[114:117]
	v_mfma_f32_16x16x32_bf16 v[102:105], v[150:153], v[174:177], v[102:105]
	v_mfma_f32_16x16x32_bf16 v[98:101], v[158:161], v[174:177], v[98:101]
	v_mfma_f32_16x16x32_bf16 v[86:89], v[150:153], v[182:185], v[86:89]
	v_mfma_f32_16x16x32_bf16 v[82:85], v[158:161], v[182:185], v[82:85]
	v_mfma_f32_16x16x32_bf16 v[70:73], v[150:153], v[214:217], v[70:73]
	v_mfma_f32_16x16x32_bf16 v[66:69], v[158:161], v[214:217], v[66:69]
	s_setprio 0
	s_barrier
; #define PG8_STAGE(bufoff, gbase, voff) do { _Pragma("unroll") for (int _i = 0; _i < 2; ++_i) \
;         __builtin_amdgcn_global_load_lds((const unsigned*)((const char*)(gbase) + (voff)[_i]), (PG8_LAS unsigned*)(lds + (bufoff) + ldsw + _i * 8192), 16, 0, 0); } while (0)
; #define PG8_LDA(dst, b, h) do { _Pragma("unroll") for (int m = 0; m < 4; ++m) _Pragma("unroll") for (int k = 0; k < 2; ++k) dst[m][k] = *(const PG8_LAS bf16x8*)(lds + PG8_SA(b, h) + aoff + m * 2048 + k * 1024); } while (0)
; #define PG8_WAIT_V(n) asm volatile("s_waitcnt vmcnt(" #n ")" ::: "memory")
; #define PG8_WAIT_L(n) asm volatile("s_waitcnt lgkmcnt(" #n ")" ::: "memory")
; #define PG8_BAR __builtin_amdgcn_s_barrier()
; template <class Epi, class Sched, bool ALIGN_EPI = false, bool SP2 = false>
; __device__ __forceinline__ void gemm_phase(PG8_LAS unsigned char* lds, const Gemm g, const Sched& S, const Epi& E, const int wave_id) {
;     ...
;         for (int t = 0; t < nt; t += 2) {
;             const bool last = (t == nt - 2);
;             const char* a1 = cA + (size_t)(t + 1) * kstep;
;             const char* a2 = last ? nA : cA + (size_t)(t + 2) * kstep; const char* b2 = last ? nB : cB + (size_t)(t + 2) * kstep;
;             const char* a3 = a2 + kstep; const char* b3 = b2 + kstep;
;             if (last && has_next) S.a_ready(nxt);
;             if constexpr (SP2) {
;             PG8_LDB(B0, 0, 0); PG8_LDB(B1, 0, 1); PG8_SCHED; PG8_LDA(At, 0, 0); PG8_STAGE(PG8_SA(1, 1), a1 + hstep, voffA);
;             PG8_WAIT_V(8); PG8_WAIT_L(0); PG8_BAR; PG8_MMA(0, 0, At, B0); PG8_MMA(0, 1, At, B1); PG8_BAR; PG8_SCHED;
;             PG8_LDA(At, 0, 1); PG8_STAGE(PG8_SB(0, 0), b2, voffB); PG8_STAGE(PG8_SB(0, 1), b2 + hstep, voffB); PG8_STAGE(PG8_SA(0, 0), a2, voffA);
;             PG8_WAIT_V(8); PG8_WAIT_L(0); PG8_BAR; PG8_MMA(1, 0, At, B0); PG8_MMA(1, 1, At, B1); PG8_BAR; PG8_SCHED;
;             PG8_LDB(B0, 1, 0); PG8_LDB(B1, 1, 1); PG8_SCHED; PG8_LDA(At, 1, 0); PG8_STAGE(PG8_SA(0, 1), a2 + hstep, voffA);
;             PG8_WAIT_V(8); PG8_WAIT_L(0); PG8_BAR; PG8_MMA(0, 0, At, B0); PG8_MMA(0, 1, At, B1); PG8_BAR; PG8_SCHED;
;             PG8_LDA(At, 1, 1); PG8_STAGE(PG8_SB(1, 0), b3, voffB); PG8_STAGE(PG8_SB(1, 1), b3 + hstep, voffB); PG8_STAGE(PG8_SA(1, 0), a3, voffA);
;             PG8_WAIT_V(8); PG8_WAIT_L(0); PG8_BAR; PG8_MMA(1, 0, At, B0); PG8_MMA(1, 1, At, B1); PG8_BAR; PG8_SCHED;
	s_add_u32 vcc_lo, s44, 0xfff80080
	s_addc_u32 vcc_hi, s45, -1
	s_mov_b32 m0, s70
	s_nop 0
	global_load_lds_dwordx4 v190, vcc
	ds_read_b128 v[162:165], v222 offset:49152
	ds_read_b128 v[166:169], v222 offset:50176
	s_mov_b32 m0, s71
	s_add_i32 s44, s77, s53
	global_load_lds_dwordx4 v206, vcc
	ds_read_b128 v[170:173], v222 offset:51200
	ds_read_b128 v[174:177], v222 offset:52224
	s_add_u32 vcc_lo, s42, 0x80
	s_addc_u32 vcc_hi, s43, 0
	s_mov_b32 m0, s44
	s_nop 0
	global_load_lds_dwordx4 v192, vcc
	ds_read_b128 v[178:181], v222 offset:53248
	ds_read_b128 v[182:185], v222 offset:54272
	s_add_i32 m0, s44, 0x2000
	s_add_u32 s42, s42, 0x80080
	s_addc_u32 s43, s43, 0
	global_load_lds_dwordx4 v208, vcc
	ds_read_b128 v[186:189], v222 offset:55296
	ds_read_b128 v[214:217], v222 offset:56320
	s_add_i32 s44, s79, s53
	s_mov_b32 m0, s44
	s_nop 0
	global_load_lds_dwordx4 v192, s[42:43]
	s_add_i32 m0, s44, 0x2000
	s_nop 0
	global_load_lds_dwordx4 v208, s[42:43]
	s_waitcnt vmcnt(8)
	s_waitcnt lgkmcnt(0)
	s_barrier
	s_setprio 1
	s_waitcnt lgkmcnt(0)
	v_mfma_f32_16x16x32_bf16 v[62:65], v[118:121], v[162:165], v[62:65]
	v_mfma_f32_16x16x32_bf16 v[58:61], v[130:133], v[162:165], v[58:61]
	v_mfma_f32_16x16x32_bf16 v[46:49], v[118:121], v[170:173], v[46:49]
	v_mfma_f32_16x16x32_bf16 v[42:45], v[130:133], v[170:173], v[42:45]
	v_mfma_f32_16x16x32_bf16 v[30:33], v[118:121], v[178:181], v[30:33]
	v_mfma_f32_16x16x32_bf16 v[26:29], v[130:133], v[178:181], v[26:29]
	v_mfma_f32_16x16x32_bf16 v[14:17], v[118:121], v[186:189], v[14:17]
	v_mfma_f32_16x16x32_bf16 v[10:13], v[130:133], v[186:189], v[10:13]
	v_mfma_f32_16x16x32_bf16 v[62:65], v[122:125], v[166:169], v[62:65]
	v_mfma_f32_16x16x32_bf16 v[58:61], v[134:137], v[166:169], v[58:61]
	v_mfma_f32_16x16x32_bf16 v[46:49], v[122:125], v[174:177], v[46:49]
	v_mfma_f32_16x16x32_bf16 v[42:45], v[134:137], v[174:177], v[42:45]
	v_mfma_f32_16x16x32_bf16 v[30:33], v[122:125], v[182:185], v[30:33]
	v_mfma_f32_16x16x32_bf16 v[26:29], v[134:137], v[182:185], v[26:29]
	v_mfma_f32_16x16x32_bf16 v[14:17], v[122:125], v[214:217], v[14:17]
	v_mfma_f32_16x16x32_bf16 v[10:13], v[134:137], v[214:217], v[10:13]
	s_setprio 0
	s_setprio 1
	v_mfma_f32_16x16x32_bf16 v[54:57], v[146:149], v[162:165], v[54:57]
	v_mfma_f32_16x16x32_bf16 v[50:53], v[154:157], v[162:165], v[50:53]
	v_mfma_f32_16x16x32_bf16 v[38:41], v[146:149], v[170:173], v[38:41]
	v_mfma_f32_16x16x32_bf16 v[34:37], v[154:157], v[170:173], v[34:37]
	v_mfma_f32_16x16x32_bf16 v[22:25], v[146:149], v[178:181], v[22:25]
	v_mfma_f32_16x16x32_bf16 v[18:21], v[154:157], v[178:181], v[18:21]
	v_mfma_f32_16x16x32_bf16 v[6:9], v[146:149], v[186:189], v[6:9]
	v_mfma_f32_16x16x32_bf16 v[2:5], v[154:157], v[186:189], v[2:5]
	v_mfma_f32_16x16x32_bf16 v[54:57], v[150:153], v[166:169], v[54:57]
	v_mfma_f32_16x16x32_bf16 v[50:53], v[158:161], v[166:169], v[50:53]
	v_mfma_f32_16x16x32_bf16 v[38:41], v[150:153], v[174:177], v[38:41]
	v_mfma_f32_16x16x32_bf16 v[34:37], v[158:161], v[174:177], v[34:37]
	v_mfma_f32_16x16x32_bf16 v[22:25], v[150:153], v[182:185], v[22:25]
	v_mfma_f32_16x16x32_bf16 v[18:21], v[158:161], v[182:185], v[18:21]
	v_mfma_f32_16x16x32_bf16 v[6:9], v[150:153], v[214:217], v[6:9]
	v_mfma_f32_16x16x32_bf16 v[2:5], v[158:161], v[214:217], v[2:5]
	s_setprio 0
	s_barrier
	s_add_i32 s76, s76, 2
	s_add_u32 s40, s40, 0x100
	s_addc_u32 s41, s41, 0
	s_add_u32 s74, s74, 0x100
	s_addc_u32 s75, s75, 0
	s_cmp_gt_u32 s76, 29
	s_cbranch_scc1 .Lpeel_exit_g2
.LBB0_524:
	s_add_u32 s42, s40, 0xfff80080
	s_addc_u32 s43, s41, -1
	s_add_i32 s77, 0, 0x10000
	s_cmp_eq_u32 s76, 28
	s_cselect_b32 s45, s15, s43
	s_cselect_b32 s44, s21, s42
	s_cselect_b32 s43, s13, s75
	s_cselect_b32 s42, s73, s74
	s_add_i32 s79, 0, 0x14000
	s_add_i32 m0, s56, 0xc000
	s_nop 0
	global_load_lds_dwordx4 v210, s[40:41]
	ds_read_b128 v[118:121], v226
	ds_read_b128 v[122:125], v226 offset:1024
	ds_read_b128 v[130:133], v226 offset:2048
	ds_read_b128 v[134:137], v226 offset:3072
	ds_read_b128 v[146:149], v226 offset:16384
	ds_read_b128 v[150:153], v226 offset:17408
	ds_read_b128 v[154:157], v226 offset:18432
	ds_read_b128 v[158:161], v226 offset:19456
	s_add_i32 m0, s56, 0xe000
	s_nop 0
	global_load_lds_dwordx4 v212, s[40:41]
	ds_read_b128 v[162:165], v222
	ds_read_b128 v[166:169], v222 offset:1024
	ds_read_b128 v[170:173], v222 offset:2048
	ds_read_b128 v[174:177], v222 offset:3072
	ds_read_b128 v[178:181], v222 offset:4096
	ds_read_b128 v[182:185], v222 offset:5120
	ds_read_b128 v[186:189], v222 offset:6144
	ds_read_b128 v[214:217], v222 offset:7168
	s_waitcnt vmcnt(8)
	s_waitcnt lgkmcnt(0)
	s_barrier
; #define PG8_STAGE(bufoff, gbase, voff) do { _Pragma("unroll") for (int _i = 0; _i < 2; ++_i) \
;         __builtin_amdgcn_global_load_lds((const unsigned*)((const char*)(gbase) + (voff)[_i]), (PG8_LAS unsigned*)(lds + (bufoff) + ldsw + _i * 8192), 16, 0, 0); } while (0)
; #define PG8_LDA(dst, b, h) do { _Pragma("unroll") for (int m = 0; m < 4; ++m) _Pragma("unroll") for (int k = 0; k < 2; ++k) dst[m][k] = *(const PG8_LAS bf16x8*)(lds + PG8_SA(b, h) + aoff + m * 2048 + k * 1024); } while (0)
; #define PG8_WAIT_V(n) asm volatile("s_waitcnt vmcnt(" #n ")" ::: "memory")
; #define PG8_WAIT_L(n) asm volatile("s_waitcnt lgkmcnt(" #n ")" ::: "memory")
; #define PG8_BAR __builtin_amdgcn_s_barrier()
; template <class Epi, class Sched, bool ALIGN_EPI = false, bool SP2 = false>
; __device__ __forceinline__ void gemm_phase(PG8_LAS unsigned char* lds, const Gemm g, const Sched& S, const Epi& E, const int wave_id) {
;     ...
;         for (int t = 0; t < nt; t += 2) {
;             const bool last = (t == nt - 2);
;             const char* a1 = cA + (size_t)(t + 1) * kstep;
;             const char* a2 = last ? nA : cA + (size_t)(t + 2) * kstep; const char* b2 = last ? nB : cB + (size_t)(t + 2) * kstep;
;             const char* a3 = a2 + kstep; const char* b3 = b2 + kstep;
;             if (last && has_next) S.a_ready(nxt);
;             if constexpr (SP2) {
;             PG8_LDB(B0, 0, 0); PG8_LDB(B1, 0, 1); PG8_SCHED; PG8_LDA(At, 0, 0); PG8_STAGE(PG8_SA(1, 1), a1 + hstep, voffA);
;             PG8_WAIT_V(8); PG8_WAIT_L(0); PG8_BAR; PG8_MMA(0, 0, At, B0); PG8_MMA(0, 1, At, B1); PG8_BAR; PG8_SCHED;
;             PG8_LDA(At, 0, 1); PG8_STAGE(PG8_SB(0, 0), b2, voffB); PG8_STAGE(PG8_SB(0, 1), b2 + hstep, voffB); PG8_STAGE(PG8_SA(0, 0), a2, voffA);
;             PG8_WAIT_V(8); PG8_WAIT_L(0); PG8_BAR; PG8_MMA(1, 0, At, B0); PG8_MMA(1, 1, At, B1); PG8_BAR; PG8_SCHED;
;             PG8_LDB(B0, 1, 0); PG8_LDB(B1, 1, 1); PG8_SCHED; PG8_LDA(At, 1, 0); PG8_STAGE(PG8_SA(0, 1), a2 + hstep, voffA);
;             PG8_WAIT_V(8); PG8_WAIT_L(0); PG8_BAR; PG8_MMA(0, 0, At, B0); PG8_MMA(0, 1, At, B1); PG8_BAR; PG8_SCHED;
;             PG8_LDA(At, 1, 1); PG8_STAGE(PG8_SB(1, 0), b3, voffB); PG8_STAGE(PG8_SB(1, 1), b3 + hstep, voffB); PG8_STAGE(PG8_SA(1, 0), a3, voffA);
;             PG8_WAIT_V(8); PG8_WAIT_L(0); PG8_BAR; PG8_MMA(1, 0, At, B0); PG8_MMA(1, 1, At, B1); PG8_BAR; PG8_SCHED;
	s_setprio 1
	s_waitcnt lgkmcnt(0)
	v_mfma_f32_16x16x32_bf16 v[142:145], v[118:121], v[162:165], v[142:145]
	v_mfma_f32_16x16x32_bf16 v[138:141], v[130:133], v[162:165], v[138:141]
	v_mfma_f32_16x16x32_bf16 v[110:113], v[118:121], v[170:173], v[110:113]
	v_mfma_f32_16x16x32_bf16 v[106:109], v[130:133], v[170:173], v[106:109]
	v_mfma_f32_16x16x32_bf16 v[94:97], v[118:121], v[178:181], v[94:97]
	v_mfma_f32_16x16x32_bf16 v[90:93], v[130:133], v[178:181], v[90:93]
	v_mfma_f32_16x16x32_bf16 v[78:81], v[118:121], v[186:189], v[78:81]
	v_mfma_f32_16x16x32_bf16 v[74:77], v[130:133], v[186:189], v[74:77]
	v_mfma_f32_16x16x32_bf16 v[142:145], v[122:125], v[166:169], v[142:145]
	v_mfma_f32_16x16x32_bf16 v[138:141], v[134:137], v[166:169], v[138:141]
	v_mfma_f32_16x16x32_bf16 v[110:113], v[122:125], v[174:177], v[110:113]
	v_mfma_f32_16x16x32_bf16 v[106:109], v[134:137], v[174:177], v[106:109]
	v_mfma_f32_16x16x32_bf16 v[94:97], v[122:125], v[182:185], v[94:97]
	v_mfma_f32_16x16x32_bf16 v[90:93], v[134:137], v[182:185], v[90:93]
	v_mfma_f32_16x16x32_bf16 v[78:81], v[122:125], v[214:217], v[78:81]
	v_mfma_f32_16x16x32_bf16 v[74:77], v[134:137], v[214:217], v[74:77]
	s_setprio 0
	s_setprio 1
	v_mfma_f32_16x16x32_bf16 v[126:129], v[146:149], v[162:165], v[126:129]
	v_mfma_f32_16x16x32_bf16 v[114:117], v[154:157], v[162:165], v[114:117]
	v_mfma_f32_16x16x32_bf16 v[102:105], v[146:149], v[170:173], v[102:105]
	v_mfma_f32_16x16x32_bf16 v[98:101], v[154:157], v[170:173], v[98:101]
	v_mfma_f32_16x16x32_bf16 v[86:89], v[146:149], v[178:181], v[86:89]
	v_mfma_f32_16x16x32_bf16 v[82:85], v[154:157], v[178:181], v[82:85]
	v_mfma_f32_16x16x32_bf16 v[70:73], v[146:149], v[186:189], v[70:73]
	v_mfma_f32_16x16x32_bf16 v[66:69], v[154:157], v[186:189], v[66:69]
	v_mfma_f32_16x16x32_bf16 v[126:129], v[150:153], v[166:169], v[126:129]
	v_mfma_f32_16x16x32_bf16 v[114:117], v[158:161], v[166:169], v[114:117]
	v_mfma_f32_16x16x32_bf16 v[102:105], v[150:153], v[174:177], v[102:105]
	v_mfma_f32_16x16x32_bf16 v[98:101], v[158:161], v[174:177], v[98:101]
	v_mfma_f32_16x16x32_bf16 v[86:89], v[150:153], v[182:185], v[86:89]
	v_mfma_f32_16x16x32_bf16 v[82:85], v[158:161], v[182:185], v[82:85]
	v_mfma_f32_16x16x32_bf16 v[70:73], v[150:153], v[214:217], v[70:73]
	v_mfma_f32_16x16x32_bf16 v[66:69], v[158:161], v[214:217], v[66:69]
	s_setprio 0
	s_barrier
	s_add_i32 s77, s77, s53
	s_mov_b32 m0, s77
	s_nop 0
	global_load_lds_dwordx4 v192, s[42:43]
	ds_read_b128 v[162:165], v222 offset:16384
	ds_read_b128 v[166:169], v222 offset:17408
	s_add_i32 m0, s77, 0x2000
	s_add_u32 s80, s42, 0x80000
	s_addc_u32 s81, s43, 0
	s_add_i32 s77, s79, s53
	global_load_lds_dwordx4 v208, s[42:43]
	ds_read_b128 v[170:173], v222 offset:18432
	ds_read_b128 v[174:177], v222 offset:19456
	s_mov_b32 m0, s77
	s_nop 0
	global_load_lds_dwordx4 v192, s[80:81]
	ds_read_b128 v[178:181], v222 offset:20480
	ds_read_b128 v[182:185], v222 offset:21504
	s_add_i32 m0, s77, 0x2000
	s_nop 0
	global_load_lds_dwordx4 v208, s[80:81]
	ds_read_b128 v[186:189], v222 offset:22528
	ds_read_b128 v[214:217], v222 offset:23552
	s_mov_b32 m0, s56
	s_nop 0
	global_load_lds_dwordx4 v190, s[44:45]
	s_mov_b32 m0, s57
	s_nop 0
	global_load_lds_dwordx4 v206, s[44:45]
	s_waitcnt vmcnt(8)
	s_waitcnt lgkmcnt(0)
	s_barrier
	s_setprio 1
	s_waitcnt lgkmcnt(0)
	v_mfma_f32_16x16x32_bf16 v[62:65], v[118:121], v[162:165], v[62:65]
	v_mfma_f32_16x16x32_bf16 v[58:61], v[130:133], v[162:165], v[58:61]
	v_mfma_f32_16x16x32_bf16 v[46:49], v[118:121], v[170:173], v[46:49]
	v_mfma_f32_16x16x32_bf16 v[42:45], v[130:133], v[170:173], v[42:45]
	v_mfma_f32_16x16x32_bf16 v[30:33], v[118:121], v[178:181], v[30:33]
	v_mfma_f32_16x16x32_bf16 v[26:29], v[130:133], v[178:181], v[26:29]
	v_mfma_f32_16x16x32_bf16 v[14:17], v[118:121], v[186:189], v[14:17]
	v_mfma_f32_16x16x32_bf16 v[10:13], v[130:133], v[186:189], v[10:13]
	v_mfma_f32_16x16x32_bf16 v[62:65], v[122:125], v[166:169], v[62:65]
	v_mfma_f32_16x16x32_bf16 v[58:61], v[134:137], v[166:169], v[58:61]
	v_mfma_f32_16x16x32_bf16 v[46:49], v[122:125], v[174:177], v[46:49]
	v_mfma_f32_16x16x32_bf16 v[42:45], v[134:137], v[174:177], v[42:45]
	v_mfma_f32_16x16x32_bf16 v[30:33], v[122:125], v[182:185], v[30:33]
	v_mfma_f32_16x16x32_bf16 v[26:29], v[134:137], v[182:185], v[26:29]
	v_mfma_f32_16x16x32_bf16 v[14:17], v[122:125], v[214:217], v[14:17]
	v_mfma_f32_16x16x32_bf16 v[10:13], v[134:137], v[214:217], v[10:13]
	s_setprio 0
	s_setprio 1
	v_mfma_f32_16x16x32_bf16 v[54:57], v[146:149], v[162:165], v[54:57]
	v_mfma_f32_16x16x32_bf16 v[50:53], v[154:157], v[162:165], v[50:53]
	v_mfma_f32_16x16x32_bf16 v[38:41], v[146:149], v[170:173], v[38:41]
	v_mfma_f32_16x16x32_bf16 v[34:37], v[154:157], v[170:173], v[34:37]
	v_mfma_f32_16x16x32_bf16 v[22:25], v[146:149], v[178:181], v[22:25]
	v_mfma_f32_16x16x32_bf16 v[18:21], v[154:157], v[178:181], v[18:21]
	v_mfma_f32_16x16x32_bf16 v[6:9], v[146:149], v[186:189], v[6:9]
	v_mfma_f32_16x16x32_bf16 v[2:5], v[154:157], v[186:189], v[2:5]
	v_mfma_f32_16x16x32_bf16 v[54:57], v[150:153], v[166:169], v[54:57]
	v_mfma_f32_16x16x32_bf16 v[50:53], v[158:161], v[166:169], v[50:53]
	v_mfma_f32_16x16x32_bf16 v[38:41], v[150:153], v[174:177], v[38:41]
	v_mfma_f32_16x16x32_bf16 v[34:37], v[158:161], v[174:177], v[34:37]
	v_mfma_f32_16x16x32_bf16 v[22:25], v[150:153], v[182:185], v[22:25]
	v_mfma_f32_16x16x32_bf16 v[18:21], v[158:161], v[182:185], v[18:21]
	v_mfma_f32_16x16x32_bf16 v[6:9], v[150:153], v[214:217], v[6:9]
	v_mfma_f32_16x16x32_bf16 v[2:5], v[158:161], v[214:217], v[2:5]
	s_setprio 0
	s_barrier
; #define PG8_STAGE(bufoff, gbase, voff) do { _Pragma("unroll") for (int _i = 0; _i < 2; ++_i) \
;         __builtin_amdgcn_global_load_lds((const unsigned*)((const char*)(gbase) + (voff)[_i]), (PG8_LAS unsigned*)(lds + (bufoff) + ldsw + _i * 8192), 16, 0, 0); } while (0)
; #define PG8_LDA(dst, b, h) do { _Pragma("unroll") for (int m = 0; m < 4; ++m) _Pragma("unroll") for (int k = 0; k < 2; ++k) dst[m][k] = *(const PG8_LAS bf16x8*)(lds + PG8_SA(b, h) + aoff + m * 2048 + k * 1024); } while (0)
; #define PG8_WAIT_V(n) asm volatile("s_waitcnt vmcnt(" #n ")" ::: "memory")
; #define PG8_WAIT_L(n) asm volatile("s_waitcnt lgkmcnt(" #n ")" ::: "memory")
; #define PG8_BAR __builtin_amdgcn_s_barrier()
; template <class Epi, class Sched, bool ALIGN_EPI = false, bool SP2 = false>
; __device__ __forceinline__ void gemm_phase(PG8_LAS unsigned char* lds, const Gemm g, const Sched& S, const Epi& E, const int wave_id) {
;     ...
;         for (int t = 0; t < nt; t += 2) {
;             const bool last = (t == nt - 2);
;             const char* a1 = cA + (size_t)(t + 1) * kstep;
;             const char* a2 = last ? nA : cA + (size_t)(t + 2) * kstep; const char* b2 = last ? nB : cB + (size_t)(t + 2) * kstep;
;             const char* a3 = a2 + kstep; const char* b3 = b2 + kstep;
;             if (last && has_next) S.a_ready(nxt);
;             if constexpr (SP2) {
;             PG8_LDB(B0, 0, 0); PG8_LDB(B1, 0, 1); PG8_SCHED; PG8_LDA(At, 0, 0); PG8_STAGE(PG8_SA(1, 1), a1 + hstep, voffA);
;             PG8_WAIT_V(8); PG8_WAIT_L(0); PG8_BAR; PG8_MMA(0, 0, At, B0); PG8_MMA(0, 1, At, B1); PG8_BAR; PG8_SCHED;
;             PG8_LDA(At, 0, 1); PG8_STAGE(PG8_SB(0, 0), b2, voffB); PG8_STAGE(PG8_SB(0, 1), b2 + hstep, voffB); PG8_STAGE(PG8_SA(0, 0), a2, voffA);
;             PG8_WAIT_V(8); PG8_WAIT_L(0); PG8_BAR; PG8_MMA(1, 0, At, B0); PG8_MMA(1, 1, At, B1); PG8_BAR; PG8_SCHED;
;             PG8_LDB(B0, 1, 0); PG8_LDB(B1, 1, 1); PG8_SCHED; PG8_LDA(At, 1, 0); PG8_STAGE(PG8_SA(0, 1), a2 + hstep, voffA);
;             PG8_WAIT_V(8); PG8_WAIT_L(0); PG8_BAR; PG8_MMA(0, 0, At, B0); PG8_MMA(0, 1, At, B1); PG8_BAR; PG8_SCHED;
;             PG8_LDA(At, 1, 1); PG8_STAGE(PG8_SB(1, 0), b3, voffB); PG8_STAGE(PG8_SB(1, 1), b3 + hstep, voffB); PG8_STAGE(PG8_SA(1, 0), a3, voffA);
;             PG8_WAIT_V(8); PG8_WAIT_L(0); PG8_BAR; PG8_MMA(1, 0, At, B0); PG8_MMA(1, 1, At, B1); PG8_BAR; PG8_SCHED;
	s_add_i32 s77, 0, 0x18000
	s_add_i32 s79, 0, 0x1c000
	s_add_u32 s44, s44, 0x80000
	s_addc_u32 s45, s45, 0
	s_mov_b32 m0, s64
	s_nop 0
	global_load_lds_dwordx4 v190, s[44:45]
	ds_read_b128 v[118:121], v226 offset:32768
	ds_read_b128 v[122:125], v226 offset:33792
	ds_read_b128 v[130:133], v226 offset:34816
	ds_read_b128 v[134:137], v226 offset:35840
	ds_read_b128 v[146:149], v226 offset:49152
	ds_read_b128 v[150:153], v226 offset:50176
	ds_read_b128 v[154:157], v226 offset:51200
	ds_read_b128 v[158:161], v226 offset:52224
	s_mov_b32 m0, s65
	s_nop 0
	global_load_lds_dwordx4 v206, s[44:45]
	ds_read_b128 v[162:165], v222 offset:32768
	ds_read_b128 v[166:169], v222 offset:33792
	ds_read_b128 v[170:173], v222 offset:34816
	ds_read_b128 v[174:177], v222 offset:35840
	ds_read_b128 v[178:181], v222 offset:36864
	ds_read_b128 v[182:185], v222 offset:37888
	ds_read_b128 v[186:189], v222 offset:38912
	ds_read_b128 v[214:217], v222 offset:39936
	s_waitcnt vmcnt(8)
	s_waitcnt lgkmcnt(0)
	s_barrier
	s_setprio 1
	s_waitcnt lgkmcnt(0)
	v_mfma_f32_16x16x32_bf16 v[142:145], v[118:121], v[162:165], v[142:145]
	v_mfma_f32_16x16x32_bf16 v[138:141], v[130:133], v[162:165], v[138:141]
	v_mfma_f32_16x16x32_bf16 v[110:113], v[118:121], v[170:173], v[110:113]
	v_mfma_f32_16x16x32_bf16 v[106:109], v[130:133], v[170:173], v[106:109]
	v_mfma_f32_16x16x32_bf16 v[94:97], v[118:121], v[178:181], v[94:97]
	v_mfma_f32_16x16x32_bf16 v[90:93], v[130:133], v[178:181], v[90:93]
	v_mfma_f32_16x16x32_bf16 v[78:81], v[118:121], v[186:189], v[78:81]
	v_mfma_f32_16x16x32_bf16 v[74:77], v[130:133], v[186:189], v[74:77]
	v_mfma_f32_16x16x32_bf16 v[142:145], v[122:125], v[166:169], v[142:145]
	v_mfma_f32_16x16x32_bf16 v[138:141], v[134:137], v[166:169], v[138:141]
	v_mfma_f32_16x16x32_bf16 v[110:113], v[122:125], v[174:177], v[110:113]
	v_mfma_f32_16x16x32_bf16 v[106:109], v[134:137], v[174:177], v[106:109]
	v_mfma_f32_16x16x32_bf16 v[94:97], v[122:125], v[182:185], v[94:97]
	v_mfma_f32_16x16x32_bf16 v[90:93], v[134:137], v[182:185], v[90:93]
	v_mfma_f32_16x16x32_bf16 v[78:81], v[122:125], v[214:217], v[78:81]
	v_mfma_f32_16x16x32_bf16 v[74:77], v[134:137], v[214:217], v[74:77]
	s_setprio 0
	s_setprio 1
	v_mfma_f32_16x16x32_bf16 v[126:129], v[146:149], v[162:165], v[126:129]
	v_mfma_f32_16x16x32_bf16 v[114:117], v[154:157], v[162:165], v[114:117]
	v_mfma_f32_16x16x32_bf16 v[102:105], v[146:149], v[170:173], v[102:105]
	v_mfma_f32_16x16x32_bf16 v[98:101], v[154:157], v[170:173], v[98:101]
	v_mfma_f32_16x16x32_bf16 v[86:89], v[146:149], v[178:181], v[86:89]
	v_mfma_f32_16x16x32_bf16 v[82:85], v[154:157], v[178:181], v[82:85]
	v_mfma_f32_16x16x32_bf16 v[70:73], v[146:149], v[186:189], v[70:73]
	v_mfma_f32_16x16x32_bf16 v[66:69], v[154:157], v[186:189], v[66:69]
	v_mfma_f32_16x16x32_bf16 v[126:129], v[150:153], v[166:169], v[126:129]
	v_mfma_f32_16x16x32_bf16 v[114:117], v[158:161], v[166:169], v[114:117]
	v_mfma_f32_16x16x32_bf16 v[102:105], v[150:153], v[174:177], v[102:105]
	v_mfma_f32_16x16x32_bf16 v[98:101], v[158:161], v[174:177], v[98:101]
	v_mfma_f32_16x16x32_bf16 v[86:89], v[150:153], v[182:185], v[86:89]
	v_mfma_f32_16x16x32_bf16 v[82:85], v[158:161], v[182:185], v[82:85]
	v_mfma_f32_16x16x32_bf16 v[70:73], v[150:153], v[214:217], v[70:73]
	v_mfma_f32_16x16x32_bf16 v[66:69], v[158:161], v[214:217], v[66:69]
	s_setprio 0
	s_barrier
	s_add_u32 vcc_lo, s44, 0xfff80080
	s_addc_u32 vcc_hi, s45, -1
	s_mov_b32 m0, s70
	s_nop 0
	global_load_lds_dwordx4 v190, vcc
	ds_read_b128 v[162:165], v222 offset:49152
	ds_read_b128 v[166:169], v222 offset:50176
	s_mov_b32 m0, s71
	s_add_i32 s44, s77, s53
	global_load_lds_dwordx4 v206, vcc
	ds_read_b128 v[170:173], v222 offset:51200
	ds_read_b128 v[174:177], v222 offset:52224
	s_add_u32 vcc_lo, s42, 0x80
	s_addc_u32 vcc_hi, s43, 0
	s_mov_b32 m0, s44
	s_nop 0
	global_load_lds_dwordx4 v192, vcc
	ds_read_b128 v[178:181], v222 offset:53248
	ds_read_b128 v[182:185], v222 offset:54272
	s_add_i32 m0, s44, 0x2000
	s_add_u32 s42, s42, 0x80080
	s_addc_u32 s43, s43, 0
	global_load_lds_dwordx4 v208, vcc
	ds_read_b128 v[186:189], v222 offset:55296
	ds_read_b128 v[214:217], v222 offset:56320
	s_add_i32 s44, s79, s53
	s_mov_b32 m0, s44
	s_nop 0
	global_load_lds_dwordx4 v192, s[42:43]
	s_add_i32 m0, s44, 0x2000
	s_nop 0
	global_load_lds_dwordx4 v208, s[42:43]
	s_waitcnt vmcnt(8)
	s_waitcnt lgkmcnt(0)
	s_barrier
	s_setprio 1
	s_waitcnt lgkmcnt(0)
	v_mfma_f32_16x16x32_bf16 v[62:65], v[118:121], v[162:165], v[62:65]
	v_mfma_f32_16x16x32_bf16 v[58:61], v[130:133], v[162:165], v[58:61]
	v_mfma_f32_16x16x32_bf16 v[46:49], v[118:121], v[170:173], v[46:49]
	v_mfma_f32_16x16x32_bf16 v[42:45], v[130:133], v[170:173], v[42:45]
	v_mfma_f32_16x16x32_bf16 v[30:33], v[118:121], v[178:181], v[30:33]
	v_mfma_f32_16x16x32_bf16 v[26:29], v[130:133], v[178:181], v[26:29]
	v_mfma_f32_16x16x32_bf16 v[14:17], v[118:121], v[186:189], v[14:17]
	v_mfma_f32_16x16x32_bf16 v[10:13], v[130:133], v[186:189], v[10:13]
	v_mfma_f32_16x16x32_bf16 v[62:65], v[122:125], v[166:169], v[62:65]
	v_mfma_f32_16x16x32_bf16 v[58:61], v[134:137], v[166:169], v[58:61]
	v_mfma_f32_16x16x32_bf16 v[46:49], v[122:125], v[174:177], v[46:49]
	v_mfma_f32_16x16x32_bf16 v[42:45], v[134:137], v[174:177], v[42:45]
	v_mfma_f32_16x16x32_bf16 v[30:33], v[122:125], v[182:185], v[30:33]
	v_mfma_f32_16x16x32_bf16 v[26:29], v[134:137], v[182:185], v[26:29]
	v_mfma_f32_16x16x32_bf16 v[14:17], v[122:125], v[214:217], v[14:17]
	v_mfma_f32_16x16x32_bf16 v[10:13], v[134:137], v[214:217], v[10:13]
	s_setprio 0
	s_setprio 1
	v_mfma_f32_16x16x32_bf16 v[54:57], v[146:149], v[162:165], v[54:57]
	v_mfma_f32_16x16x32_bf16 v[50:53], v[154:157], v[162:165], v[50:53]
	v_mfma_f32_16x16x32_bf16 v[38:41], v[146:149], v[170:173], v[38:41]
	v_mfma_f32_16x16x32_bf16 v[34:37], v[154:157], v[170:173], v[34:37]
	v_mfma_f32_16x16x32_bf16 v[22:25], v[146:149], v[178:181], v[22:25]
	v_mfma_f32_16x16x32_bf16 v[18:21], v[154:157], v[178:181], v[18:21]
	v_mfma_f32_16x16x32_bf16 v[6:9], v[146:149], v[186:189], v[6:9]
	v_mfma_f32_16x16x32_bf16 v[2:5], v[154:157], v[186:189], v[2:5]
	v_mfma_f32_16x16x32_bf16 v[54:57], v[150:153], v[166:169], v[54:57]
	v_mfma_f32_16x16x32_bf16 v[50:53], v[158:161], v[166:169], v[50:53]
	v_mfma_f32_16x16x32_bf16 v[38:41], v[150:153], v[174:177], v[38:41]
	v_mfma_f32_16x16x32_bf16 v[34:37], v[158:161], v[174:177], v[34:37]
	v_mfma_f32_16x16x32_bf16 v[22:25], v[150:153], v[182:185], v[22:25]
	v_mfma_f32_16x16x32_bf16 v[18:21], v[158:161], v[182:185], v[18:21]
	v_mfma_f32_16x16x32_bf16 v[6:9], v[150:153], v[214:217], v[6:9]
	v_mfma_f32_16x16x32_bf16 v[2:5], v[158:161], v[214:217], v[2:5]
	s_setprio 0
	s_barrier
	s_add_i32 s76, s76, 2
	s_add_u32 s40, s40, 0x100
	s_addc_u32 s41, s41, 0
	s_add_u32 s74, s74, 0x100
	s_addc_u32 s75, s75, 0
	s_cmp_gt_u32 s76, 29
	s_cbranch_scc0 .LBB0_524

;     __host__ __device__ bool next(int i, Unit& u) const { const bool ok = StaticOrder::next(i, u); u.lm = 0; u.ln = 0; return ok; }
; #define PG8_BAR __builtin_amdgcn_s_barrier()
; template <class Epi, class Sched, bool ALIGN_EPI = false, bool SP2 = false>
; __device__ __forceinline__ void gemm_phase(PG8_LAS unsigned char* lds, const Gemm g, const Sched& S, const Epi& E, const int wave_id) {
;     ...
;         const bool has_next = S.next(ui + 1, nxt);
;         const char* nA = has_next ? (const char*)g.A + (size_t)nxt.lm * tstep : cA; const char* nB = has_next ? (const char*)g.Bt + (size_t)nxt.ln * tstep : cB;
; #pragma unroll 1
;         for (int t = 0; t < nt; t += 2) {
;             const bool last = (t == nt - 2);
;             const char* a1 = cA + (size_t)(t + 1) * kstep;
;             const char* a2 = last ? nA : cA + (size_t)(t + 2) * kstep; const char* b2 = last ? nB : cB + (size_t)(t + 2) * kstep;
;             const char* a3 = a2 + kstep; const char* b3 = b2 + kstep;
;             if (last && has_next) S.a_ready(nxt);
;             if constexpr (SP2) {
;             PG8_LDB(B0, 0, 0); PG8_LDB(B1, 0, 1); PG8_SCHED; PG8_LDA(At, 0, 0); PG8_STAGE(PG8_SA(1, 1), a1 + hstep, voffA);
;             PG8_WAIT_V(8); PG8_WAIT_L(0); PG8_BAR; PG8_MMA(0, 0, At, B0); PG8_MMA(0, 1, At, B1); PG8_BAR; PG8_SCHED;
;             PG8_LDA(At, 0, 1); PG8_STAGE(PG8_SB(0, 0), b2, voffB); PG8_STAGE(PG8_SB(0, 1), b2 + hstep, voffB); PG8_STAGE(PG8_SA(0, 0), a2, voffA);
;             PG8_WAIT_V(8); PG8_WAIT_L(0); PG8_BAR; PG8_MMA(1, 0, At, B0); PG8_MMA(1, 1, At, B1); PG8_BAR; PG8_SCHED;
;             PG8_LDB(B0, 1, 0); PG8_LDB(B1, 1, 1); PG8_SCHED; PG8_LDA(At, 1, 0); PG8_STAGE(PG8_SA(0, 1), a2 + hstep, voffA);
;             PG8_WAIT_V(8); PG8_WAIT_L(0); PG8_BAR; PG8_MMA(0, 0, At, B0); PG8_MMA(0, 1, At, B1); PG8_BAR; PG8_SCHED;
;             PG8_LDA(At, 1, 1); PG8_STAGE(PG8_SB(1, 0), b3, voffB); PG8_STAGE(PG8_SB(1, 1), b3 + hstep, voffB); PG8_STAGE(PG8_SA(1, 0), a3, voffA);
;             PG8_WAIT_V(8); PG8_WAIT_L(0); PG8_BAR; PG8_MMA(1, 0, At, B0); PG8_MMA(1, 1, At, B1); PG8_BAR; PG8_SCHED;
;     ...
; #pragma unroll
;         for (int a = 0; a < 2; ++a)
; #pragma unroll
;             for (int b = 0; b < 2; ++b)
; #pragma unroll
;                 for (int m = 0; m < 4; ++m)
; #pragma unroll
;                     for (int n = 0; n < 2; ++n) acc[a][b][m][n] = (f32x4){0.f, 0.f, 0.f, 0.f};
.LBB0_640:
	s_ashr_i32 s15, s14, 31
	s_lshl_b64 s[16:17], s[14:15], 20
	s_add_u32 s16, s47, s16
	s_addc_u32 s17, s48, s17
	s_and_b64 s[18:19], s[38:39], exec
	s_cselect_b32 s15, s17, s21
	s_cselect_b32 s71, s16, s20
	s_ashr_i32 s13, s12, 31
	s_lshl_b64 s[18:19], s[12:13], 20
	s_add_u32 s18, s49, s18
	s_addc_u32 s19, s52, s19
	s_and_b64 s[44:45], s[38:39], exec
	s_cselect_b32 s13, s19, s43
	s_cselect_b32 s72, s18, s42
	s_add_u32 s20, s20, 0x80080
	s_addc_u32 s21, s21, 0
	s_add_u32 s73, s42, 0x100
	s_addc_u32 s74, s43, 0
	s_mov_b32 s75, -2
	v_add_u32_e32 v144, 0x10000, v147
	s_add_u32 s42, s20, 0xfff80080
	s_addc_u32 s43, s21, -1
	s_add_i32 s76, 0, 0x10000
	s_cmp_eq_u32 s75, 28
	s_cselect_b32 s45, s15, s43
	s_cselect_b32 s44, s71, s42
	s_cselect_b32 s43, s13, s74
	s_cselect_b32 s42, s72, s73
	s_add_i32 s79, 0, 0x14000
	s_add_i32 m0, s53, 0xc000
	s_nop 0
	global_load_lds_dwordx4 v138, s[20:21]
	ds_read_b128 v[158:161], v144
	ds_read_b128 v[162:165], v144 offset:1024
	ds_read_b128 v[166:169], v144 offset:2048
	ds_read_b128 v[170:173], v144 offset:3072
	ds_read_b128 v[174:177], v144 offset:16384
	ds_read_b128 v[178:181], v144 offset:17408
	ds_read_b128 v[182:185], v144 offset:18432
	ds_read_b128 v[186:189], v144 offset:19456
	s_add_i32 m0, s53, 0xe000
	s_nop 0
	global_load_lds_dwordx4 v140, s[20:21]
	ds_read_b128 v[190:193], v155
	ds_read_b128 v[206:209], v155 offset:1024
	ds_read_b128 v[210:213], v155 offset:2048
	ds_read_b128 v[214:217], v155 offset:3072
	ds_read_b128 v[226:229], v155 offset:4096
	ds_read_b128 v[234:237], v155 offset:5120
	ds_read_b128 v[238:241], v155 offset:6144
	ds_read_b128 v[242:245], v155 offset:7168
	s_waitcnt vmcnt(8)
	s_waitcnt lgkmcnt(0)
	s_barrier
	s_setprio 1
	s_waitcnt lgkmcnt(0)
	v_mfma_f32_16x16x32_bf16 v[126:129], v[158:161], v[190:193], 0
	v_mfma_f32_16x16x32_bf16 v[118:121], v[166:169], v[190:193], 0
	v_mfma_f32_16x16x32_bf16 v[110:113], v[158:161], v[210:213], 0
	v_mfma_f32_16x16x32_bf16 v[102:105], v[166:169], v[210:213], 0
	v_mfma_f32_16x16x32_bf16 v[94:97], v[158:161], v[226:229], 0
	v_mfma_f32_16x16x32_bf16 v[86:89], v[166:169], v[226:229], 0
	v_mfma_f32_16x16x32_bf16 v[78:81], v[158:161], v[238:241], 0
	v_mfma_f32_16x16x32_bf16 v[70:73], v[166:169], v[238:241], 0
	v_mfma_f32_16x16x32_bf16 v[126:129], v[162:165], v[206:209], v[126:129]
	v_mfma_f32_16x16x32_bf16 v[118:121], v[170:173], v[206:209], v[118:121]
	v_mfma_f32_16x16x32_bf16 v[110:113], v[162:165], v[214:217], v[110:113]
	v_mfma_f32_16x16x32_bf16 v[102:105], v[170:173], v[214:217], v[102:105]
	v_mfma_f32_16x16x32_bf16 v[94:97], v[162:165], v[234:237], v[94:97]
	v_mfma_f32_16x16x32_bf16 v[86:89], v[170:173], v[234:237], v[86:89]
	v_mfma_f32_16x16x32_bf16 v[78:81], v[162:165], v[242:245], v[78:81]
	v_mfma_f32_16x16x32_bf16 v[70:73], v[170:173], v[242:245], v[70:73]
	s_setprio 0
	s_setprio 1
	v_mfma_f32_16x16x32_bf16 v[122:125], v[174:177], v[190:193], 0
	v_mfma_f32_16x16x32_bf16 v[114:117], v[182:185], v[190:193], 0
	v_mfma_f32_16x16x32_bf16 v[106:109], v[174:177], v[210:213], 0
	v_mfma_f32_16x16x32_bf16 v[98:101], v[182:185], v[210:213], 0
	v_mfma_f32_16x16x32_bf16 v[90:93], v[174:177], v[226:229], 0
	v_mfma_f32_16x16x32_bf16 v[82:85], v[182:185], v[226:229], 0
	v_mfma_f32_16x16x32_bf16 v[74:77], v[174:177], v[238:241], 0
	v_mfma_f32_16x16x32_bf16 v[66:69], v[182:185], v[238:241], 0
	v_mfma_f32_16x16x32_bf16 v[122:125], v[178:181], v[206:209], v[122:125]
	v_mfma_f32_16x16x32_bf16 v[114:117], v[186:189], v[206:209], v[114:117]
	v_mfma_f32_16x16x32_bf16 v[106:109], v[178:181], v[214:217], v[106:109]
	v_mfma_f32_16x16x32_bf16 v[98:101], v[186:189], v[214:217], v[98:101]
	v_mfma_f32_16x16x32_bf16 v[90:93], v[178:181], v[234:237], v[90:93]
	v_mfma_f32_16x16x32_bf16 v[82:85], v[186:189], v[234:237], v[82:85]
	v_mfma_f32_16x16x32_bf16 v[74:77], v[178:181], v[242:245], v[74:77]
	v_mfma_f32_16x16x32_bf16 v[66:69], v[186:189], v[242:245], v[66:69]
	s_setprio 0
	s_barrier
	s_add_i32 s76, s76, s41
	s_mov_b32 m0, s76
	s_nop 0
	global_load_lds_dwordx4 v132, s[42:43]
	ds_read_b128 v[190:193], v155 offset:16384
	ds_read_b128 v[206:209], v155 offset:17408
	s_add_i32 m0, s76, 0x2000
	s_add_u32 s76, s42, 0x80000
	s_addc_u32 s77, s43, 0
	s_add_i32 s79, s79, s41
	global_load_lds_dwordx4 v136, s[42:43]
	ds_read_b128 v[210:213], v155 offset:18432
	ds_read_b128 v[214:217], v155 offset:19456
	s_mov_b32 m0, s79
	s_nop 0
	global_load_lds_dwordx4 v132, s[76:77]
	ds_read_b128 v[226:229], v155 offset:20480
	ds_read_b128 v[234:237], v155 offset:21504
	s_add_i32 m0, s79, 0x2000
	s_nop 0
	global_load_lds_dwordx4 v136, s[76:77]
	ds_read_b128 v[238:241], v155 offset:22528
	ds_read_b128 v[242:245], v155 offset:23552
	s_mov_b32 m0, s53
	s_nop 0
	global_load_lds_dwordx4 v130, s[44:45]
	s_mov_b32 m0, s56
	s_nop 0
	global_load_lds_dwordx4 v134, s[44:45]
	s_waitcnt vmcnt(8)
	s_waitcnt lgkmcnt(0)
	s_barrier
; #define PG8_STAGE(bufoff, gbase, voff) do { _Pragma("unroll") for (int _i = 0; _i < 2; ++_i) \
;         __builtin_amdgcn_global_load_lds((const unsigned*)((const char*)(gbase) + (voff)[_i]), (PG8_LAS unsigned*)(lds + (bufoff) + ldsw + _i * 8192), 16, 0, 0); } while (0)
; #define PG8_LDA(dst, b, h) do { _Pragma("unroll") for (int m = 0; m < 4; ++m) _Pragma("unroll") for (int k = 0; k < 2; ++k) dst[m][k] = *(const PG8_LAS bf16x8*)(lds + PG8_SA(b, h) + aoff + m * 2048 + k * 1024); } while (0)
; #define PG8_WAIT_V(n) asm volatile("s_waitcnt vmcnt(" #n ")" ::: "memory")
; #define PG8_WAIT_L(n) asm volatile("s_waitcnt lgkmcnt(" #n ")" ::: "memory")
; #define PG8_BAR __builtin_amdgcn_s_barrier()
; template <class Epi, class Sched, bool ALIGN_EPI = false, bool SP2 = false>
; __device__ __forceinline__ void gemm_phase(PG8_LAS unsigned char* lds, const Gemm g, const Sched& S, const Epi& E, const int wave_id) {
;     ...
;         for (int t = 0; t < nt; t += 2) {
;             const bool last = (t == nt - 2);
;             const char* a1 = cA + (size_t)(t + 1) * kstep;
;             const char* a2 = last ? nA : cA + (size_t)(t + 2) * kstep; const char* b2 = last ? nB : cB + (size_t)(t + 2) * kstep;
;             const char* a3 = a2 + kstep; const char* b3 = b2 + kstep;
;             if (last && has_next) S.a_ready(nxt);
;             if constexpr (SP2) {
;             PG8_LDB(B0, 0, 0); PG8_LDB(B1, 0, 1); PG8_SCHED; PG8_LDA(At, 0, 0); PG8_STAGE(PG8_SA(1, 1), a1 + hstep, voffA);
;             PG8_WAIT_V(8); PG8_WAIT_L(0); PG8_BAR; PG8_MMA(0, 0, At, B0); PG8_MMA(0, 1, At, B1); PG8_BAR; PG8_SCHED;
;             PG8_LDA(At, 0, 1); PG8_STAGE(PG8_SB(0, 0), b2, voffB); PG8_STAGE(PG8_SB(0, 1), b2 + hstep, voffB); PG8_STAGE(PG8_SA(0, 0), a2, voffA);
;             PG8_WAIT_V(8); PG8_WAIT_L(0); PG8_BAR; PG8_MMA(1, 0, At, B0); PG8_MMA(1, 1, At, B1); PG8_BAR; PG8_SCHED;
;             PG8_LDB(B0, 1, 0); PG8_LDB(B1, 1, 1); PG8_SCHED; PG8_LDA(At, 1, 0); PG8_STAGE(PG8_SA(0, 1), a2 + hstep, voffA);
;             PG8_WAIT_V(8); PG8_WAIT_L(0); PG8_BAR; PG8_MMA(0, 0, At, B0); PG8_MMA(0, 1, At, B1); PG8_BAR; PG8_SCHED;
;             PG8_LDA(At, 1, 1); PG8_STAGE(PG8_SB(1, 0), b3, voffB); PG8_STAGE(PG8_SB(1, 1), b3 + hstep, voffB); PG8_STAGE(PG8_SA(1, 0), a3, voffA);
;             PG8_WAIT_V(8); PG8_WAIT_L(0); PG8_BAR; PG8_MMA(1, 0, At, B0); PG8_MMA(1, 1, At, B1); PG8_BAR; PG8_SCHED;
	s_setprio 1
	s_waitcnt lgkmcnt(0)
	v_mfma_f32_16x16x32_bf16 v[62:65], v[158:161], v[190:193], 0
	v_mfma_f32_16x16x32_bf16 v[54:57], v[166:169], v[190:193], 0
	v_mfma_f32_16x16x32_bf16 v[46:49], v[158:161], v[210:213], 0
	v_mfma_f32_16x16x32_bf16 v[38:41], v[166:169], v[210:213], 0
	v_mfma_f32_16x16x32_bf16 v[30:33], v[158:161], v[226:229], 0
	v_mfma_f32_16x16x32_bf16 v[22:25], v[166:169], v[226:229], 0
	v_mfma_f32_16x16x32_bf16 v[14:17], v[158:161], v[238:241], 0
	v_mfma_f32_16x16x32_bf16 v[6:9], v[166:169], v[238:241], 0
	v_mfma_f32_16x16x32_bf16 v[62:65], v[162:165], v[206:209], v[62:65]
	v_mfma_f32_16x16x32_bf16 v[54:57], v[170:173], v[206:209], v[54:57]
	v_mfma_f32_16x16x32_bf16 v[46:49], v[162:165], v[214:217], v[46:49]
	v_mfma_f32_16x16x32_bf16 v[38:41], v[170:173], v[214:217], v[38:41]
	v_mfma_f32_16x16x32_bf16 v[30:33], v[162:165], v[234:237], v[30:33]
	v_mfma_f32_16x16x32_bf16 v[22:25], v[170:173], v[234:237], v[22:25]
	v_mfma_f32_16x16x32_bf16 v[14:17], v[162:165], v[242:245], v[14:17]
	v_mfma_f32_16x16x32_bf16 v[6:9], v[170:173], v[242:245], v[6:9]
	s_setprio 0
	s_setprio 1
	v_mfma_f32_16x16x32_bf16 v[58:61], v[174:177], v[190:193], 0
	v_mfma_f32_16x16x32_bf16 v[50:53], v[182:185], v[190:193], 0
	v_mfma_f32_16x16x32_bf16 v[42:45], v[174:177], v[210:213], 0
	v_mfma_f32_16x16x32_bf16 v[34:37], v[182:185], v[210:213], 0
	v_mfma_f32_16x16x32_bf16 v[26:29], v[174:177], v[226:229], 0
	v_mfma_f32_16x16x32_bf16 v[18:21], v[182:185], v[226:229], 0
	v_mfma_f32_16x16x32_bf16 v[10:13], v[174:177], v[238:241], 0
	v_mfma_f32_16x16x32_bf16 v[2:5], v[182:185], v[238:241], 0
	v_mfma_f32_16x16x32_bf16 v[58:61], v[178:181], v[206:209], v[58:61]
	v_mfma_f32_16x16x32_bf16 v[50:53], v[186:189], v[206:209], v[50:53]
	v_mfma_f32_16x16x32_bf16 v[42:45], v[178:181], v[214:217], v[42:45]
	v_mfma_f32_16x16x32_bf16 v[34:37], v[186:189], v[214:217], v[34:37]
	v_mfma_f32_16x16x32_bf16 v[26:29], v[178:181], v[234:237], v[26:29]
	v_mfma_f32_16x16x32_bf16 v[18:21], v[186:189], v[234:237], v[18:21]
	v_mfma_f32_16x16x32_bf16 v[10:13], v[178:181], v[242:245], v[10:13]
	v_mfma_f32_16x16x32_bf16 v[2:5], v[186:189], v[242:245], v[2:5]
	s_setprio 0
	s_barrier
	s_add_i32 s76, 0, 0x18000
	s_add_i32 s77, 0, 0x1c000
	s_add_u32 s44, s44, 0x80000
	s_addc_u32 s45, s45, 0
	s_mov_b32 m0, s57
	s_nop 0
	global_load_lds_dwordx4 v130, s[44:45]
	ds_read_b128 v[158:161], v144 offset:32768
	ds_read_b128 v[162:165], v144 offset:33792
	ds_read_b128 v[166:169], v144 offset:34816
	ds_read_b128 v[170:173], v144 offset:35840
	ds_read_b128 v[174:177], v144 offset:49152
	ds_read_b128 v[178:181], v144 offset:50176
	ds_read_b128 v[182:185], v144 offset:51200
	ds_read_b128 v[186:189], v144 offset:52224
	s_mov_b32 m0, s64
	s_nop 0
	global_load_lds_dwordx4 v134, s[44:45]
	ds_read_b128 v[190:193], v155 offset:32768
	ds_read_b128 v[206:209], v155 offset:33792
	ds_read_b128 v[210:213], v155 offset:34816
	ds_read_b128 v[214:217], v155 offset:35840
	ds_read_b128 v[226:229], v155 offset:36864
	ds_read_b128 v[234:237], v155 offset:37888
	ds_read_b128 v[238:241], v155 offset:38912
	ds_read_b128 v[242:245], v155 offset:39936
	s_waitcnt vmcnt(8)
	s_waitcnt lgkmcnt(0)
	s_barrier
	s_setprio 1
	s_waitcnt lgkmcnt(0)
	v_mfma_f32_16x16x32_bf16 v[126:129], v[158:161], v[190:193], v[126:129]
	v_mfma_f32_16x16x32_bf16 v[118:121], v[166:169], v[190:193], v[118:121]
	v_mfma_f32_16x16x32_bf16 v[110:113], v[158:161], v[210:213], v[110:113]
	v_mfma_f32_16x16x32_bf16 v[102:105], v[166:169], v[210:213], v[102:105]
	v_mfma_f32_16x16x32_bf16 v[94:97], v[158:161], v[226:229], v[94:97]
	v_mfma_f32_16x16x32_bf16 v[86:89], v[166:169], v[226:229], v[86:89]
	v_mfma_f32_16x16x32_bf16 v[78:81], v[158:161], v[238:241], v[78:81]
	v_mfma_f32_16x16x32_bf16 v[70:73], v[166:169], v[238:241], v[70:73]
	v_mfma_f32_16x16x32_bf16 v[126:129], v[162:165], v[206:209], v[126:129]
	v_mfma_f32_16x16x32_bf16 v[118:121], v[170:173], v[206:209], v[118:121]
	v_mfma_f32_16x16x32_bf16 v[110:113], v[162:165], v[214:217], v[110:113]
	v_mfma_f32_16x16x32_bf16 v[102:105], v[170:173], v[214:217], v[102:105]
	v_mfma_f32_16x16x32_bf16 v[94:97], v[162:165], v[234:237], v[94:97]
	v_mfma_f32_16x16x32_bf16 v[86:89], v[170:173], v[234:237], v[86:89]
	v_mfma_f32_16x16x32_bf16 v[78:81], v[162:165], v[242:245], v[78:81]
	v_mfma_f32_16x16x32_bf16 v[70:73], v[170:173], v[242:245], v[70:73]
	s_setprio 0
	s_setprio 1
	v_mfma_f32_16x16x32_bf16 v[122:125], v[174:177], v[190:193], v[122:125]
	v_mfma_f32_16x16x32_bf16 v[114:117], v[182:185], v[190:193], v[114:117]
	v_mfma_f32_16x16x32_bf16 v[106:109], v[174:177], v[210:213], v[106:109]
	v_mfma_f32_16x16x32_bf16 v[98:101], v[182:185], v[210:213], v[98:101]
	v_mfma_f32_16x16x32_bf16 v[90:93], v[174:177], v[226:229], v[90:93]
	v_mfma_f32_16x16x32_bf16 v[82:85], v[182:185], v[226:229], v[82:85]
	v_mfma_f32_16x16x32_bf16 v[74:77], v[174:177], v[238:241], v[74:77]
	v_mfma_f32_16x16x32_bf16 v[66:69], v[182:185], v[238:241], v[66:69]
	v_mfma_f32_16x16x32_bf16 v[122:125], v[178:181], v[206:209], v[122:125]
	v_mfma_f32_16x16x32_bf16 v[114:117], v[186:189], v[206:209], v[114:117]
	v_mfma_f32_16x16x32_bf16 v[106:109], v[178:181], v[214:217], v[106:109]
	v_mfma_f32_16x16x32_bf16 v[98:101], v[186:189], v[214:217], v[98:101]
	v_mfma_f32_16x16x32_bf16 v[90:93], v[178:181], v[234:237], v[90:93]
	v_mfma_f32_16x16x32_bf16 v[82:85], v[186:189], v[234:237], v[82:85]
	v_mfma_f32_16x16x32_bf16 v[74:77], v[178:181], v[242:245], v[74:77]
	v_mfma_f32_16x16x32_bf16 v[66:69], v[186:189], v[242:245], v[66:69]
	s_setprio 0
	s_barrier
; #define PG8_STAGE(bufoff, gbase, voff) do { _Pragma("unroll") for (int _i = 0; _i < 2; ++_i) \
;         __builtin_amdgcn_global_load_lds((const unsigned*)((const char*)(gbase) + (voff)[_i]), (PG8_LAS unsigned*)(lds + (bufoff) + ldsw + _i * 8192), 16, 0, 0); } while (0)
; #define PG8_LDA(dst, b, h) do { _Pragma("unroll") for (int m = 0; m < 4; ++m) _Pragma("unroll") for (int k = 0; k < 2; ++k) dst[m][k] = *(const PG8_LAS bf16x8*)(lds + PG8_SA(b, h) + aoff + m * 2048 + k * 1024); } while (0)
; #define PG8_WAIT_V(n) asm volatile("s_waitcnt vmcnt(" #n ")" ::: "memory")
; #define PG8_WAIT_L(n) asm volatile("s_waitcnt lgkmcnt(" #n ")" ::: "memory")
; #define PG8_BAR __builtin_amdgcn_s_barrier()
; template <class Epi, class Sched, bool ALIGN_EPI = false, bool SP2 = false>
; __device__ __forceinline__ void gemm_phase(PG8_LAS unsigned char* lds, const Gemm g, const Sched& S, const Epi& E, const int wave_id) {
;     ...
;         for (int t = 0; t < nt; t += 2) {
;             const bool last = (t == nt - 2);
;             const char* a1 = cA + (size_t)(t + 1) * kstep;
;             const char* a2 = last ? nA : cA + (size_t)(t + 2) * kstep; const char* b2 = last ? nB : cB + (size_t)(t + 2) * kstep;
;             const char* a3 = a2 + kstep; const char* b3 = b2 + kstep;
;             if (last && has_next) S.a_ready(nxt);
;             if constexpr (SP2) {
;             PG8_LDB(B0, 0, 0); PG8_LDB(B1, 0, 1); PG8_SCHED; PG8_LDA(At, 0, 0); PG8_STAGE(PG8_SA(1, 1), a1 + hstep, voffA);
;             PG8_WAIT_V(8); PG8_WAIT_L(0); PG8_BAR; PG8_MMA(0, 0, At, B0); PG8_MMA(0, 1, At, B1); PG8_BAR; PG8_SCHED;
;             PG8_LDA(At, 0, 1); PG8_STAGE(PG8_SB(0, 0), b2, voffB); PG8_STAGE(PG8_SB(0, 1), b2 + hstep, voffB); PG8_STAGE(PG8_SA(0, 0), a2, voffA);
;             PG8_WAIT_V(8); PG8_WAIT_L(0); PG8_BAR; PG8_MMA(1, 0, At, B0); PG8_MMA(1, 1, At, B1); PG8_BAR; PG8_SCHED;
;             PG8_LDB(B0, 1, 0); PG8_LDB(B1, 1, 1); PG8_SCHED; PG8_LDA(At, 1, 0); PG8_STAGE(PG8_SA(0, 1), a2 + hstep, voffA);
;             PG8_WAIT_V(8); PG8_WAIT_L(0); PG8_BAR; PG8_MMA(0, 0, At, B0); PG8_MMA(0, 1, At, B1); PG8_BAR; PG8_SCHED;
;             PG8_LDA(At, 1, 1); PG8_STAGE(PG8_SB(1, 0), b3, voffB); PG8_STAGE(PG8_SB(1, 1), b3 + hstep, voffB); PG8_STAGE(PG8_SA(1, 0), a3, voffA);
;             PG8_WAIT_V(8); PG8_WAIT_L(0); PG8_BAR; PG8_MMA(1, 0, At, B0); PG8_MMA(1, 1, At, B1); PG8_BAR; PG8_SCHED;
	s_add_u32 vcc_lo, s44, 0xfff80080
	s_addc_u32 vcc_hi, s45, -1
	s_mov_b32 m0, s65
	s_nop 0
	global_load_lds_dwordx4 v130, vcc
	ds_read_b128 v[190:193], v155 offset:49152
	ds_read_b128 v[206:209], v155 offset:50176
	s_mov_b32 m0, s68
	s_add_i32 s44, s76, s41
	global_load_lds_dwordx4 v134, vcc
	ds_read_b128 v[210:213], v155 offset:51200
	ds_read_b128 v[214:217], v155 offset:52224
	s_add_u32 vcc_lo, s42, 0x80
	s_addc_u32 vcc_hi, s43, 0
	s_mov_b32 m0, s44
	s_nop 0
	global_load_lds_dwordx4 v132, vcc
	ds_read_b128 v[226:229], v155 offset:53248
	ds_read_b128 v[234:237], v155 offset:54272
	s_add_i32 m0, s44, 0x2000
	s_add_u32 s42, s42, 0x80080
	s_addc_u32 s43, s43, 0
	global_load_lds_dwordx4 v136, vcc
	ds_read_b128 v[238:241], v155 offset:55296
	ds_read_b128 v[242:245], v155 offset:56320
	s_add_i32 s44, s77, s41
	s_mov_b32 m0, s44
	s_nop 0
	global_load_lds_dwordx4 v132, s[42:43]
	s_add_i32 m0, s44, 0x2000
	s_nop 0
	global_load_lds_dwordx4 v136, s[42:43]
	s_waitcnt vmcnt(8)
	s_waitcnt lgkmcnt(0)
	s_barrier
	s_setprio 1
	s_waitcnt lgkmcnt(0)
	v_mfma_f32_16x16x32_bf16 v[62:65], v[158:161], v[190:193], v[62:65]
	v_mfma_f32_16x16x32_bf16 v[54:57], v[166:169], v[190:193], v[54:57]
	v_mfma_f32_16x16x32_bf16 v[46:49], v[158:161], v[210:213], v[46:49]
	v_mfma_f32_16x16x32_bf16 v[38:41], v[166:169], v[210:213], v[38:41]
	v_mfma_f32_16x16x32_bf16 v[30:33], v[158:161], v[226:229], v[30:33]
	v_mfma_f32_16x16x32_bf16 v[22:25], v[166:169], v[226:229], v[22:25]
	v_mfma_f32_16x16x32_bf16 v[14:17], v[158:161], v[238:241], v[14:17]
	v_mfma_f32_16x16x32_bf16 v[6:9], v[166:169], v[238:241], v[6:9]
	v_mfma_f32_16x16x32_bf16 v[62:65], v[162:165], v[206:209], v[62:65]
	v_mfma_f32_16x16x32_bf16 v[54:57], v[170:173], v[206:209], v[54:57]
	v_mfma_f32_16x16x32_bf16 v[46:49], v[162:165], v[214:217], v[46:49]
	v_mfma_f32_16x16x32_bf16 v[38:41], v[170:173], v[214:217], v[38:41]
	v_mfma_f32_16x16x32_bf16 v[30:33], v[162:165], v[234:237], v[30:33]
	v_mfma_f32_16x16x32_bf16 v[22:25], v[170:173], v[234:237], v[22:25]
	v_mfma_f32_16x16x32_bf16 v[14:17], v[162:165], v[242:245], v[14:17]
	v_mfma_f32_16x16x32_bf16 v[6:9], v[170:173], v[242:245], v[6:9]
	s_setprio 0
	s_setprio 1
	v_mfma_f32_16x16x32_bf16 v[58:61], v[174:177], v[190:193], v[58:61]
	v_mfma_f32_16x16x32_bf16 v[50:53], v[182:185], v[190:193], v[50:53]
	v_mfma_f32_16x16x32_bf16 v[42:45], v[174:177], v[210:213], v[42:45]
	v_mfma_f32_16x16x32_bf16 v[34:37], v[182:185], v[210:213], v[34:37]
	v_mfma_f32_16x16x32_bf16 v[26:29], v[174:177], v[226:229], v[26:29]
	v_mfma_f32_16x16x32_bf16 v[18:21], v[182:185], v[226:229], v[18:21]
	v_mfma_f32_16x16x32_bf16 v[10:13], v[174:177], v[238:241], v[10:13]
	v_mfma_f32_16x16x32_bf16 v[2:5], v[182:185], v[238:241], v[2:5]
	v_mfma_f32_16x16x32_bf16 v[58:61], v[178:181], v[206:209], v[58:61]
	v_mfma_f32_16x16x32_bf16 v[50:53], v[186:189], v[206:209], v[50:53]
	v_mfma_f32_16x16x32_bf16 v[42:45], v[178:181], v[214:217], v[42:45]
	v_mfma_f32_16x16x32_bf16 v[34:37], v[186:189], v[214:217], v[34:37]
	v_mfma_f32_16x16x32_bf16 v[26:29], v[178:181], v[234:237], v[26:29]
	v_mfma_f32_16x16x32_bf16 v[18:21], v[186:189], v[234:237], v[18:21]
	v_mfma_f32_16x16x32_bf16 v[10:13], v[178:181], v[242:245], v[10:13]
	v_mfma_f32_16x16x32_bf16 v[2:5], v[186:189], v[242:245], v[2:5]
	s_setprio 0
	s_barrier
	s_add_i32 s75, s75, 2
	s_add_u32 s20, s20, 0x100
	s_addc_u32 s21, s21, 0
	s_add_u32 s73, s73, 0x100
	s_addc_u32 s74, s74, 0
	s_cmp_gt_u32 s75, 29
	s_cbranch_scc1 .Lpeel_exit_g3
.LBB0_641:
	s_add_u32 s42, s20, 0xfff80080
	s_addc_u32 s43, s21, -1
	s_add_i32 s76, 0, 0x10000
	s_cmp_eq_u32 s75, 28
	s_cselect_b32 s45, s15, s43
	s_cselect_b32 s44, s71, s42
	s_cselect_b32 s43, s13, s74
	s_cselect_b32 s42, s72, s73
	s_add_i32 s79, 0, 0x14000
	s_add_i32 m0, s53, 0xc000
	s_nop 0
	global_load_lds_dwordx4 v138, s[20:21]
	ds_read_b128 v[158:161], v144
	ds_read_b128 v[162:165], v144 offset:1024
	ds_read_b128 v[166:169], v144 offset:2048
	ds_read_b128 v[170:173], v144 offset:3072
	ds_read_b128 v[174:177], v144 offset:16384
	ds_read_b128 v[178:181], v144 offset:17408
	ds_read_b128 v[182:185], v144 offset:18432
	ds_read_b128 v[186:189], v144 offset:19456
	s_add_i32 m0, s53, 0xe000
	s_nop 0
	global_load_lds_dwordx4 v140, s[20:21]
	ds_read_b128 v[190:193], v155
	ds_read_b128 v[206:209], v155 offset:1024
	ds_read_b128 v[210:213], v155 offset:2048
	ds_read_b128 v[214:217], v155 offset:3072
	ds_read_b128 v[226:229], v155 offset:4096
	ds_read_b128 v[234:237], v155 offset:5120
	ds_read_b128 v[238:241], v155 offset:6144
	ds_read_b128 v[242:245], v155 offset:7168
	s_waitcnt vmcnt(8)
	s_waitcnt lgkmcnt(0)
	s_barrier
; #define PG8_STAGE(bufoff, gbase, voff) do { _Pragma("unroll") for (int _i = 0; _i < 2; ++_i) \
;         __builtin_amdgcn_global_load_lds((const unsigned*)((const char*)(gbase) + (voff)[_i]), (PG8_LAS unsigned*)(lds + (bufoff) + ldsw + _i * 8192), 16, 0, 0); } while (0)
; #define PG8_LDA(dst, b, h) do { _Pragma("unroll") for (int m = 0; m < 4; ++m) _Pragma("unroll") for (int k = 0; k < 2; ++k) dst[m][k] = *(const PG8_LAS bf16x8*)(lds + PG8_SA(b, h) + aoff + m * 2048 + k * 1024); } while (0)
; #define PG8_WAIT_V(n) asm volatile("s_waitcnt vmcnt(" #n ")" ::: "memory")
; #define PG8_WAIT_L(n) asm volatile("s_waitcnt lgkmcnt(" #n ")" ::: "memory")
; #define PG8_BAR __builtin_amdgcn_s_barrier()
; template <class Epi, class Sched, bool ALIGN_EPI = false, bool SP2 = false>
; __device__ __forceinline__ void gemm_phase(PG8_LAS unsigned char* lds, const Gemm g, const Sched& S, const Epi& E, const int wave_id) {
;     ...
;         for (int t = 0; t < nt; t += 2) {
;             const bool last = (t == nt - 2);
;             const char* a1 = cA + (size_t)(t + 1) * kstep;
;             const char* a2 = last ? nA : cA + (size_t)(t + 2) * kstep; const char* b2 = last ? nB : cB + (size_t)(t + 2) * kstep;
;             const char* a3 = a2 + kstep; const char* b3 = b2 + kstep;
;             if (last && has_next) S.a_ready(nxt);
;             if constexpr (SP2) {
;             PG8_LDB(B0, 0, 0); PG8_LDB(B1, 0, 1); PG8_SCHED; PG8_LDA(At, 0, 0); PG8_STAGE(PG8_SA(1, 1), a1 + hstep, voffA);
;             PG8_WAIT_V(8); PG8_WAIT_L(0); PG8_BAR; PG8_MMA(0, 0, At, B0); PG8_MMA(0, 1, At, B1); PG8_BAR; PG8_SCHED;
;             PG8_LDA(At, 0, 1); PG8_STAGE(PG8_SB(0, 0), b2, voffB); PG8_STAGE(PG8_SB(0, 1), b2 + hstep, voffB); PG8_STAGE(PG8_SA(0, 0), a2, voffA);
;             PG8_WAIT_V(8); PG8_WAIT_L(0); PG8_BAR; PG8_MMA(1, 0, At, B0); PG8_MMA(1, 1, At, B1); PG8_BAR; PG8_SCHED;
;             PG8_LDB(B0, 1, 0); PG8_LDB(B1, 1, 1); PG8_SCHED; PG8_LDA(At, 1, 0); PG8_STAGE(PG8_SA(0, 1), a2 + hstep, voffA);
;             PG8_WAIT_V(8); PG8_WAIT_L(0); PG8_BAR; PG8_MMA(0, 0, At, B0); PG8_MMA(0, 1, At, B1); PG8_BAR; PG8_SCHED;
;             PG8_LDA(At, 1, 1); PG8_STAGE(PG8_SB(1, 0), b3, voffB); PG8_STAGE(PG8_SB(1, 1), b3 + hstep, voffB); PG8_STAGE(PG8_SA(1, 0), a3, voffA);
;             PG8_WAIT_V(8); PG8_WAIT_L(0); PG8_BAR; PG8_MMA(1, 0, At, B0); PG8_MMA(1, 1, At, B1); PG8_BAR; PG8_SCHED;
	s_setprio 1
	s_waitcnt lgkmcnt(0)
	v_mfma_f32_16x16x32_bf16 v[126:129], v[158:161], v[190:193], v[126:129]
	v_mfma_f32_16x16x32_bf16 v[118:121], v[166:169], v[190:193], v[118:121]
	v_mfma_f32_16x16x32_bf16 v[110:113], v[158:161], v[210:213], v[110:113]
	v_mfma_f32_16x16x32_bf16 v[102:105], v[166:169], v[210:213], v[102:105]
	v_mfma_f32_16x16x32_bf16 v[94:97], v[158:161], v[226:229], v[94:97]
	v_mfma_f32_16x16x32_bf16 v[86:89], v[166:169], v[226:229], v[86:89]
	v_mfma_f32_16x16x32_bf16 v[78:81], v[158:161], v[238:241], v[78:81]
	v_mfma_f32_16x16x32_bf16 v[70:73], v[166:169], v[238:241], v[70:73]
	v_mfma_f32_16x16x32_bf16 v[126:129], v[162:165], v[206:209], v[126:129]
	v_mfma_f32_16x16x32_bf16 v[118:121], v[170:173], v[206:209], v[118:121]
	v_mfma_f32_16x16x32_bf16 v[110:113], v[162:165], v[214:217], v[110:113]
	v_mfma_f32_16x16x32_bf16 v[102:105], v[170:173], v[214:217], v[102:105]
	v_mfma_f32_16x16x32_bf16 v[94:97], v[162:165], v[234:237], v[94:97]
	v_mfma_f32_16x16x32_bf16 v[86:89], v[170:173], v[234:237], v[86:89]
	v_mfma_f32_16x16x32_bf16 v[78:81], v[162:165], v[242:245], v[78:81]
	v_mfma_f32_16x16x32_bf16 v[70:73], v[170:173], v[242:245], v[70:73]
	s_setprio 0
	s_setprio 1
	v_mfma_f32_16x16x32_bf16 v[122:125], v[174:177], v[190:193], v[122:125]
	v_mfma_f32_16x16x32_bf16 v[114:117], v[182:185], v[190:193], v[114:117]
	v_mfma_f32_16x16x32_bf16 v[106:109], v[174:177], v[210:213], v[106:109]
	v_mfma_f32_16x16x32_bf16 v[98:101], v[182:185], v[210:213], v[98:101]
	v_mfma_f32_16x16x32_bf16 v[90:93], v[174:177], v[226:229], v[90:93]
	v_mfma_f32_16x16x32_bf16 v[82:85], v[182:185], v[226:229], v[82:85]
	v_mfma_f32_16x16x32_bf16 v[74:77], v[174:177], v[238:241], v[74:77]
	v_mfma_f32_16x16x32_bf16 v[66:69], v[182:185], v[238:241], v[66:69]
	v_mfma_f32_16x16x32_bf16 v[122:125], v[178:181], v[206:209], v[122:125]
	v_mfma_f32_16x16x32_bf16 v[114:117], v[186:189], v[206:209], v[114:117]
	v_mfma_f32_16x16x32_bf16 v[106:109], v[178:181], v[214:217], v[106:109]
	v_mfma_f32_16x16x32_bf16 v[98:101], v[186:189], v[214:217], v[98:101]
	v_mfma_f32_16x16x32_bf16 v[90:93], v[178:181], v[234:237], v[90:93]
	v_mfma_f32_16x16x32_bf16 v[82:85], v[186:189], v[234:237], v[82:85]
	v_mfma_f32_16x16x32_bf16 v[74:77], v[178:181], v[242:245], v[74:77]
	v_mfma_f32_16x16x32_bf16 v[66:69], v[186:189], v[242:245], v[66:69]
	s_setprio 0
	s_barrier
	s_add_i32 s76, s76, s41
	s_mov_b32 m0, s76
	s_nop 0
	global_load_lds_dwordx4 v132, s[42:43]
	ds_read_b128 v[190:193], v155 offset:16384
	ds_read_b128 v[206:209], v155 offset:17408
	s_add_i32 m0, s76, 0x2000
	s_add_u32 s76, s42, 0x80000
	s_addc_u32 s77, s43, 0
	s_add_i32 s79, s79, s41
	global_load_lds_dwordx4 v136, s[42:43]
	ds_read_b128 v[210:213], v155 offset:18432
	ds_read_b128 v[214:217], v155 offset:19456
	s_mov_b32 m0, s79
	s_nop 0
	global_load_lds_dwordx4 v132, s[76:77]
	ds_read_b128 v[226:229], v155 offset:20480
	ds_read_b128 v[234:237], v155 offset:21504
	s_add_i32 m0, s79, 0x2000
	s_nop 0
	global_load_lds_dwordx4 v136, s[76:77]
	ds_read_b128 v[238:241], v155 offset:22528
	ds_read_b128 v[242:245], v155 offset:23552
	s_mov_b32 m0, s53
	s_nop 0
	global_load_lds_dwordx4 v130, s[44:45]
	s_mov_b32 m0, s56
	s_nop 0
	global_load_lds_dwordx4 v134, s[44:45]
	s_waitcnt vmcnt(8)
	s_waitcnt lgkmcnt(0)
	s_barrier
	s_setprio 1
	s_waitcnt lgkmcnt(0)
	v_mfma_f32_16x16x32_bf16 v[62:65], v[158:161], v[190:193], v[62:65]
	v_mfma_f32_16x16x32_bf16 v[54:57], v[166:169], v[190:193], v[54:57]
	v_mfma_f32_16x16x32_bf16 v[46:49], v[158:161], v[210:213], v[46:49]
	v_mfma_f32_16x16x32_bf16 v[38:41], v[166:169], v[210:213], v[38:41]
	v_mfma_f32_16x16x32_bf16 v[30:33], v[158:161], v[226:229], v[30:33]
	v_mfma_f32_16x16x32_bf16 v[22:25], v[166:169], v[226:229], v[22:25]
	v_mfma_f32_16x16x32_bf16 v[14:17], v[158:161], v[238:241], v[14:17]
	v_mfma_f32_16x16x32_bf16 v[6:9], v[166:169], v[238:241], v[6:9]
	v_mfma_f32_16x16x32_bf16 v[62:65], v[162:165], v[206:209], v[62:65]
	v_mfma_f32_16x16x32_bf16 v[54:57], v[170:173], v[206:209], v[54:57]
	v_mfma_f32_16x16x32_bf16 v[46:49], v[162:165], v[214:217], v[46:49]
	v_mfma_f32_16x16x32_bf16 v[38:41], v[170:173], v[214:217], v[38:41]
	v_mfma_f32_16x16x32_bf16 v[30:33], v[162:165], v[234:237], v[30:33]
	v_mfma_f32_16x16x32_bf16 v[22:25], v[170:173], v[234:237], v[22:25]
	v_mfma_f32_16x16x32_bf16 v[14:17], v[162:165], v[242:245], v[14:17]
	v_mfma_f32_16x16x32_bf16 v[6:9], v[170:173], v[242:245], v[6:9]
	s_setprio 0
	s_setprio 1
	v_mfma_f32_16x16x32_bf16 v[58:61], v[174:177], v[190:193], v[58:61]
	v_mfma_f32_16x16x32_bf16 v[50:53], v[182:185], v[190:193], v[50:53]
	v_mfma_f32_16x16x32_bf16 v[42:45], v[174:177], v[210:213], v[42:45]
	v_mfma_f32_16x16x32_bf16 v[34:37], v[182:185], v[210:213], v[34:37]
	v_mfma_f32_16x16x32_bf16 v[26:29], v[174:177], v[226:229], v[26:29]
	v_mfma_f32_16x16x32_bf16 v[18:21], v[182:185], v[226:229], v[18:21]
	v_mfma_f32_16x16x32_bf16 v[10:13], v[174:177], v[238:241], v[10:13]
	v_mfma_f32_16x16x32_bf16 v[2:5], v[182:185], v[238:241], v[2:5]
	v_mfma_f32_16x16x32_bf16 v[58:61], v[178:181], v[206:209], v[58:61]
	v_mfma_f32_16x16x32_bf16 v[50:53], v[186:189], v[206:209], v[50:53]
	v_mfma_f32_16x16x32_bf16 v[42:45], v[178:181], v[214:217], v[42:45]
	v_mfma_f32_16x16x32_bf16 v[34:37], v[186:189], v[214:217], v[34:37]
	v_mfma_f32_16x16x32_bf16 v[26:29], v[178:181], v[234:237], v[26:29]
	v_mfma_f32_16x16x32_bf16 v[18:21], v[186:189], v[234:237], v[18:21]
	v_mfma_f32_16x16x32_bf16 v[10:13], v[178:181], v[242:245], v[10:13]
	v_mfma_f32_16x16x32_bf16 v[2:5], v[186:189], v[242:245], v[2:5]
	s_setprio 0
	s_barrier
; #define PG8_STAGE(bufoff, gbase, voff) do { _Pragma("unroll") for (int _i = 0; _i < 2; ++_i) \
;         __builtin_amdgcn_global_load_lds((const unsigned*)((const char*)(gbase) + (voff)[_i]), (PG8_LAS unsigned*)(lds + (bufoff) + ldsw + _i * 8192), 16, 0, 0); } while (0)
; #define PG8_LDA(dst, b, h) do { _Pragma("unroll") for (int m = 0; m < 4; ++m) _Pragma("unroll") for (int k = 0; k < 2; ++k) dst[m][k] = *(const PG8_LAS bf16x8*)(lds + PG8_SA(b, h) + aoff + m * 2048 + k * 1024); } while (0)
; #define PG8_WAIT_V(n) asm volatile("s_waitcnt vmcnt(" #n ")" ::: "memory")
; #define PG8_WAIT_L(n) asm volatile("s_waitcnt lgkmcnt(" #n ")" ::: "memory")
; #define PG8_BAR __builtin_amdgcn_s_barrier()
; template <class Epi, class Sched, bool ALIGN_EPI = false, bool SP2 = false>
; __device__ __forceinline__ void gemm_phase(PG8_LAS unsigned char* lds, const Gemm g, const Sched& S, const Epi& E, const int wave_id) {
;     ...
;         for (int t = 0; t < nt; t += 2) {
;             const bool last = (t == nt - 2);
;             const char* a1 = cA + (size_t)(t + 1) * kstep;
;             const char* a2 = last ? nA : cA + (size_t)(t + 2) * kstep; const char* b2 = last ? nB : cB + (size_t)(t + 2) * kstep;
;             const char* a3 = a2 + kstep; const char* b3 = b2 + kstep;
;             if (last && has_next) S.a_ready(nxt);
;             if constexpr (SP2) {
;             PG8_LDB(B0, 0, 0); PG8_LDB(B1, 0, 1); PG8_SCHED; PG8_LDA(At, 0, 0); PG8_STAGE(PG8_SA(1, 1), a1 + hstep, voffA);
;             PG8_WAIT_V(8); PG8_WAIT_L(0); PG8_BAR; PG8_MMA(0, 0, At, B0); PG8_MMA(0, 1, At, B1); PG8_BAR; PG8_SCHED;
;             PG8_LDA(At, 0, 1); PG8_STAGE(PG8_SB(0, 0), b2, voffB); PG8_STAGE(PG8_SB(0, 1), b2 + hstep, voffB); PG8_STAGE(PG8_SA(0, 0), a2, voffA);
;             PG8_WAIT_V(8); PG8_WAIT_L(0); PG8_BAR; PG8_MMA(1, 0, At, B0); PG8_MMA(1, 1, At, B1); PG8_BAR; PG8_SCHED;
;             PG8_LDB(B0, 1, 0); PG8_LDB(B1, 1, 1); PG8_SCHED; PG8_LDA(At, 1, 0); PG8_STAGE(PG8_SA(0, 1), a2 + hstep, voffA);
;             PG8_WAIT_V(8); PG8_WAIT_L(0); PG8_BAR; PG8_MMA(0, 0, At, B0); PG8_MMA(0, 1, At, B1); PG8_BAR; PG8_SCHED;
;             PG8_LDA(At, 1, 1); PG8_STAGE(PG8_SB(1, 0), b3, voffB); PG8_STAGE(PG8_SB(1, 1), b3 + hstep, voffB); PG8_STAGE(PG8_SA(1, 0), a3, voffA);
;             PG8_WAIT_V(8); PG8_WAIT_L(0); PG8_BAR; PG8_MMA(1, 0, At, B0); PG8_MMA(1, 1, At, B1); PG8_BAR; PG8_SCHED;
	s_add_i32 s76, 0, 0x18000
	s_add_i32 s77, 0, 0x1c000
	s_add_u32 s44, s44, 0x80000
	s_addc_u32 s45, s45, 0
	s_mov_b32 m0, s57
	s_nop 0
	global_load_lds_dwordx4 v130, s[44:45]
	ds_read_b128 v[158:161], v144 offset:32768
	ds_read_b128 v[162:165], v144 offset:33792
	ds_read_b128 v[166:169], v144 offset:34816
	ds_read_b128 v[170:173], v144 offset:35840
	ds_read_b128 v[174:177], v144 offset:49152
	ds_read_b128 v[178:181], v144 offset:50176
	ds_read_b128 v[182:185], v144 offset:51200
	ds_read_b128 v[186:189], v144 offset:52224
	s_mov_b32 m0, s64
	s_nop 0
	global_load_lds_dwordx4 v134, s[44:45]
	ds_read_b128 v[190:193], v155 offset:32768
	ds_read_b128 v[206:209], v155 offset:33792
	ds_read_b128 v[210:213], v155 offset:34816
	ds_read_b128 v[214:217], v155 offset:35840
	ds_read_b128 v[226:229], v155 offset:36864
	ds_read_b128 v[234:237], v155 offset:37888
	ds_read_b128 v[238:241], v155 offset:38912
	ds_read_b128 v[242:245], v155 offset:39936
	s_waitcnt vmcnt(8)
	s_waitcnt lgkmcnt(0)
	s_barrier
	s_setprio 1
	s_waitcnt lgkmcnt(0)
	v_mfma_f32_16x16x32_bf16 v[126:129], v[158:161], v[190:193], v[126:129]
	v_mfma_f32_16x16x32_bf16 v[118:121], v[166:169], v[190:193], v[118:121]
	v_mfma_f32_16x16x32_bf16 v[110:113], v[158:161], v[210:213], v[110:113]
	v_mfma_f32_16x16x32_bf16 v[102:105], v[166:169], v[210:213], v[102:105]
	v_mfma_f32_16x16x32_bf16 v[94:97], v[158:161], v[226:229], v[94:97]
	v_mfma_f32_16x16x32_bf16 v[86:89], v[166:169], v[226:229], v[86:89]
	v_mfma_f32_16x16x32_bf16 v[78:81], v[158:161], v[238:241], v[78:81]
	v_mfma_f32_16x16x32_bf16 v[70:73], v[166:169], v[238:241], v[70:73]
	v_mfma_f32_16x16x32_bf16 v[126:129], v[162:165], v[206:209], v[126:129]
	v_mfma_f32_16x16x32_bf16 v[118:121], v[170:173], v[206:209], v[118:121]
	v_mfma_f32_16x16x32_bf16 v[110:113], v[162:165], v[214:217], v[110:113]
	v_mfma_f32_16x16x32_bf16 v[102:105], v[170:173], v[214:217], v[102:105]
	v_mfma_f32_16x16x32_bf16 v[94:97], v[162:165], v[234:237], v[94:97]
	v_mfma_f32_16x16x32_bf16 v[86:89], v[170:173], v[234:237], v[86:89]
	v_mfma_f32_16x16x32_bf16 v[78:81], v[162:165], v[242:245], v[78:81]
	v_mfma_f32_16x16x32_bf16 v[70:73], v[170:173], v[242:245], v[70:73]
	s_setprio 0
	s_setprio 1
	v_mfma_f32_16x16x32_bf16 v[122:125], v[174:177], v[190:193], v[122:125]
	v_mfma_f32_16x16x32_bf16 v[114:117], v[182:185], v[190:193], v[114:117]
	v_mfma_f32_16x16x32_bf16 v[106:109], v[174:177], v[210:213], v[106:109]
	v_mfma_f32_16x16x32_bf16 v[98:101], v[182:185], v[210:213], v[98:101]
	v_mfma_f32_16x16x32_bf16 v[90:93], v[174:177], v[226:229], v[90:93]
	v_mfma_f32_16x16x32_bf16 v[82:85], v[182:185], v[226:229], v[82:85]
	v_mfma_f32_16x16x32_bf16 v[74:77], v[174:177], v[238:241], v[74:77]
	v_mfma_f32_16x16x32_bf16 v[66:69], v[182:185], v[238:241], v[66:69]
	v_mfma_f32_16x16x32_bf16 v[122:125], v[178:181], v[206:209], v[122:125]
	v_mfma_f32_16x16x32_bf16 v[114:117], v[186:189], v[206:209], v[114:117]
	v_mfma_f32_16x16x32_bf16 v[106:109], v[178:181], v[214:217], v[106:109]
	v_mfma_f32_16x16x32_bf16 v[98:101], v[186:189], v[214:217], v[98:101]
	v_mfma_f32_16x16x32_bf16 v[90:93], v[178:181], v[234:237], v[90:93]
	v_mfma_f32_16x16x32_bf16 v[82:85], v[186:189], v[234:237], v[82:85]
	v_mfma_f32_16x16x32_bf16 v[74:77], v[178:181], v[242:245], v[74:77]
	v_mfma_f32_16x16x32_bf16 v[66:69], v[186:189], v[242:245], v[66:69]
	s_setprio 0
	s_barrier
	s_add_u32 vcc_lo, s44, 0xfff80080
	s_addc_u32 vcc_hi, s45, -1
	s_mov_b32 m0, s65
	s_nop 0
	global_load_lds_dwordx4 v130, vcc
	ds_read_b128 v[190:193], v155 offset:49152
	ds_read_b128 v[206:209], v155 offset:50176
	s_mov_b32 m0, s68
	s_add_i32 s44, s76, s41
	global_load_lds_dwordx4 v134, vcc
	ds_read_b128 v[210:213], v155 offset:51200
	ds_read_b128 v[214:217], v155 offset:52224
	s_add_u32 vcc_lo, s42, 0x80
	s_addc_u32 vcc_hi, s43, 0
	s_mov_b32 m0, s44
	s_nop 0
	global_load_lds_dwordx4 v132, vcc
	ds_read_b128 v[226:229], v155 offset:53248
	ds_read_b128 v[234:237], v155 offset:54272
	s_add_i32 m0, s44, 0x2000
	s_add_u32 s42, s42, 0x80080
	s_addc_u32 s43, s43, 0
	global_load_lds_dwordx4 v136, vcc
	ds_read_b128 v[238:241], v155 offset:55296
	ds_read_b128 v[242:245], v155 offset:56320
	s_add_i32 s44, s77, s41
	s_mov_b32 m0, s44
	s_nop 0
	global_load_lds_dwordx4 v132, s[42:43]
	s_add_i32 m0, s44, 0x2000
	s_nop 0
	global_load_lds_dwordx4 v136, s[42:43]
	s_waitcnt vmcnt(8)
	s_waitcnt lgkmcnt(0)
	s_barrier
	s_setprio 1
	s_waitcnt lgkmcnt(0)
	v_mfma_f32_16x16x32_bf16 v[62:65], v[158:161], v[190:193], v[62:65]
	v_mfma_f32_16x16x32_bf16 v[54:57], v[166:169], v[190:193], v[54:57]
	v_mfma_f32_16x16x32_bf16 v[46:49], v[158:161], v[210:213], v[46:49]
	v_mfma_f32_16x16x32_bf16 v[38:41], v[166:169], v[210:213], v[38:41]
	v_mfma_f32_16x16x32_bf16 v[30:33], v[158:161], v[226:229], v[30:33]
	v_mfma_f32_16x16x32_bf16 v[22:25], v[166:169], v[226:229], v[22:25]
	v_mfma_f32_16x16x32_bf16 v[14:17], v[158:161], v[238:241], v[14:17]
	v_mfma_f32_16x16x32_bf16 v[6:9], v[166:169], v[238:241], v[6:9]
	v_mfma_f32_16x16x32_bf16 v[62:65], v[162:165], v[206:209], v[62:65]
	v_mfma_f32_16x16x32_bf16 v[54:57], v[170:173], v[206:209], v[54:57]
	v_mfma_f32_16x16x32_bf16 v[46:49], v[162:165], v[214:217], v[46:49]
	v_mfma_f32_16x16x32_bf16 v[38:41], v[170:173], v[214:217], v[38:41]
	v_mfma_f32_16x16x32_bf16 v[30:33], v[162:165], v[234:237], v[30:33]
	v_mfma_f32_16x16x32_bf16 v[22:25], v[170:173], v[234:237], v[22:25]
	v_mfma_f32_16x16x32_bf16 v[14:17], v[162:165], v[242:245], v[14:17]
	v_mfma_f32_16x16x32_bf16 v[6:9], v[170:173], v[242:245], v[6:9]
	s_setprio 0
	s_setprio 1
	v_mfma_f32_16x16x32_bf16 v[58:61], v[174:177], v[190:193], v[58:61]
	v_mfma_f32_16x16x32_bf16 v[50:53], v[182:185], v[190:193], v[50:53]
	v_mfma_f32_16x16x32_bf16 v[42:45], v[174:177], v[210:213], v[42:45]
	v_mfma_f32_16x16x32_bf16 v[34:37], v[182:185], v[210:213], v[34:37]
	v_mfma_f32_16x16x32_bf16 v[26:29], v[174:177], v[226:229], v[26:29]
	v_mfma_f32_16x16x32_bf16 v[18:21], v[182:185], v[226:229], v[18:21]
	v_mfma_f32_16x16x32_bf16 v[10:13], v[174:177], v[238:241], v[10:13]
	v_mfma_f32_16x16x32_bf16 v[2:5], v[182:185], v[238:241], v[2:5]
	v_mfma_f32_16x16x32_bf16 v[58:61], v[178:181], v[206:209], v[58:61]
	v_mfma_f32_16x16x32_bf16 v[50:53], v[186:189], v[206:209], v[50:53]
	v_mfma_f32_16x16x32_bf16 v[42:45], v[178:181], v[214:217], v[42:45]
	v_mfma_f32_16x16x32_bf16 v[34:37], v[186:189], v[214:217], v[34:37]
	v_mfma_f32_16x16x32_bf16 v[26:29], v[178:181], v[234:237], v[26:29]
	v_mfma_f32_16x16x32_bf16 v[18:21], v[186:189], v[234:237], v[18:21]
	v_mfma_f32_16x16x32_bf16 v[10:13], v[178:181], v[242:245], v[10:13]
	v_mfma_f32_16x16x32_bf16 v[2:5], v[186:189], v[242:245], v[2:5]
	s_setprio 0
	s_barrier
	s_add_i32 s75, s75, 2
	s_add_u32 s20, s20, 0x100
	s_addc_u32 s21, s21, 0
	s_add_u32 s73, s73, 0x100
	s_addc_u32 s74, s74, 0
	s_cmp_gt_u32 s75, 29
	s_cbranch_scc0 .LBB0_641

;     __host__ __device__ bool next(int i, Unit& u) const { const bool ok = StaticOrder::next(i, u); u.lm = 0; u.ln = 0; return ok; }
; #define PG8_BAR __builtin_amdgcn_s_barrier()
; template <class Epi, class Sched, bool ALIGN_EPI = false, bool SP2 = false>
; __device__ __forceinline__ void gemm_phase(PG8_LAS unsigned char* lds, const Gemm g, const Sched& S, const Epi& E, const int wave_id) {
;     ...
;         const bool has_next = S.next(ui + 1, nxt);
;         const char* nA = has_next ? (const char*)g.A + (size_t)nxt.lm * tstep : cA; const char* nB = has_next ? (const char*)g.Bt + (size_t)nxt.ln * tstep : cB;
; #pragma unroll 1
;         for (int t = 0; t < nt; t += 2) {
;             const bool last = (t == nt - 2);
;             const char* a1 = cA + (size_t)(t + 1) * kstep;
;             const char* a2 = last ? nA : cA + (size_t)(t + 2) * kstep; const char* b2 = last ? nB : cB + (size_t)(t + 2) * kstep;
;             const char* a3 = a2 + kstep; const char* b3 = b2 + kstep;
;             if (last && has_next) S.a_ready(nxt);
;             if constexpr (SP2) {
;             PG8_LDB(B0, 0, 0); PG8_LDB(B1, 0, 1); PG8_SCHED; PG8_LDA(At, 0, 0); PG8_STAGE(PG8_SA(1, 1), a1 + hstep, voffA);
;             PG8_WAIT_V(8); PG8_WAIT_L(0); PG8_BAR; PG8_MMA(0, 0, At, B0); PG8_MMA(0, 1, At, B1); PG8_BAR; PG8_SCHED;
;             PG8_LDA(At, 0, 1); PG8_STAGE(PG8_SB(0, 0), b2, voffB); PG8_STAGE(PG8_SB(0, 1), b2 + hstep, voffB); PG8_STAGE(PG8_SA(0, 0), a2, voffA);
;             PG8_WAIT_V(8); PG8_WAIT_L(0); PG8_BAR; PG8_MMA(1, 0, At, B0); PG8_MMA(1, 1, At, B1); PG8_BAR; PG8_SCHED;
;             PG8_LDB(B0, 1, 0); PG8_LDB(B1, 1, 1); PG8_SCHED; PG8_LDA(At, 1, 0); PG8_STAGE(PG8_SA(0, 1), a2 + hstep, voffA);
;             PG8_WAIT_V(8); PG8_WAIT_L(0); PG8_BAR; PG8_MMA(0, 0, At, B0); PG8_MMA(0, 1, At, B1); PG8_BAR; PG8_SCHED;
;             PG8_LDA(At, 1, 1); PG8_STAGE(PG8_SB(1, 0), b3, voffB); PG8_STAGE(PG8_SB(1, 1), b3 + hstep, voffB); PG8_STAGE(PG8_SA(1, 0), a3, voffA);
;             PG8_WAIT_V(8); PG8_WAIT_L(0); PG8_BAR; PG8_MMA(1, 0, At, B0); PG8_MMA(1, 1, At, B1); PG8_BAR; PG8_SCHED;
;     ...
; #pragma unroll
;         for (int a = 0; a < 2; ++a)
; #pragma unroll
;             for (int b = 0; b < 2; ++b)
; #pragma unroll
;                 for (int m = 0; m < 4; ++m)
; #pragma unroll
;                     for (int n = 0; n < 2; ++n) acc[a][b][m][n] = (f32x4){0.f, 0.f, 0.f, 0.f};
.LBB0_758:
	s_add_u32 s74, s20, 0x100
	s_addc_u32 s75, s21, 0
	s_mov_b32 s76, -2
	v_add_u32_e32 v226, 0x10000, v218
	s_add_u32 s20, s18, 0x100
	s_addc_u32 s21, s19, 0
	s_add_i32 s77, 0, 0x10000
	s_cmpk_eq_i32 s76, 0x54
	s_cselect_b32 s43, s15, s21
	s_cselect_b32 s42, s14, s20
	s_cselect_b32 s41, s17, s75
	s_cselect_b32 s40, s16, s74
	s_add_i32 s79, 0, 0x14000
	s_add_i32 m0, s52, 0xc000
	s_nop 0
	global_load_lds_dwordx4 v210, s[18:19]
	ds_read_b128 v[118:121], v226
	ds_read_b128 v[122:125], v226 offset:1024
	ds_read_b128 v[130:133], v226 offset:2048
	ds_read_b128 v[134:137], v226 offset:3072
	ds_read_b128 v[146:149], v226 offset:16384
	ds_read_b128 v[150:153], v226 offset:17408
	ds_read_b128 v[154:157], v226 offset:18432
	ds_read_b128 v[158:161], v226 offset:19456
	s_add_i32 m0, s52, 0xe000
	s_nop 0
	global_load_lds_dwordx4 v212, s[18:19]
	ds_read_b128 v[162:165], v222
	ds_read_b128 v[166:169], v222 offset:1024
	ds_read_b128 v[170:173], v222 offset:2048
	ds_read_b128 v[174:177], v222 offset:3072
	ds_read_b128 v[178:181], v222 offset:4096
	ds_read_b128 v[182:185], v222 offset:5120
	ds_read_b128 v[186:189], v222 offset:6144
	ds_read_b128 v[214:217], v222 offset:7168
	s_waitcnt vmcnt(8)
	s_waitcnt lgkmcnt(0)
	s_barrier
	s_setprio 1
	s_waitcnt lgkmcnt(0)
	v_mfma_f32_16x16x32_bf16 v[142:145], v[118:121], v[162:165], 0
	v_mfma_f32_16x16x32_bf16 v[138:141], v[130:133], v[162:165], 0
	v_mfma_f32_16x16x32_bf16 v[110:113], v[118:121], v[170:173], 0
	v_mfma_f32_16x16x32_bf16 v[106:109], v[130:133], v[170:173], 0
	v_mfma_f32_16x16x32_bf16 v[94:97], v[118:121], v[178:181], 0
	v_mfma_f32_16x16x32_bf16 v[90:93], v[130:133], v[178:181], 0
	v_mfma_f32_16x16x32_bf16 v[78:81], v[118:121], v[186:189], 0
	v_mfma_f32_16x16x32_bf16 v[74:77], v[130:133], v[186:189], 0
	v_mfma_f32_16x16x32_bf16 v[142:145], v[122:125], v[166:169], v[142:145]
	v_mfma_f32_16x16x32_bf16 v[138:141], v[134:137], v[166:169], v[138:141]
	v_mfma_f32_16x16x32_bf16 v[110:113], v[122:125], v[174:177], v[110:113]
	v_mfma_f32_16x16x32_bf16 v[106:109], v[134:137], v[174:177], v[106:109]
	v_mfma_f32_16x16x32_bf16 v[94:97], v[122:125], v[182:185], v[94:97]
	v_mfma_f32_16x16x32_bf16 v[90:93], v[134:137], v[182:185], v[90:93]
	v_mfma_f32_16x16x32_bf16 v[78:81], v[122:125], v[214:217], v[78:81]
	v_mfma_f32_16x16x32_bf16 v[74:77], v[134:137], v[214:217], v[74:77]
	s_setprio 0
	s_setprio 1
	v_mfma_f32_16x16x32_bf16 v[126:129], v[146:149], v[162:165], 0
	v_mfma_f32_16x16x32_bf16 v[114:117], v[154:157], v[162:165], 0
	v_mfma_f32_16x16x32_bf16 v[102:105], v[146:149], v[170:173], 0
	v_mfma_f32_16x16x32_bf16 v[98:101], v[154:157], v[170:173], 0
	v_mfma_f32_16x16x32_bf16 v[86:89], v[146:149], v[178:181], 0
	v_mfma_f32_16x16x32_bf16 v[82:85], v[154:157], v[178:181], 0
	v_mfma_f32_16x16x32_bf16 v[70:73], v[146:149], v[186:189], 0
	v_mfma_f32_16x16x32_bf16 v[66:69], v[154:157], v[186:189], 0
	v_mfma_f32_16x16x32_bf16 v[126:129], v[150:153], v[166:169], v[126:129]
	v_mfma_f32_16x16x32_bf16 v[114:117], v[158:161], v[166:169], v[114:117]
	v_mfma_f32_16x16x32_bf16 v[102:105], v[150:153], v[174:177], v[102:105]
	v_mfma_f32_16x16x32_bf16 v[98:101], v[158:161], v[174:177], v[98:101]
	v_mfma_f32_16x16x32_bf16 v[86:89], v[150:153], v[182:185], v[86:89]
	v_mfma_f32_16x16x32_bf16 v[82:85], v[158:161], v[182:185], v[82:85]
	v_mfma_f32_16x16x32_bf16 v[70:73], v[150:153], v[214:217], v[70:73]
	v_mfma_f32_16x16x32_bf16 v[66:69], v[158:161], v[214:217], v[66:69]
	s_setprio 0
	s_barrier
	s_add_i32 s18, s77, s49
	s_mov_b32 m0, s18
	s_nop 0
	global_load_lds_dwordx4 v192, s[40:41]
	ds_read_b128 v[162:165], v222 offset:16384
	ds_read_b128 v[166:169], v222 offset:17408
	s_add_i32 m0, s18, 0x2000
	s_add_u32 s18, s40, 0x160000
	s_addc_u32 s19, s41, 0
	s_add_i32 s77, s79, s49
	global_load_lds_dwordx4 v208, s[40:41]
	ds_read_b128 v[170:173], v222 offset:18432
	ds_read_b128 v[174:177], v222 offset:19456
	s_mov_b32 m0, s77
	s_nop 0
	global_load_lds_dwordx4 v192, s[18:19]
	ds_read_b128 v[178:181], v222 offset:20480
	ds_read_b128 v[182:185], v222 offset:21504
	s_add_i32 m0, s77, 0x2000
	s_nop 0
	global_load_lds_dwordx4 v208, s[18:19]
	ds_read_b128 v[186:189], v222 offset:22528
	ds_read_b128 v[214:217], v222 offset:23552
	s_mov_b32 m0, s52
	s_nop 0
	global_load_lds_dwordx4 v190, s[42:43]
	s_mov_b32 m0, s53
	s_nop 0
	global_load_lds_dwordx4 v206, s[42:43]
	s_waitcnt vmcnt(8)
	s_waitcnt lgkmcnt(0)
	s_barrier
	s_setprio 1
	s_waitcnt lgkmcnt(0)
	v_mfma_f32_16x16x32_bf16 v[62:65], v[118:121], v[162:165], 0
	v_mfma_f32_16x16x32_bf16 v[58:61], v[130:133], v[162:165], 0
	v_mfma_f32_16x16x32_bf16 v[46:49], v[118:121], v[170:173], 0
	v_mfma_f32_16x16x32_bf16 v[42:45], v[130:133], v[170:173], 0
	v_mfma_f32_16x16x32_bf16 v[30:33], v[118:121], v[178:181], 0
	v_mfma_f32_16x16x32_bf16 v[26:29], v[130:133], v[178:181], 0
	v_mfma_f32_16x16x32_bf16 v[14:17], v[118:121], v[186:189], 0
	v_mfma_f32_16x16x32_bf16 v[10:13], v[130:133], v[186:189], 0
	v_mfma_f32_16x16x32_bf16 v[62:65], v[122:125], v[166:169], v[62:65]
	v_mfma_f32_16x16x32_bf16 v[58:61], v[134:137], v[166:169], v[58:61]
	v_mfma_f32_16x16x32_bf16 v[46:49], v[122:125], v[174:177], v[46:49]
	v_mfma_f32_16x16x32_bf16 v[42:45], v[134:137], v[174:177], v[42:45]
	v_mfma_f32_16x16x32_bf16 v[30:33], v[122:125], v[182:185], v[30:33]
	v_mfma_f32_16x16x32_bf16 v[26:29], v[134:137], v[182:185], v[26:29]
	v_mfma_f32_16x16x32_bf16 v[14:17], v[122:125], v[214:217], v[14:17]
	v_mfma_f32_16x16x32_bf16 v[10:13], v[134:137], v[214:217], v[10:13]
	s_setprio 0
	s_setprio 1
	v_mfma_f32_16x16x32_bf16 v[54:57], v[146:149], v[162:165], 0
	v_mfma_f32_16x16x32_bf16 v[50:53], v[154:157], v[162:165], 0
	v_mfma_f32_16x16x32_bf16 v[38:41], v[146:149], v[170:173], 0
	v_mfma_f32_16x16x32_bf16 v[34:37], v[154:157], v[170:173], 0
	v_mfma_f32_16x16x32_bf16 v[22:25], v[146:149], v[178:181], 0
	v_mfma_f32_16x16x32_bf16 v[18:21], v[154:157], v[178:181], 0
	v_mfma_f32_16x16x32_bf16 v[6:9], v[146:149], v[186:189], 0
	v_mfma_f32_16x16x32_bf16 v[2:5], v[154:157], v[186:189], 0
	v_mfma_f32_16x16x32_bf16 v[54:57], v[150:153], v[166:169], v[54:57]
	v_mfma_f32_16x16x32_bf16 v[50:53], v[158:161], v[166:169], v[50:53]
	v_mfma_f32_16x16x32_bf16 v[38:41], v[150:153], v[174:177], v[38:41]
	v_mfma_f32_16x16x32_bf16 v[34:37], v[158:161], v[174:177], v[34:37]
	v_mfma_f32_16x16x32_bf16 v[22:25], v[150:153], v[182:185], v[22:25]
	v_mfma_f32_16x16x32_bf16 v[18:21], v[158:161], v[182:185], v[18:21]
	v_mfma_f32_16x16x32_bf16 v[6:9], v[150:153], v[214:217], v[6:9]
	v_mfma_f32_16x16x32_bf16 v[2:5], v[158:161], v[214:217], v[2:5]
	s_setprio 0
	s_barrier
; #define PG8_STAGE(bufoff, gbase, voff) do { _Pragma("unroll") for (int _i = 0; _i < 2; ++_i) \
;         __builtin_amdgcn_global_load_lds((const unsigned*)((const char*)(gbase) + (voff)[_i]), (PG8_LAS unsigned*)(lds + (bufoff) + ldsw + _i * 8192), 16, 0, 0); } while (0)
; #define PG8_LDA(dst, b, h) do { _Pragma("unroll") for (int m = 0; m < 4; ++m) _Pragma("unroll") for (int k = 0; k < 2; ++k) dst[m][k] = *(const PG8_LAS bf16x8*)(lds + PG8_SA(b, h) + aoff + m * 2048 + k * 1024); } while (0)
; #define PG8_WAIT_V(n) asm volatile("s_waitcnt vmcnt(" #n ")" ::: "memory")
; #define PG8_WAIT_L(n) asm volatile("s_waitcnt lgkmcnt(" #n ")" ::: "memory")
; #define PG8_BAR __builtin_amdgcn_s_barrier()
; template <class Epi, class Sched, bool ALIGN_EPI = false, bool SP2 = false>
; __device__ __forceinline__ void gemm_phase(PG8_LAS unsigned char* lds, const Gemm g, const Sched& S, const Epi& E, const int wave_id) {
;     ...
;         for (int t = 0; t < nt; t += 2) {
;             const bool last = (t == nt - 2);
;             const char* a1 = cA + (size_t)(t + 1) * kstep;
;             const char* a2 = last ? nA : cA + (size_t)(t + 2) * kstep; const char* b2 = last ? nB : cB + (size_t)(t + 2) * kstep;
;             const char* a3 = a2 + kstep; const char* b3 = b2 + kstep;
;             if (last && has_next) S.a_ready(nxt);
;             if constexpr (SP2) {
;             PG8_LDB(B0, 0, 0); PG8_LDB(B1, 0, 1); PG8_SCHED; PG8_LDA(At, 0, 0); PG8_STAGE(PG8_SA(1, 1), a1 + hstep, voffA);
;             PG8_WAIT_V(8); PG8_WAIT_L(0); PG8_BAR; PG8_MMA(0, 0, At, B0); PG8_MMA(0, 1, At, B1); PG8_BAR; PG8_SCHED;
;             PG8_LDA(At, 0, 1); PG8_STAGE(PG8_SB(0, 0), b2, voffB); PG8_STAGE(PG8_SB(0, 1), b2 + hstep, voffB); PG8_STAGE(PG8_SA(0, 0), a2, voffA);
;             PG8_WAIT_V(8); PG8_WAIT_L(0); PG8_BAR; PG8_MMA(1, 0, At, B0); PG8_MMA(1, 1, At, B1); PG8_BAR; PG8_SCHED;
;             PG8_LDB(B0, 1, 0); PG8_LDB(B1, 1, 1); PG8_SCHED; PG8_LDA(At, 1, 0); PG8_STAGE(PG8_SA(0, 1), a2 + hstep, voffA);
;             PG8_WAIT_V(8); PG8_WAIT_L(0); PG8_BAR; PG8_MMA(0, 0, At, B0); PG8_MMA(0, 1, At, B1); PG8_BAR; PG8_SCHED;
;             PG8_LDA(At, 1, 1); PG8_STAGE(PG8_SB(1, 0), b3, voffB); PG8_STAGE(PG8_SB(1, 1), b3 + hstep, voffB); PG8_STAGE(PG8_SA(1, 0), a3, voffA);
;             PG8_WAIT_V(8); PG8_WAIT_L(0); PG8_BAR; PG8_MMA(1, 0, At, B0); PG8_MMA(1, 1, At, B1); PG8_BAR; PG8_SCHED;
	s_add_i32 s77, 0, 0x18000
	s_add_i32 s79, 0, 0x1c000
	s_add_u32 s18, s42, 0x160000
	s_addc_u32 s19, s43, 0
	s_mov_b32 m0, s56
	s_nop 0
	global_load_lds_dwordx4 v190, s[18:19]
	ds_read_b128 v[118:121], v226 offset:32768
	ds_read_b128 v[122:125], v226 offset:33792
	ds_read_b128 v[130:133], v226 offset:34816
	ds_read_b128 v[134:137], v226 offset:35840
	ds_read_b128 v[146:149], v226 offset:49152
	ds_read_b128 v[150:153], v226 offset:50176
	ds_read_b128 v[154:157], v226 offset:51200
	ds_read_b128 v[158:161], v226 offset:52224
	s_mov_b32 m0, s57
	s_nop 0
	global_load_lds_dwordx4 v206, s[18:19]
	ds_read_b128 v[162:165], v222 offset:32768
	ds_read_b128 v[166:169], v222 offset:33792
	ds_read_b128 v[170:173], v222 offset:34816
	ds_read_b128 v[174:177], v222 offset:35840
	ds_read_b128 v[178:181], v222 offset:36864
	ds_read_b128 v[182:185], v222 offset:37888
	ds_read_b128 v[186:189], v222 offset:38912
	ds_read_b128 v[214:217], v222 offset:39936
	s_waitcnt vmcnt(8)
	s_waitcnt lgkmcnt(0)
	s_barrier
	s_setprio 1
	s_waitcnt lgkmcnt(0)
	v_mfma_f32_16x16x32_bf16 v[142:145], v[118:121], v[162:165], v[142:145]
	v_mfma_f32_16x16x32_bf16 v[138:141], v[130:133], v[162:165], v[138:141]
	v_mfma_f32_16x16x32_bf16 v[110:113], v[118:121], v[170:173], v[110:113]
	v_mfma_f32_16x16x32_bf16 v[106:109], v[130:133], v[170:173], v[106:109]
	v_mfma_f32_16x16x32_bf16 v[94:97], v[118:121], v[178:181], v[94:97]
	v_mfma_f32_16x16x32_bf16 v[90:93], v[130:133], v[178:181], v[90:93]
	v_mfma_f32_16x16x32_bf16 v[78:81], v[118:121], v[186:189], v[78:81]
	v_mfma_f32_16x16x32_bf16 v[74:77], v[130:133], v[186:189], v[74:77]
	v_mfma_f32_16x16x32_bf16 v[142:145], v[122:125], v[166:169], v[142:145]
	v_mfma_f32_16x16x32_bf16 v[138:141], v[134:137], v[166:169], v[138:141]
	v_mfma_f32_16x16x32_bf16 v[110:113], v[122:125], v[174:177], v[110:113]
	v_mfma_f32_16x16x32_bf16 v[106:109], v[134:137], v[174:177], v[106:109]
	v_mfma_f32_16x16x32_bf16 v[94:97], v[122:125], v[182:185], v[94:97]
	v_mfma_f32_16x16x32_bf16 v[90:93], v[134:137], v[182:185], v[90:93]
	v_mfma_f32_16x16x32_bf16 v[78:81], v[122:125], v[214:217], v[78:81]
	v_mfma_f32_16x16x32_bf16 v[74:77], v[134:137], v[214:217], v[74:77]
	s_setprio 0
	s_setprio 1
	v_mfma_f32_16x16x32_bf16 v[126:129], v[146:149], v[162:165], v[126:129]
	v_mfma_f32_16x16x32_bf16 v[114:117], v[154:157], v[162:165], v[114:117]
	v_mfma_f32_16x16x32_bf16 v[102:105], v[146:149], v[170:173], v[102:105]
	v_mfma_f32_16x16x32_bf16 v[98:101], v[154:157], v[170:173], v[98:101]
	v_mfma_f32_16x16x32_bf16 v[86:89], v[146:149], v[178:181], v[86:89]
	v_mfma_f32_16x16x32_bf16 v[82:85], v[154:157], v[178:181], v[82:85]
	v_mfma_f32_16x16x32_bf16 v[70:73], v[146:149], v[186:189], v[70:73]
	v_mfma_f32_16x16x32_bf16 v[66:69], v[154:157], v[186:189], v[66:69]
	v_mfma_f32_16x16x32_bf16 v[126:129], v[150:153], v[166:169], v[126:129]
	v_mfma_f32_16x16x32_bf16 v[114:117], v[158:161], v[166:169], v[114:117]
	v_mfma_f32_16x16x32_bf16 v[102:105], v[150:153], v[174:177], v[102:105]
	v_mfma_f32_16x16x32_bf16 v[98:101], v[158:161], v[174:177], v[98:101]
	v_mfma_f32_16x16x32_bf16 v[86:89], v[150:153], v[182:185], v[86:89]
	v_mfma_f32_16x16x32_bf16 v[82:85], v[158:161], v[182:185], v[82:85]
	v_mfma_f32_16x16x32_bf16 v[70:73], v[150:153], v[214:217], v[70:73]
	v_mfma_f32_16x16x32_bf16 v[66:69], v[158:161], v[214:217], v[66:69]
	s_setprio 0
	s_barrier
	s_add_u32 vcc_lo, s42, 0x80
	s_addc_u32 vcc_hi, s43, 0
	s_mov_b32 m0, s68
	s_nop 0
	global_load_lds_dwordx4 v190, vcc
	ds_read_b128 v[162:165], v222 offset:49152
	ds_read_b128 v[166:169], v222 offset:50176
	s_mov_b32 m0, s69
	s_add_i32 s18, s77, s49
	global_load_lds_dwordx4 v206, vcc
	ds_read_b128 v[170:173], v222 offset:51200
	ds_read_b128 v[174:177], v222 offset:52224
	s_add_u32 vcc_lo, s40, 0x80
	s_addc_u32 vcc_hi, s41, 0
	s_mov_b32 m0, s18
	s_nop 0
	global_load_lds_dwordx4 v192, vcc
	ds_read_b128 v[178:181], v222 offset:53248
	ds_read_b128 v[182:185], v222 offset:54272
	s_add_i32 m0, s18, 0x2000
	s_add_u32 s18, s40, 0x160080
	s_addc_u32 s19, s41, 0
	global_load_lds_dwordx4 v208, vcc
	ds_read_b128 v[186:189], v222 offset:55296
	ds_read_b128 v[214:217], v222 offset:56320
	s_add_i32 s40, s79, s49
	s_mov_b32 m0, s40
	s_nop 0
	global_load_lds_dwordx4 v192, s[18:19]
	s_add_i32 m0, s40, 0x2000
	s_nop 0
	global_load_lds_dwordx4 v208, s[18:19]
	s_waitcnt vmcnt(8)
	s_waitcnt lgkmcnt(0)
	s_barrier
	s_setprio 1
	s_waitcnt lgkmcnt(0)
	v_mfma_f32_16x16x32_bf16 v[62:65], v[118:121], v[162:165], v[62:65]
	v_mfma_f32_16x16x32_bf16 v[58:61], v[130:133], v[162:165], v[58:61]
	v_mfma_f32_16x16x32_bf16 v[46:49], v[118:121], v[170:173], v[46:49]
	v_mfma_f32_16x16x32_bf16 v[42:45], v[130:133], v[170:173], v[42:45]
	v_mfma_f32_16x16x32_bf16 v[30:33], v[118:121], v[178:181], v[30:33]
	v_mfma_f32_16x16x32_bf16 v[26:29], v[130:133], v[178:181], v[26:29]
	v_mfma_f32_16x16x32_bf16 v[14:17], v[118:121], v[186:189], v[14:17]
	v_mfma_f32_16x16x32_bf16 v[10:13], v[130:133], v[186:189], v[10:13]
	v_mfma_f32_16x16x32_bf16 v[62:65], v[122:125], v[166:169], v[62:65]
	v_mfma_f32_16x16x32_bf16 v[58:61], v[134:137], v[166:169], v[58:61]
	v_mfma_f32_16x16x32_bf16 v[46:49], v[122:125], v[174:177], v[46:49]
	v_mfma_f32_16x16x32_bf16 v[42:45], v[134:137], v[174:177], v[42:45]
	v_mfma_f32_16x16x32_bf16 v[30:33], v[122:125], v[182:185], v[30:33]
	v_mfma_f32_16x16x32_bf16 v[26:29], v[134:137], v[182:185], v[26:29]
	v_mfma_f32_16x16x32_bf16 v[14:17], v[122:125], v[214:217], v[14:17]
	v_mfma_f32_16x16x32_bf16 v[10:13], v[134:137], v[214:217], v[10:13]
	s_setprio 0
	s_setprio 1
	v_mfma_f32_16x16x32_bf16 v[54:57], v[146:149], v[162:165], v[54:57]
	v_mfma_f32_16x16x32_bf16 v[50:53], v[154:157], v[162:165], v[50:53]
	v_mfma_f32_16x16x32_bf16 v[38:41], v[146:149], v[170:173], v[38:41]
	v_mfma_f32_16x16x32_bf16 v[34:37], v[154:157], v[170:173], v[34:37]
	v_mfma_f32_16x16x32_bf16 v[22:25], v[146:149], v[178:181], v[22:25]
	v_mfma_f32_16x16x32_bf16 v[18:21], v[154:157], v[178:181], v[18:21]
	v_mfma_f32_16x16x32_bf16 v[6:9], v[146:149], v[186:189], v[6:9]
	v_mfma_f32_16x16x32_bf16 v[2:5], v[154:157], v[186:189], v[2:5]
	v_mfma_f32_16x16x32_bf16 v[54:57], v[150:153], v[166:169], v[54:57]
	v_mfma_f32_16x16x32_bf16 v[50:53], v[158:161], v[166:169], v[50:53]
	v_mfma_f32_16x16x32_bf16 v[38:41], v[150:153], v[174:177], v[38:41]
	v_mfma_f32_16x16x32_bf16 v[34:37], v[158:161], v[174:177], v[34:37]
	v_mfma_f32_16x16x32_bf16 v[22:25], v[150:153], v[182:185], v[22:25]
	v_mfma_f32_16x16x32_bf16 v[18:21], v[158:161], v[182:185], v[18:21]
	v_mfma_f32_16x16x32_bf16 v[6:9], v[150:153], v[214:217], v[6:9]
	v_mfma_f32_16x16x32_bf16 v[2:5], v[158:161], v[214:217], v[2:5]
	s_setprio 0
	s_barrier
	s_add_i32 s76, s76, 2
	s_add_u32 s74, s74, 0x100
	s_addc_u32 s75, s75, 0
	s_cmpk_gt_u32 s76, 0x55
	s_mov_b64 s[18:19], s[20:21]
	s_cbranch_scc1 .Lpeel_exit_g4
; #define PG8_STAGE(bufoff, gbase, voff) do { _Pragma("unroll") for (int _i = 0; _i < 2; ++_i) \
;         __builtin_amdgcn_global_load_lds((const unsigned*)((const char*)(gbase) + (voff)[_i]), (PG8_LAS unsigned*)(lds + (bufoff) + ldsw + _i * 8192), 16, 0, 0); } while (0)
; #define PG8_LDA(dst, b, h) do { _Pragma("unroll") for (int m = 0; m < 4; ++m) _Pragma("unroll") for (int k = 0; k < 2; ++k) dst[m][k] = *(const PG8_LAS bf16x8*)(lds + PG8_SA(b, h) + aoff + m * 2048 + k * 1024); } while (0)
; #define PG8_WAIT_V(n) asm volatile("s_waitcnt vmcnt(" #n ")" ::: "memory")
; #define PG8_WAIT_L(n) asm volatile("s_waitcnt lgkmcnt(" #n ")" ::: "memory")
; #define PG8_BAR __builtin_amdgcn_s_barrier()
; template <class Epi, class Sched, bool ALIGN_EPI = false, bool SP2 = false>
; __device__ __forceinline__ void gemm_phase(PG8_LAS unsigned char* lds, const Gemm g, const Sched& S, const Epi& E, const int wave_id) {
;     ...
;         for (int t = 0; t < nt; t += 2) {
;             const bool last = (t == nt - 2);
;             const char* a1 = cA + (size_t)(t + 1) * kstep;
;             const char* a2 = last ? nA : cA + (size_t)(t + 2) * kstep; const char* b2 = last ? nB : cB + (size_t)(t + 2) * kstep;
;             const char* a3 = a2 + kstep; const char* b3 = b2 + kstep;
;             if (last && has_next) S.a_ready(nxt);
;             if constexpr (SP2) {
;             PG8_LDB(B0, 0, 0); PG8_LDB(B1, 0, 1); PG8_SCHED; PG8_LDA(At, 0, 0); PG8_STAGE(PG8_SA(1, 1), a1 + hstep, voffA);
;             PG8_WAIT_V(8); PG8_WAIT_L(0); PG8_BAR; PG8_MMA(0, 0, At, B0); PG8_MMA(0, 1, At, B1); PG8_BAR; PG8_SCHED;
;             PG8_LDA(At, 0, 1); PG8_STAGE(PG8_SB(0, 0), b2, voffB); PG8_STAGE(PG8_SB(0, 1), b2 + hstep, voffB); PG8_STAGE(PG8_SA(0, 0), a2, voffA);
;             PG8_WAIT_V(8); PG8_WAIT_L(0); PG8_BAR; PG8_MMA(1, 0, At, B0); PG8_MMA(1, 1, At, B1); PG8_BAR; PG8_SCHED;
;             PG8_LDB(B0, 1, 0); PG8_LDB(B1, 1, 1); PG8_SCHED; PG8_LDA(At, 1, 0); PG8_STAGE(PG8_SA(0, 1), a2 + hstep, voffA);
;             PG8_WAIT_V(8); PG8_WAIT_L(0); PG8_BAR; PG8_MMA(0, 0, At, B0); PG8_MMA(0, 1, At, B1); PG8_BAR; PG8_SCHED;
;             PG8_LDA(At, 1, 1); PG8_STAGE(PG8_SB(1, 0), b3, voffB); PG8_STAGE(PG8_SB(1, 1), b3 + hstep, voffB); PG8_STAGE(PG8_SA(1, 0), a3, voffA);
;             PG8_WAIT_V(8); PG8_WAIT_L(0); PG8_BAR; PG8_MMA(1, 0, At, B0); PG8_MMA(1, 1, At, B1); PG8_BAR; PG8_SCHED;
.LBB0_759:
	s_add_u32 s20, s18, 0x100
	s_addc_u32 s21, s19, 0
	s_add_i32 s77, 0, 0x10000
	s_cmpk_eq_i32 s76, 0x54
	s_cselect_b32 s43, s15, s21
	s_cselect_b32 s42, s14, s20
	s_cselect_b32 s41, s17, s75
	s_cselect_b32 s40, s16, s74
	s_add_i32 s79, 0, 0x14000
	s_add_i32 m0, s52, 0xc000
	s_nop 0
	global_load_lds_dwordx4 v210, s[18:19]
	ds_read_b128 v[118:121], v226
	ds_read_b128 v[122:125], v226 offset:1024
	ds_read_b128 v[130:133], v226 offset:2048
	ds_read_b128 v[134:137], v226 offset:3072
	ds_read_b128 v[146:149], v226 offset:16384
	ds_read_b128 v[150:153], v226 offset:17408
	ds_read_b128 v[154:157], v226 offset:18432
	ds_read_b128 v[158:161], v226 offset:19456
	s_add_i32 m0, s52, 0xe000
	s_nop 0
	global_load_lds_dwordx4 v212, s[18:19]
	ds_read_b128 v[162:165], v222
	ds_read_b128 v[166:169], v222 offset:1024
	ds_read_b128 v[170:173], v222 offset:2048
	ds_read_b128 v[174:177], v222 offset:3072
	ds_read_b128 v[178:181], v222 offset:4096
	ds_read_b128 v[182:185], v222 offset:5120
	ds_read_b128 v[186:189], v222 offset:6144
	ds_read_b128 v[214:217], v222 offset:7168
	s_waitcnt vmcnt(8)
	s_waitcnt lgkmcnt(0)
	s_barrier
	s_setprio 1
	s_waitcnt lgkmcnt(0)
	v_mfma_f32_16x16x32_bf16 v[142:145], v[118:121], v[162:165], v[142:145]
	v_mfma_f32_16x16x32_bf16 v[138:141], v[130:133], v[162:165], v[138:141]
	v_mfma_f32_16x16x32_bf16 v[110:113], v[118:121], v[170:173], v[110:113]
	v_mfma_f32_16x16x32_bf16 v[106:109], v[130:133], v[170:173], v[106:109]
	v_mfma_f32_16x16x32_bf16 v[94:97], v[118:121], v[178:181], v[94:97]
	v_mfma_f32_16x16x32_bf16 v[90:93], v[130:133], v[178:181], v[90:93]
	v_mfma_f32_16x16x32_bf16 v[78:81], v[118:121], v[186:189], v[78:81]
	v_mfma_f32_16x16x32_bf16 v[74:77], v[130:133], v[186:189], v[74:77]
	v_mfma_f32_16x16x32_bf16 v[142:145], v[122:125], v[166:169], v[142:145]
	v_mfma_f32_16x16x32_bf16 v[138:141], v[134:137], v[166:169], v[138:141]
	v_mfma_f32_16x16x32_bf16 v[110:113], v[122:125], v[174:177], v[110:113]
	v_mfma_f32_16x16x32_bf16 v[106:109], v[134:137], v[174:177], v[106:109]
	v_mfma_f32_16x16x32_bf16 v[94:97], v[122:125], v[182:185], v[94:97]
	v_mfma_f32_16x16x32_bf16 v[90:93], v[134:137], v[182:185], v[90:93]
	v_mfma_f32_16x16x32_bf16 v[78:81], v[122:125], v[214:217], v[78:81]
	v_mfma_f32_16x16x32_bf16 v[74:77], v[134:137], v[214:217], v[74:77]
	s_setprio 0
	s_setprio 1
	v_mfma_f32_16x16x32_bf16 v[126:129], v[146:149], v[162:165], v[126:129]
	v_mfma_f32_16x16x32_bf16 v[114:117], v[154:157], v[162:165], v[114:117]
	v_mfma_f32_16x16x32_bf16 v[102:105], v[146:149], v[170:173], v[102:105]
	v_mfma_f32_16x16x32_bf16 v[98:101], v[154:157], v[170:173], v[98:101]
	v_mfma_f32_16x16x32_bf16 v[86:89], v[146:149], v[178:181], v[86:89]
	v_mfma_f32_16x16x32_bf16 v[82:85], v[154:157], v[178:181], v[82:85]
	v_mfma_f32_16x16x32_bf16 v[70:73], v[146:149], v[186:189], v[70:73]
	v_mfma_f32_16x16x32_bf16 v[66:69], v[154:157], v[186:189], v[66:69]
	v_mfma_f32_16x16x32_bf16 v[126:129], v[150:153], v[166:169], v[126:129]
	v_mfma_f32_16x16x32_bf16 v[114:117], v[158:161], v[166:169], v[114:117]
	v_mfma_f32_16x16x32_bf16 v[102:105], v[150:153], v[174:177], v[102:105]
	v_mfma_f32_16x16x32_bf16 v[98:101], v[158:161], v[174:177], v[98:101]
	v_mfma_f32_16x16x32_bf16 v[86:89], v[150:153], v[182:185], v[86:89]
	v_mfma_f32_16x16x32_bf16 v[82:85], v[158:161], v[182:185], v[82:85]
	v_mfma_f32_16x16x32_bf16 v[70:73], v[150:153], v[214:217], v[70:73]
	v_mfma_f32_16x16x32_bf16 v[66:69], v[158:161], v[214:217], v[66:69]
	s_setprio 0
	s_barrier
	s_add_i32 s18, s77, s49
	s_mov_b32 m0, s18
	s_nop 0
	global_load_lds_dwordx4 v192, s[40:41]
	ds_read_b128 v[162:165], v222 offset:16384
	ds_read_b128 v[166:169], v222 offset:17408
	s_add_i32 m0, s18, 0x2000
	s_add_u32 s18, s40, 0x160000
	s_addc_u32 s19, s41, 0
	s_add_i32 s77, s79, s49
	global_load_lds_dwordx4 v208, s[40:41]
	ds_read_b128 v[170:173], v222 offset:18432
	ds_read_b128 v[174:177], v222 offset:19456
	s_mov_b32 m0, s77
	s_nop 0
	global_load_lds_dwordx4 v192, s[18:19]
	ds_read_b128 v[178:181], v222 offset:20480
	ds_read_b128 v[182:185], v222 offset:21504
	s_add_i32 m0, s77, 0x2000
	s_nop 0
	global_load_lds_dwordx4 v208, s[18:19]
	ds_read_b128 v[186:189], v222 offset:22528
	ds_read_b128 v[214:217], v222 offset:23552
	s_mov_b32 m0, s52
	s_nop 0
	global_load_lds_dwordx4 v190, s[42:43]
	s_mov_b32 m0, s53
	s_nop 0
	global_load_lds_dwordx4 v206, s[42:43]
	s_waitcnt vmcnt(8)
	s_waitcnt lgkmcnt(0)
	s_barrier
	s_setprio 1
	s_waitcnt lgkmcnt(0)
	v_mfma_f32_16x16x32_bf16 v[62:65], v[118:121], v[162:165], v[62:65]
	v_mfma_f32_16x16x32_bf16 v[58:61], v[130:133], v[162:165], v[58:61]
	v_mfma_f32_16x16x32_bf16 v[46:49], v[118:121], v[170:173], v[46:49]
	v_mfma_f32_16x16x32_bf16 v[42:45], v[130:133], v[170:173], v[42:45]
	v_mfma_f32_16x16x32_bf16 v[30:33], v[118:121], v[178:181], v[30:33]
	v_mfma_f32_16x16x32_bf16 v[26:29], v[130:133], v[178:181], v[26:29]
	v_mfma_f32_16x16x32_bf16 v[14:17], v[118:121], v[186:189], v[14:17]
	v_mfma_f32_16x16x32_bf16 v[10:13], v[130:133], v[186:189], v[10:13]
	v_mfma_f32_16x16x32_bf16 v[62:65], v[122:125], v[166:169], v[62:65]
	v_mfma_f32_16x16x32_bf16 v[58:61], v[134:137], v[166:169], v[58:61]
	v_mfma_f32_16x16x32_bf16 v[46:49], v[122:125], v[174:177], v[46:49]
	v_mfma_f32_16x16x32_bf16 v[42:45], v[134:137], v[174:177], v[42:45]
	v_mfma_f32_16x16x32_bf16 v[30:33], v[122:125], v[182:185], v[30:33]
	v_mfma_f32_16x16x32_bf16 v[26:29], v[134:137], v[182:185], v[26:29]
	v_mfma_f32_16x16x32_bf16 v[14:17], v[122:125], v[214:217], v[14:17]
	v_mfma_f32_16x16x32_bf16 v[10:13], v[134:137], v[214:217], v[10:13]
	s_setprio 0
	s_setprio 1
	v_mfma_f32_16x16x32_bf16 v[54:57], v[146:149], v[162:165], v[54:57]
	v_mfma_f32_16x16x32_bf16 v[50:53], v[154:157], v[162:165], v[50:53]
	v_mfma_f32_16x16x32_bf16 v[38:41], v[146:149], v[170:173], v[38:41]
	v_mfma_f32_16x16x32_bf16 v[34:37], v[154:157], v[170:173], v[34:37]
	v_mfma_f32_16x16x32_bf16 v[22:25], v[146:149], v[178:181], v[22:25]
	v_mfma_f32_16x16x32_bf16 v[18:21], v[154:157], v[178:181], v[18:21]
	v_mfma_f32_16x16x32_bf16 v[6:9], v[146:149], v[186:189], v[6:9]
	v_mfma_f32_16x16x32_bf16 v[2:5], v[154:157], v[186:189], v[2:5]
	v_mfma_f32_16x16x32_bf16 v[54:57], v[150:153], v[166:169], v[54:57]
	v_mfma_f32_16x16x32_bf16 v[50:53], v[158:161], v[166:169], v[50:53]
	v_mfma_f32_16x16x32_bf16 v[38:41], v[150:153], v[174:177], v[38:41]
	v_mfma_f32_16x16x32_bf16 v[34:37], v[158:161], v[174:177], v[34:37]
	v_mfma_f32_16x16x32_bf16 v[22:25], v[150:153], v[182:185], v[22:25]
	v_mfma_f32_16x16x32_bf16 v[18:21], v[158:161], v[182:185], v[18:21]
	v_mfma_f32_16x16x32_bf16 v[6:9], v[150:153], v[214:217], v[6:9]
	v_mfma_f32_16x16x32_bf16 v[2:5], v[158:161], v[214:217], v[2:5]
	s_setprio 0
	s_barrier
; #define PG8_STAGE(bufoff, gbase, voff) do { _Pragma("unroll") for (int _i = 0; _i < 2; ++_i) \
;         __builtin_amdgcn_global_load_lds((const unsigned*)((const char*)(gbase) + (voff)[_i]), (PG8_LAS unsigned*)(lds + (bufoff) + ldsw + _i * 8192), 16, 0, 0); } while (0)
; #define PG8_LDA(dst, b, h) do { _Pragma("unroll") for (int m = 0; m < 4; ++m) _Pragma("unroll") for (int k = 0; k < 2; ++k) dst[m][k] = *(const PG8_LAS bf16x8*)(lds + PG8_SA(b, h) + aoff + m * 2048 + k * 1024); } while (0)
; #define PG8_WAIT_V(n) asm volatile("s_waitcnt vmcnt(" #n ")" ::: "memory")
; #define PG8_WAIT_L(n) asm volatile("s_waitcnt lgkmcnt(" #n ")" ::: "memory")
; #define PG8_BAR __builtin_amdgcn_s_barrier()
; template <class Epi, class Sched, bool ALIGN_EPI = false, bool SP2 = false>
; __device__ __forceinline__ void gemm_phase(PG8_LAS unsigned char* lds, const Gemm g, const Sched& S, const Epi& E, const int wave_id) {
;     ...
;         for (int t = 0; t < nt; t += 2) {
;             const bool last = (t == nt - 2);
;             const char* a1 = cA + (size_t)(t + 1) * kstep;
;             const char* a2 = last ? nA : cA + (size_t)(t + 2) * kstep; const char* b2 = last ? nB : cB + (size_t)(t + 2) * kstep;
;             const char* a3 = a2 + kstep; const char* b3 = b2 + kstep;
;             if (last && has_next) S.a_ready(nxt);
;             if constexpr (SP2) {
;             PG8_LDB(B0, 0, 0); PG8_LDB(B1, 0, 1); PG8_SCHED; PG8_LDA(At, 0, 0); PG8_STAGE(PG8_SA(1, 1), a1 + hstep, voffA);
;             PG8_WAIT_V(8); PG8_WAIT_L(0); PG8_BAR; PG8_MMA(0, 0, At, B0); PG8_MMA(0, 1, At, B1); PG8_BAR; PG8_SCHED;
;             PG8_LDA(At, 0, 1); PG8_STAGE(PG8_SB(0, 0), b2, voffB); PG8_STAGE(PG8_SB(0, 1), b2 + hstep, voffB); PG8_STAGE(PG8_SA(0, 0), a2, voffA);
;             PG8_WAIT_V(8); PG8_WAIT_L(0); PG8_BAR; PG8_MMA(1, 0, At, B0); PG8_MMA(1, 1, At, B1); PG8_BAR; PG8_SCHED;
;             PG8_LDB(B0, 1, 0); PG8_LDB(B1, 1, 1); PG8_SCHED; PG8_LDA(At, 1, 0); PG8_STAGE(PG8_SA(0, 1), a2 + hstep, voffA);
;             PG8_WAIT_V(8); PG8_WAIT_L(0); PG8_BAR; PG8_MMA(0, 0, At, B0); PG8_MMA(0, 1, At, B1); PG8_BAR; PG8_SCHED;
;             PG8_LDA(At, 1, 1); PG8_STAGE(PG8_SB(1, 0), b3, voffB); PG8_STAGE(PG8_SB(1, 1), b3 + hstep, voffB); PG8_STAGE(PG8_SA(1, 0), a3, voffA);
;             PG8_WAIT_V(8); PG8_WAIT_L(0); PG8_BAR; PG8_MMA(1, 0, At, B0); PG8_MMA(1, 1, At, B1); PG8_BAR; PG8_SCHED;
	s_add_i32 s77, 0, 0x18000
	s_add_i32 s79, 0, 0x1c000
	s_add_u32 s18, s42, 0x160000
	s_addc_u32 s19, s43, 0
	s_mov_b32 m0, s56
	s_nop 0
	global_load_lds_dwordx4 v190, s[18:19]
	ds_read_b128 v[118:121], v226 offset:32768
	ds_read_b128 v[122:125], v226 offset:33792
	ds_read_b128 v[130:133], v226 offset:34816
	ds_read_b128 v[134:137], v226 offset:35840
	ds_read_b128 v[146:149], v226 offset:49152
	ds_read_b128 v[150:153], v226 offset:50176
	ds_read_b128 v[154:157], v226 offset:51200
	ds_read_b128 v[158:161], v226 offset:52224
	s_mov_b32 m0, s57
	s_nop 0
	global_load_lds_dwordx4 v206, s[18:19]
	ds_read_b128 v[162:165], v222 offset:32768
	ds_read_b128 v[166:169], v222 offset:33792
	ds_read_b128 v[170:173], v222 offset:34816
	ds_read_b128 v[174:177], v222 offset:35840
	ds_read_b128 v[178:181], v222 offset:36864
	ds_read_b128 v[182:185], v222 offset:37888
	ds_read_b128 v[186:189], v222 offset:38912
	ds_read_b128 v[214:217], v222 offset:39936
	s_waitcnt vmcnt(8)
	s_waitcnt lgkmcnt(0)
	s_barrier
	s_setprio 1
	s_waitcnt lgkmcnt(0)
	v_mfma_f32_16x16x32_bf16 v[142:145], v[118:121], v[162:165], v[142:145]
	v_mfma_f32_16x16x32_bf16 v[138:141], v[130:133], v[162:165], v[138:141]
	v_mfma_f32_16x16x32_bf16 v[110:113], v[118:121], v[170:173], v[110:113]
	v_mfma_f32_16x16x32_bf16 v[106:109], v[130:133], v[170:173], v[106:109]
	v_mfma_f32_16x16x32_bf16 v[94:97], v[118:121], v[178:181], v[94:97]
	v_mfma_f32_16x16x32_bf16 v[90:93], v[130:133], v[178:181], v[90:93]
	v_mfma_f32_16x16x32_bf16 v[78:81], v[118:121], v[186:189], v[78:81]
	v_mfma_f32_16x16x32_bf16 v[74:77], v[130:133], v[186:189], v[74:77]
	v_mfma_f32_16x16x32_bf16 v[142:145], v[122:125], v[166:169], v[142:145]
	v_mfma_f32_16x16x32_bf16 v[138:141], v[134:137], v[166:169], v[138:141]
	v_mfma_f32_16x16x32_bf16 v[110:113], v[122:125], v[174:177], v[110:113]
	v_mfma_f32_16x16x32_bf16 v[106:109], v[134:137], v[174:177], v[106:109]
	v_mfma_f32_16x16x32_bf16 v[94:97], v[122:125], v[182:185], v[94:97]
	v_mfma_f32_16x16x32_bf16 v[90:93], v[134:137], v[182:185], v[90:93]
	v_mfma_f32_16x16x32_bf16 v[78:81], v[122:125], v[214:217], v[78:81]
	v_mfma_f32_16x16x32_bf16 v[74:77], v[134:137], v[214:217], v[74:77]
	s_setprio 0
	s_setprio 1
	v_mfma_f32_16x16x32_bf16 v[126:129], v[146:149], v[162:165], v[126:129]
	v_mfma_f32_16x16x32_bf16 v[114:117], v[154:157], v[162:165], v[114:117]
	v_mfma_f32_16x16x32_bf16 v[102:105], v[146:149], v[170:173], v[102:105]
	v_mfma_f32_16x16x32_bf16 v[98:101], v[154:157], v[170:173], v[98:101]
	v_mfma_f32_16x16x32_bf16 v[86:89], v[146:149], v[178:181], v[86:89]
	v_mfma_f32_16x16x32_bf16 v[82:85], v[154:157], v[178:181], v[82:85]
	v_mfma_f32_16x16x32_bf16 v[70:73], v[146:149], v[186:189], v[70:73]
	v_mfma_f32_16x16x32_bf16 v[66:69], v[154:157], v[186:189], v[66:69]
	v_mfma_f32_16x16x32_bf16 v[126:129], v[150:153], v[166:169], v[126:129]
	v_mfma_f32_16x16x32_bf16 v[114:117], v[158:161], v[166:169], v[114:117]
	v_mfma_f32_16x16x32_bf16 v[102:105], v[150:153], v[174:177], v[102:105]
	v_mfma_f32_16x16x32_bf16 v[98:101], v[158:161], v[174:177], v[98:101]
	v_mfma_f32_16x16x32_bf16 v[86:89], v[150:153], v[182:185], v[86:89]
	v_mfma_f32_16x16x32_bf16 v[82:85], v[158:161], v[182:185], v[82:85]
	v_mfma_f32_16x16x32_bf16 v[70:73], v[150:153], v[214:217], v[70:73]
	v_mfma_f32_16x16x32_bf16 v[66:69], v[158:161], v[214:217], v[66:69]
	s_setprio 0
	s_barrier
	s_add_u32 vcc_lo, s42, 0x80
	s_addc_u32 vcc_hi, s43, 0
	s_mov_b32 m0, s68
	s_nop 0
	global_load_lds_dwordx4 v190, vcc
	ds_read_b128 v[162:165], v222 offset:49152
	ds_read_b128 v[166:169], v222 offset:50176
	s_mov_b32 m0, s69
	s_add_i32 s18, s77, s49
	global_load_lds_dwordx4 v206, vcc
	ds_read_b128 v[170:173], v222 offset:51200
	ds_read_b128 v[174:177], v222 offset:52224
	s_add_u32 vcc_lo, s40, 0x80
	s_addc_u32 vcc_hi, s41, 0
	s_mov_b32 m0, s18
	s_nop 0
	global_load_lds_dwordx4 v192, vcc
	ds_read_b128 v[178:181], v222 offset:53248
	ds_read_b128 v[182:185], v222 offset:54272
	s_add_i32 m0, s18, 0x2000
	s_add_u32 s18, s40, 0x160080
	s_addc_u32 s19, s41, 0
	global_load_lds_dwordx4 v208, vcc
	ds_read_b128 v[186:189], v222 offset:55296
	ds_read_b128 v[214:217], v222 offset:56320
	s_add_i32 s40, s79, s49
	s_mov_b32 m0, s40
	s_nop 0
	global_load_lds_dwordx4 v192, s[18:19]
	s_add_i32 m0, s40, 0x2000
	s_nop 0
	global_load_lds_dwordx4 v208, s[18:19]
	s_waitcnt vmcnt(8)
	s_waitcnt lgkmcnt(0)
	s_barrier
	s_setprio 1
	s_waitcnt lgkmcnt(0)
	v_mfma_f32_16x16x32_bf16 v[62:65], v[118:121], v[162:165], v[62:65]
	v_mfma_f32_16x16x32_bf16 v[58:61], v[130:133], v[162:165], v[58:61]
	v_mfma_f32_16x16x32_bf16 v[46:49], v[118:121], v[170:173], v[46:49]
	v_mfma_f32_16x16x32_bf16 v[42:45], v[130:133], v[170:173], v[42:45]
	v_mfma_f32_16x16x32_bf16 v[30:33], v[118:121], v[178:181], v[30:33]
	v_mfma_f32_16x16x32_bf16 v[26:29], v[130:133], v[178:181], v[26:29]
	v_mfma_f32_16x16x32_bf16 v[14:17], v[118:121], v[186:189], v[14:17]
	v_mfma_f32_16x16x32_bf16 v[10:13], v[130:133], v[186:189], v[10:13]
	v_mfma_f32_16x16x32_bf16 v[62:65], v[122:125], v[166:169], v[62:65]
	v_mfma_f32_16x16x32_bf16 v[58:61], v[134:137], v[166:169], v[58:61]
	v_mfma_f32_16x16x32_bf16 v[46:49], v[122:125], v[174:177], v[46:49]
	v_mfma_f32_16x16x32_bf16 v[42:45], v[134:137], v[174:177], v[42:45]
	v_mfma_f32_16x16x32_bf16 v[30:33], v[122:125], v[182:185], v[30:33]
	v_mfma_f32_16x16x32_bf16 v[26:29], v[134:137], v[182:185], v[26:29]
	v_mfma_f32_16x16x32_bf16 v[14:17], v[122:125], v[214:217], v[14:17]
	v_mfma_f32_16x16x32_bf16 v[10:13], v[134:137], v[214:217], v[10:13]
	s_setprio 0
	s_setprio 1
	v_mfma_f32_16x16x32_bf16 v[54:57], v[146:149], v[162:165], v[54:57]
	v_mfma_f32_16x16x32_bf16 v[50:53], v[154:157], v[162:165], v[50:53]
	v_mfma_f32_16x16x32_bf16 v[38:41], v[146:149], v[170:173], v[38:41]
	v_mfma_f32_16x16x32_bf16 v[34:37], v[154:157], v[170:173], v[34:37]
	v_mfma_f32_16x16x32_bf16 v[22:25], v[146:149], v[178:181], v[22:25]
	v_mfma_f32_16x16x32_bf16 v[18:21], v[154:157], v[178:181], v[18:21]
	v_mfma_f32_16x16x32_bf16 v[6:9], v[146:149], v[186:189], v[6:9]
	v_mfma_f32_16x16x32_bf16 v[2:5], v[154:157], v[186:189], v[2:5]
	v_mfma_f32_16x16x32_bf16 v[54:57], v[150:153], v[166:169], v[54:57]
	v_mfma_f32_16x16x32_bf16 v[50:53], v[158:161], v[166:169], v[50:53]
	v_mfma_f32_16x16x32_bf16 v[38:41], v[150:153], v[174:177], v[38:41]
	v_mfma_f32_16x16x32_bf16 v[34:37], v[158:161], v[174:177], v[34:37]
	v_mfma_f32_16x16x32_bf16 v[22:25], v[150:153], v[182:185], v[22:25]
	v_mfma_f32_16x16x32_bf16 v[18:21], v[158:161], v[182:185], v[18:21]
	v_mfma_f32_16x16x32_bf16 v[6:9], v[150:153], v[214:217], v[6:9]
	v_mfma_f32_16x16x32_bf16 v[2:5], v[158:161], v[214:217], v[2:5]
	s_setprio 0
	s_barrier
	s_add_i32 s76, s76, 2
	s_add_u32 s74, s74, 0x100
	s_addc_u32 s75, s75, 0
	s_cmpk_gt_u32 s76, 0x55
	s_mov_b64 s[18:19], s[20:21]
	s_cbranch_scc0 .LBB0_759

;     __host__ __device__ bool next(int i, Unit& u) const { const bool ok = StaticOrder::next(i, u); u.lm = 0; u.ln = 0; return ok; }
; #define PG8_BAR __builtin_amdgcn_s_barrier()
; template <class Epi, class Sched, bool ALIGN_EPI = false, bool SP2 = false>
; __device__ __forceinline__ void gemm_phase(PG8_LAS unsigned char* lds, const Gemm g, const Sched& S, const Epi& E, const int wave_id) {
;     ...
;         const bool has_next = S.next(ui + 1, nxt);
;         const char* nA = has_next ? (const char*)g.A + (size_t)nxt.lm * tstep : cA; const char* nB = has_next ? (const char*)g.Bt + (size_t)nxt.ln * tstep : cB;
; #pragma unroll 1
;         for (int t = 0; t < nt; t += 2) {
;             const bool last = (t == nt - 2);
;             const char* a1 = cA + (size_t)(t + 1) * kstep;
;             const char* a2 = last ? nA : cA + (size_t)(t + 2) * kstep; const char* b2 = last ? nB : cB + (size_t)(t + 2) * kstep;
;             const char* a3 = a2 + kstep; const char* b3 = b2 + kstep;
;             if (last && has_next) S.a_ready(nxt);
;             if constexpr (SP2) {
;             PG8_LDB(B0, 0, 0); PG8_LDB(B1, 0, 1); PG8_SCHED; PG8_LDA(At, 0, 0); PG8_STAGE(PG8_SA(1, 1), a1 + hstep, voffA);
;             PG8_WAIT_V(8); PG8_WAIT_L(0); PG8_BAR; PG8_MMA(0, 0, At, B0); PG8_MMA(0, 1, At, B1); PG8_BAR; PG8_SCHED;
;             PG8_LDA(At, 0, 1); PG8_STAGE(PG8_SB(0, 0), b2, voffB); PG8_STAGE(PG8_SB(0, 1), b2 + hstep, voffB); PG8_STAGE(PG8_SA(0, 0), a2, voffA);
;             PG8_WAIT_V(8); PG8_WAIT_L(0); PG8_BAR; PG8_MMA(1, 0, At, B0); PG8_MMA(1, 1, At, B1); PG8_BAR; PG8_SCHED;
;             PG8_LDB(B0, 1, 0); PG8_LDB(B1, 1, 1); PG8_SCHED; PG8_LDA(At, 1, 0); PG8_STAGE(PG8_SA(0, 1), a2 + hstep, voffA);
;             PG8_WAIT_V(8); PG8_WAIT_L(0); PG8_BAR; PG8_MMA(0, 0, At, B0); PG8_MMA(0, 1, At, B1); PG8_BAR; PG8_SCHED;
;             PG8_LDA(At, 1, 1); PG8_STAGE(PG8_SB(1, 0), b3, voffB); PG8_STAGE(PG8_SB(1, 1), b3 + hstep, voffB); PG8_STAGE(PG8_SA(1, 0), a3, voffA);
;             PG8_WAIT_V(8); PG8_WAIT_L(0); PG8_BAR; PG8_MMA(1, 0, At, B0); PG8_MMA(1, 1, At, B1); PG8_BAR; PG8_SCHED;
;     ...
; #pragma unroll
;         for (int a = 0; a < 2; ++a)
; #pragma unroll
;             for (int b = 0; b < 2; ++b)
; #pragma unroll
;                 for (int m = 0; m < 4; ++m)
; #pragma unroll
;                     for (int n = 0; n < 2; ++n) acc[a][b][m][n] = (f32x4){0.f, 0.f, 0.f, 0.f};
.LBB0_798:
	s_ashr_i32 s19, s18, 31
	s_lshl_b64 s[20:21], s[18:19], 17
	s_add_u32 s20, s56, s20
	s_addc_u32 s21, s57, s21
	s_and_b64 s[38:39], s[36:37], exec
	s_cselect_b32 s19, s21, s15
	s_cselect_b32 s77, s20, s14
	s_ashr_i32 s17, s16, 31
	s_lshl_b64 s[38:39], s[16:17], 17
	s_add_u32 s38, s64, s38
	s_addc_u32 s39, s65, s39
	s_and_b64 s[40:41], s[36:37], exec
	s_cselect_b32 s17, s39, s13
	s_cselect_b32 s79, s38, s12
	s_mov_b64 s[44:45], 0
	s_mov_b64 s[40:41], -1
	s_mov_b64 s[42:43], 0
	s_add_u32 s52, s14, s44
	s_addc_u32 s53, s15, s45
	s_add_u32 s48, s52, 0x100
	s_addc_u32 s49, s53, 0
	s_and_b64 s[46:47], s[42:43], exec
	s_cselect_b32 s47, s19, s49
	s_cselect_b32 s46, s77, s48
	s_add_u32 s44, s12, s44
	s_addc_u32 s45, s13, s45
	s_add_u32 s44, s44, 0x100
	s_addc_u32 s45, s45, 0
	s_add_i32 s96, 0, 0x10000
	s_and_b64 s[42:43], s[42:43], exec
	s_cselect_b32 s49, s17, s45
	s_cselect_b32 s48, s79, s44
	s_add_i32 s43, 0, 0x14000
	s_add_u32 s82, s52, 0x10080
	s_addc_u32 s83, s53, 0
	s_add_i32 s93, s96, s68
	s_add_i32 m0, s69, 0xc000
	s_add_i32 vcc_lo, s69, 0xe000
	s_add_i32 s88, s93, 0x2000
	v_add_u32_e32 v141, s96, v138
	s_add_u32 s52, s48, 0x10000
	ds_read_b128 v[142:145], v141
	ds_read_b128 v[146:149], v141 offset:1024
	ds_read_b128 v[150:153], v141 offset:2048
	ds_read_b128 v[154:157], v141 offset:3072
	v_add_u32_e32 v141, s43, v138
	s_addc_u32 s53, s49, 0
	s_add_i32 s92, s43, s68
	ds_read_b128 v[158:161], v141
	ds_read_b128 v[162:165], v141 offset:1024
	ds_read_b128 v[166:169], v141 offset:2048
	ds_read_b128 v[170:173], v141 offset:3072
	s_add_i32 s89, s92, 0x2000
	s_add_i32 s85, 0, 0x18000
	s_add_i32 s84, 0, 0x1c000
	s_add_u32 s44, s46, 0x10000
	s_addc_u32 s45, s47, 0
	s_add_i32 s81, s85, s68
	s_add_i32 s80, s81, 0x2000
	s_add_u32 s42, s48, 0x10080
	s_addc_u32 s43, s49, 0
	s_add_i32 s97, s84, s68
	s_add_i32 s96, s97, 0x2000
	v_lshl_add_u64 v[226:227], s[82:83], 0, v[130:131]
	ds_read_b128 v[174:177], v140
	ds_read_b128 v[178:181], v140 offset:1024
	ds_read_b128 v[182:185], v140 offset:2048
	ds_read_b128 v[186:189], v140 offset:3072
	ds_read_b128 v[190:193], v140 offset:4096
	ds_read_b128 v[206:209], v140 offset:5120
	ds_read_b128 v[210:213], v140 offset:6144
	ds_read_b128 v[214:217], v140 offset:7168
	global_load_lds_dwordx4 v[226:227], off
	v_lshl_add_u64 v[226:227], s[82:83], 0, v[134:135]
	s_mov_b32 m0, vcc_lo
	s_nop 0
	global_load_lds_dwordx4 v[226:227], off
	s_waitcnt vmcnt(8)
	s_waitcnt lgkmcnt(0)
	s_barrier
	s_setprio 1
	s_waitcnt lgkmcnt(0)
	v_mfma_f32_16x16x32_bf16 v[126:129], v[142:145], v[174:177], 0
	v_mfma_f32_16x16x32_bf16 v[122:125], v[150:153], v[174:177], 0
	v_mfma_f32_16x16x32_bf16 v[118:121], v[142:145], v[182:185], 0
	v_mfma_f32_16x16x32_bf16 v[114:117], v[150:153], v[182:185], 0
	v_mfma_f32_16x16x32_bf16 v[102:105], v[142:145], v[190:193], 0
	v_mfma_f32_16x16x32_bf16 v[98:101], v[150:153], v[190:193], 0
	v_mfma_f32_16x16x32_bf16 v[86:89], v[142:145], v[210:213], 0
	v_mfma_f32_16x16x32_bf16 v[82:85], v[150:153], v[210:213], 0
	v_mfma_f32_16x16x32_bf16 v[126:129], v[146:149], v[178:181], v[126:129]
	v_mfma_f32_16x16x32_bf16 v[122:125], v[154:157], v[178:181], v[122:125]
	v_mfma_f32_16x16x32_bf16 v[118:121], v[146:149], v[186:189], v[118:121]
	v_mfma_f32_16x16x32_bf16 v[114:117], v[154:157], v[186:189], v[114:117]
	v_mfma_f32_16x16x32_bf16 v[102:105], v[146:149], v[206:209], v[102:105]
	v_mfma_f32_16x16x32_bf16 v[98:101], v[154:157], v[206:209], v[98:101]
	v_mfma_f32_16x16x32_bf16 v[86:89], v[146:149], v[214:217], v[86:89]
	v_mfma_f32_16x16x32_bf16 v[82:85], v[154:157], v[214:217], v[82:85]
	s_setprio 0
	s_setprio 1
	v_mfma_f32_16x16x32_bf16 v[110:113], v[158:161], v[174:177], 0
	v_mfma_f32_16x16x32_bf16 v[106:109], v[166:169], v[174:177], 0
	v_mfma_f32_16x16x32_bf16 v[94:97], v[158:161], v[182:185], 0
	v_mfma_f32_16x16x32_bf16 v[90:93], v[166:169], v[182:185], 0
	v_mfma_f32_16x16x32_bf16 v[78:81], v[158:161], v[190:193], 0
	v_mfma_f32_16x16x32_bf16 v[74:77], v[166:169], v[190:193], 0
	v_mfma_f32_16x16x32_bf16 v[70:73], v[158:161], v[210:213], 0
	v_mfma_f32_16x16x32_bf16 v[66:69], v[166:169], v[210:213], 0
	v_mfma_f32_16x16x32_bf16 v[110:113], v[162:165], v[178:181], v[110:113]
	v_mfma_f32_16x16x32_bf16 v[106:109], v[170:173], v[178:181], v[106:109]
	v_mfma_f32_16x16x32_bf16 v[94:97], v[162:165], v[186:189], v[94:97]
	v_mfma_f32_16x16x32_bf16 v[90:93], v[170:173], v[186:189], v[90:93]
	v_mfma_f32_16x16x32_bf16 v[78:81], v[162:165], v[206:209], v[78:81]
	v_mfma_f32_16x16x32_bf16 v[74:77], v[170:173], v[206:209], v[74:77]
	v_mfma_f32_16x16x32_bf16 v[70:73], v[162:165], v[214:217], v[70:73]
	v_mfma_f32_16x16x32_bf16 v[66:69], v[170:173], v[214:217], v[66:69]
	s_setprio 0
	s_barrier
	s_mov_b32 m0, s93
	v_lshl_add_u64 v[226:227], s[48:49], 0, v[132:133]
	ds_read_b128 v[174:177], v140 offset:16384
	ds_read_b128 v[178:181], v140 offset:17408
	ds_read_b128 v[182:185], v140 offset:18432
	ds_read_b128 v[186:189], v140 offset:19456
	ds_read_b128 v[190:193], v140 offset:20480
	ds_read_b128 v[206:209], v140 offset:21504
	ds_read_b128 v[210:213], v140 offset:22528
	ds_read_b128 v[214:217], v140 offset:23552
	global_load_lds_dwordx4 v[226:227], off
	v_lshl_add_u64 v[228:229], s[48:49], 0, v[136:137]
	s_mov_b32 m0, s88
	v_lshl_add_u64 v[230:231], s[52:53], 0, v[132:133]
	global_load_lds_dwordx4 v[228:229], off
	s_mov_b32 m0, s92
	v_lshl_add_u64 v[234:235], s[46:47], 0, v[134:135]
	global_load_lds_dwordx4 v[230:231], off
	v_lshl_add_u64 v[230:231], s[52:53], 0, v[136:137]
	s_mov_b32 m0, s89
	s_nop 0
	global_load_lds_dwordx4 v[230:231], off
	v_lshl_add_u64 v[230:231], s[46:47], 0, v[130:131]
	s_mov_b32 m0, s69
	s_nop 0
	global_load_lds_dwordx4 v[230:231], off
	s_mov_b32 m0, s70
	s_nop 0
	global_load_lds_dwordx4 v[234:235], off
	s_waitcnt vmcnt(8)
	s_waitcnt lgkmcnt(0)
	s_barrier
; #define PG8_STAGE(bufoff, gbase, voff) do { _Pragma("unroll") for (int _i = 0; _i < 2; ++_i) \
;         __builtin_amdgcn_global_load_lds((const unsigned*)((const char*)(gbase) + (voff)[_i]), (PG8_LAS unsigned*)(lds + (bufoff) + ldsw + _i * 8192), 16, 0, 0); } while (0)
; #define PG8_LDA(dst, b, h) do { _Pragma("unroll") for (int m = 0; m < 4; ++m) _Pragma("unroll") for (int k = 0; k < 2; ++k) dst[m][k] = *(const PG8_LAS bf16x8*)(lds + PG8_SA(b, h) + aoff + m * 2048 + k * 1024); } while (0)
; #define PG8_WAIT_V(n) asm volatile("s_waitcnt vmcnt(" #n ")" ::: "memory")
; #define PG8_WAIT_L(n) asm volatile("s_waitcnt lgkmcnt(" #n ")" ::: "memory")
; #define PG8_BAR __builtin_amdgcn_s_barrier()
; template <class Epi, class Sched, bool ALIGN_EPI = false, bool SP2 = false>
; __device__ __forceinline__ void gemm_phase(PG8_LAS unsigned char* lds, const Gemm g, const Sched& S, const Epi& E, const int wave_id) {
;     ...
;         for (int t = 0; t < nt; t += 2) {
;             const bool last = (t == nt - 2);
;             const char* a1 = cA + (size_t)(t + 1) * kstep;
;             const char* a2 = last ? nA : cA + (size_t)(t + 2) * kstep; const char* b2 = last ? nB : cB + (size_t)(t + 2) * kstep;
;             const char* a3 = a2 + kstep; const char* b3 = b2 + kstep;
;             if (last && has_next) S.a_ready(nxt);
;             if constexpr (SP2) {
;             PG8_LDB(B0, 0, 0); PG8_LDB(B1, 0, 1); PG8_SCHED; PG8_LDA(At, 0, 0); PG8_STAGE(PG8_SA(1, 1), a1 + hstep, voffA);
;             PG8_WAIT_V(8); PG8_WAIT_L(0); PG8_BAR; PG8_MMA(0, 0, At, B0); PG8_MMA(0, 1, At, B1); PG8_BAR; PG8_SCHED;
;             PG8_LDA(At, 0, 1); PG8_STAGE(PG8_SB(0, 0), b2, voffB); PG8_STAGE(PG8_SB(0, 1), b2 + hstep, voffB); PG8_STAGE(PG8_SA(0, 0), a2, voffA);
;             PG8_WAIT_V(8); PG8_WAIT_L(0); PG8_BAR; PG8_MMA(1, 0, At, B0); PG8_MMA(1, 1, At, B1); PG8_BAR; PG8_SCHED;
;             PG8_LDB(B0, 1, 0); PG8_LDB(B1, 1, 1); PG8_SCHED; PG8_LDA(At, 1, 0); PG8_STAGE(PG8_SA(0, 1), a2 + hstep, voffA);
;             PG8_WAIT_V(8); PG8_WAIT_L(0); PG8_BAR; PG8_MMA(0, 0, At, B0); PG8_MMA(0, 1, At, B1); PG8_BAR; PG8_SCHED;
;             PG8_LDA(At, 1, 1); PG8_STAGE(PG8_SB(1, 0), b3, voffB); PG8_STAGE(PG8_SB(1, 1), b3 + hstep, voffB); PG8_STAGE(PG8_SA(1, 0), a3, voffA);
;             PG8_WAIT_V(8); PG8_WAIT_L(0); PG8_BAR; PG8_MMA(1, 0, At, B0); PG8_MMA(1, 1, At, B1); PG8_BAR; PG8_SCHED;
	s_setprio 1
	s_waitcnt lgkmcnt(0)
	v_mfma_f32_16x16x32_bf16 v[62:65], v[142:145], v[174:177], 0
	v_mfma_f32_16x16x32_bf16 v[58:61], v[150:153], v[174:177], 0
	v_mfma_f32_16x16x32_bf16 v[54:57], v[142:145], v[182:185], 0
	v_mfma_f32_16x16x32_bf16 v[50:53], v[150:153], v[182:185], 0
	v_mfma_f32_16x16x32_bf16 v[38:41], v[142:145], v[190:193], 0
	v_mfma_f32_16x16x32_bf16 v[34:37], v[150:153], v[190:193], 0
	v_mfma_f32_16x16x32_bf16 v[22:25], v[142:145], v[210:213], 0
	v_mfma_f32_16x16x32_bf16 v[18:21], v[150:153], v[210:213], 0
	v_mfma_f32_16x16x32_bf16 v[62:65], v[146:149], v[178:181], v[62:65]
	v_mfma_f32_16x16x32_bf16 v[58:61], v[154:157], v[178:181], v[58:61]
	v_mfma_f32_16x16x32_bf16 v[54:57], v[146:149], v[186:189], v[54:57]
	v_mfma_f32_16x16x32_bf16 v[50:53], v[154:157], v[186:189], v[50:53]
	v_mfma_f32_16x16x32_bf16 v[38:41], v[146:149], v[206:209], v[38:41]
	v_mfma_f32_16x16x32_bf16 v[34:37], v[154:157], v[206:209], v[34:37]
	v_mfma_f32_16x16x32_bf16 v[22:25], v[146:149], v[214:217], v[22:25]
	v_mfma_f32_16x16x32_bf16 v[18:21], v[154:157], v[214:217], v[18:21]
	s_setprio 0
	s_setprio 1
	v_mfma_f32_16x16x32_bf16 v[46:49], v[158:161], v[174:177], 0
	v_mfma_f32_16x16x32_bf16 v[42:45], v[166:169], v[174:177], 0
	v_mfma_f32_16x16x32_bf16 v[30:33], v[158:161], v[182:185], 0
	v_mfma_f32_16x16x32_bf16 v[26:29], v[166:169], v[182:185], 0
	v_mfma_f32_16x16x32_bf16 v[14:17], v[158:161], v[190:193], 0
	v_mfma_f32_16x16x32_bf16 v[10:13], v[166:169], v[190:193], 0
	v_mfma_f32_16x16x32_bf16 v[6:9], v[158:161], v[210:213], 0
	v_mfma_f32_16x16x32_bf16 v[2:5], v[166:169], v[210:213], 0
	v_mfma_f32_16x16x32_bf16 v[46:49], v[162:165], v[178:181], v[46:49]
	v_mfma_f32_16x16x32_bf16 v[42:45], v[170:173], v[178:181], v[42:45]
	v_mfma_f32_16x16x32_bf16 v[30:33], v[162:165], v[186:189], v[30:33]
	v_mfma_f32_16x16x32_bf16 v[26:29], v[170:173], v[186:189], v[26:29]
	v_mfma_f32_16x16x32_bf16 v[14:17], v[162:165], v[206:209], v[14:17]
	v_mfma_f32_16x16x32_bf16 v[10:13], v[170:173], v[206:209], v[10:13]
	v_mfma_f32_16x16x32_bf16 v[6:9], v[162:165], v[214:217], v[6:9]
	v_mfma_f32_16x16x32_bf16 v[2:5], v[170:173], v[214:217], v[2:5]
	s_setprio 0
	s_barrier
	v_add_u32_e32 v141, s85, v138
	ds_read_b128 v[142:145], v141
	ds_read_b128 v[146:149], v141 offset:1024
	ds_read_b128 v[150:153], v141 offset:2048
	ds_read_b128 v[154:157], v141 offset:3072
	v_add_u32_e32 v141, s84, v138
	ds_read_b128 v[158:161], v141
	ds_read_b128 v[162:165], v141 offset:1024
	ds_read_b128 v[166:169], v141 offset:2048
	ds_read_b128 v[170:173], v141 offset:3072
	s_mov_b32 m0, s71
	v_lshl_add_u64 v[236:237], s[44:45], 0, v[130:131]
	ds_read_b128 v[174:177], v140 offset:32768
	ds_read_b128 v[178:181], v140 offset:33792
	ds_read_b128 v[182:185], v140 offset:34816
	ds_read_b128 v[186:189], v140 offset:35840
	ds_read_b128 v[190:193], v140 offset:36864
	ds_read_b128 v[206:209], v140 offset:37888
	ds_read_b128 v[210:213], v140 offset:38912
	ds_read_b128 v[214:217], v140 offset:39936
	global_load_lds_dwordx4 v[236:237], off
	v_lshl_add_u64 v[236:237], s[44:45], 0, v[134:135]
	s_mov_b32 m0, s72
	s_nop 0
	global_load_lds_dwordx4 v[236:237], off
	s_waitcnt vmcnt(8)
	s_waitcnt lgkmcnt(0)
	s_barrier
	s_setprio 1
	s_waitcnt lgkmcnt(0)
	v_mfma_f32_16x16x32_bf16 v[126:129], v[142:145], v[174:177], v[126:129]
	v_mfma_f32_16x16x32_bf16 v[122:125], v[150:153], v[174:177], v[122:125]
	v_mfma_f32_16x16x32_bf16 v[118:121], v[142:145], v[182:185], v[118:121]
	v_mfma_f32_16x16x32_bf16 v[114:117], v[150:153], v[182:185], v[114:117]
	v_mfma_f32_16x16x32_bf16 v[102:105], v[142:145], v[190:193], v[102:105]
	v_mfma_f32_16x16x32_bf16 v[98:101], v[150:153], v[190:193], v[98:101]
	v_mfma_f32_16x16x32_bf16 v[86:89], v[142:145], v[210:213], v[86:89]
	v_mfma_f32_16x16x32_bf16 v[82:85], v[150:153], v[210:213], v[82:85]
	v_mfma_f32_16x16x32_bf16 v[126:129], v[146:149], v[178:181], v[126:129]
	v_mfma_f32_16x16x32_bf16 v[122:125], v[154:157], v[178:181], v[122:125]
	v_mfma_f32_16x16x32_bf16 v[118:121], v[146:149], v[186:189], v[118:121]
	v_mfma_f32_16x16x32_bf16 v[114:117], v[154:157], v[186:189], v[114:117]
	v_mfma_f32_16x16x32_bf16 v[102:105], v[146:149], v[206:209], v[102:105]
	v_mfma_f32_16x16x32_bf16 v[98:101], v[154:157], v[206:209], v[98:101]
	v_mfma_f32_16x16x32_bf16 v[86:89], v[146:149], v[214:217], v[86:89]
	v_mfma_f32_16x16x32_bf16 v[82:85], v[154:157], v[214:217], v[82:85]
	s_setprio 0
	s_setprio 1
	v_mfma_f32_16x16x32_bf16 v[110:113], v[158:161], v[174:177], v[110:113]
	v_mfma_f32_16x16x32_bf16 v[106:109], v[166:169], v[174:177], v[106:109]
	v_mfma_f32_16x16x32_bf16 v[94:97], v[158:161], v[182:185], v[94:97]
	v_mfma_f32_16x16x32_bf16 v[90:93], v[166:169], v[182:185], v[90:93]
	v_mfma_f32_16x16x32_bf16 v[78:81], v[158:161], v[190:193], v[78:81]
	v_mfma_f32_16x16x32_bf16 v[74:77], v[166:169], v[190:193], v[74:77]
	v_mfma_f32_16x16x32_bf16 v[70:73], v[158:161], v[210:213], v[70:73]
	v_mfma_f32_16x16x32_bf16 v[66:69], v[166:169], v[210:213], v[66:69]
	v_mfma_f32_16x16x32_bf16 v[110:113], v[162:165], v[178:181], v[110:113]
	v_mfma_f32_16x16x32_bf16 v[106:109], v[170:173], v[178:181], v[106:109]
	v_mfma_f32_16x16x32_bf16 v[94:97], v[162:165], v[186:189], v[94:97]
	v_mfma_f32_16x16x32_bf16 v[90:93], v[170:173], v[186:189], v[90:93]
	v_mfma_f32_16x16x32_bf16 v[78:81], v[162:165], v[206:209], v[78:81]
	v_mfma_f32_16x16x32_bf16 v[74:77], v[170:173], v[206:209], v[74:77]
	v_mfma_f32_16x16x32_bf16 v[70:73], v[162:165], v[214:217], v[70:73]
	v_mfma_f32_16x16x32_bf16 v[66:69], v[170:173], v[214:217], v[66:69]
	s_setprio 0
	s_barrier
; #define PG8_STAGE(bufoff, gbase, voff) do { _Pragma("unroll") for (int _i = 0; _i < 2; ++_i) \
;         __builtin_amdgcn_global_load_lds((const unsigned*)((const char*)(gbase) + (voff)[_i]), (PG8_LAS unsigned*)(lds + (bufoff) + ldsw + _i * 8192), 16, 0, 0); } while (0)
; #define PG8_LDA(dst, b, h) do { _Pragma("unroll") for (int m = 0; m < 4; ++m) _Pragma("unroll") for (int k = 0; k < 2; ++k) dst[m][k] = *(const PG8_LAS bf16x8*)(lds + PG8_SA(b, h) + aoff + m * 2048 + k * 1024); } while (0)
; #define PG8_WAIT_V(n) asm volatile("s_waitcnt vmcnt(" #n ")" ::: "memory")
; #define PG8_WAIT_L(n) asm volatile("s_waitcnt lgkmcnt(" #n ")" ::: "memory")
; #define PG8_BAR __builtin_amdgcn_s_barrier()
; template <class Epi, class Sched, bool ALIGN_EPI = false, bool SP2 = false>
; __device__ __forceinline__ void gemm_phase(PG8_LAS unsigned char* lds, const Gemm g, const Sched& S, const Epi& E, const int wave_id) {
;     ...
;         for (int t = 0; t < nt; t += 2) {
;             const bool last = (t == nt - 2);
;             const char* a1 = cA + (size_t)(t + 1) * kstep;
;             const char* a2 = last ? nA : cA + (size_t)(t + 2) * kstep; const char* b2 = last ? nB : cB + (size_t)(t + 2) * kstep;
;             const char* a3 = a2 + kstep; const char* b3 = b2 + kstep;
;             if (last && has_next) S.a_ready(nxt);
;             if constexpr (SP2) {
;             PG8_LDB(B0, 0, 0); PG8_LDB(B1, 0, 1); PG8_SCHED; PG8_LDA(At, 0, 0); PG8_STAGE(PG8_SA(1, 1), a1 + hstep, voffA);
;             PG8_WAIT_V(8); PG8_WAIT_L(0); PG8_BAR; PG8_MMA(0, 0, At, B0); PG8_MMA(0, 1, At, B1); PG8_BAR; PG8_SCHED;
;             PG8_LDA(At, 0, 1); PG8_STAGE(PG8_SB(0, 0), b2, voffB); PG8_STAGE(PG8_SB(0, 1), b2 + hstep, voffB); PG8_STAGE(PG8_SA(0, 0), a2, voffA);
;             PG8_WAIT_V(8); PG8_WAIT_L(0); PG8_BAR; PG8_MMA(1, 0, At, B0); PG8_MMA(1, 1, At, B1); PG8_BAR; PG8_SCHED;
;             PG8_LDB(B0, 1, 0); PG8_LDB(B1, 1, 1); PG8_SCHED; PG8_LDA(At, 1, 0); PG8_STAGE(PG8_SA(0, 1), a2 + hstep, voffA);
;             PG8_WAIT_V(8); PG8_WAIT_L(0); PG8_BAR; PG8_MMA(0, 0, At, B0); PG8_MMA(0, 1, At, B1); PG8_BAR; PG8_SCHED;
;             PG8_LDA(At, 1, 1); PG8_STAGE(PG8_SB(1, 0), b3, voffB); PG8_STAGE(PG8_SB(1, 1), b3 + hstep, voffB); PG8_STAGE(PG8_SA(1, 0), a3, voffA);
;             PG8_WAIT_V(8); PG8_WAIT_L(0); PG8_BAR; PG8_MMA(1, 0, At, B0); PG8_MMA(1, 1, At, B1); PG8_BAR; PG8_SCHED;
	s_mov_b32 m0, s81
	v_lshl_add_u64 v[226:227], v[226:227], 0, s[30:31]
	ds_read_b128 v[174:177], v140 offset:49152
	ds_read_b128 v[178:181], v140 offset:50176
	ds_read_b128 v[182:185], v140 offset:51200
	ds_read_b128 v[186:189], v140 offset:52224
	ds_read_b128 v[190:193], v140 offset:53248
	ds_read_b128 v[206:209], v140 offset:54272
	ds_read_b128 v[210:213], v140 offset:55296
	ds_read_b128 v[214:217], v140 offset:56320
	global_load_lds_dwordx4 v[226:227], off
	v_lshl_add_u64 v[226:227], v[228:229], 0, s[30:31]
	s_mov_b32 m0, s80
	s_nop 0
	global_load_lds_dwordx4 v[226:227], off
	v_lshl_add_u64 v[226:227], s[42:43], 0, v[132:133]
	s_mov_b32 m0, s97
	s_nop 0
	global_load_lds_dwordx4 v[226:227], off
	v_lshl_add_u64 v[226:227], s[42:43], 0, v[136:137]
	s_mov_b32 m0, s96
	s_nop 0
	global_load_lds_dwordx4 v[226:227], off
	v_lshl_add_u64 v[226:227], v[230:231], 0, s[30:31]
	s_mov_b32 m0, s73
	s_nop 0
	global_load_lds_dwordx4 v[226:227], off
	v_lshl_add_u64 v[226:227], v[234:235], 0, s[30:31]
	s_mov_b32 m0, s74
	s_nop 0
	global_load_lds_dwordx4 v[226:227], off
	s_waitcnt vmcnt(8)
	s_waitcnt lgkmcnt(0)
	s_barrier
	s_setprio 1
	s_waitcnt lgkmcnt(0)
	v_mfma_f32_16x16x32_bf16 v[62:65], v[142:145], v[174:177], v[62:65]
	v_mfma_f32_16x16x32_bf16 v[58:61], v[150:153], v[174:177], v[58:61]
	v_mfma_f32_16x16x32_bf16 v[54:57], v[142:145], v[182:185], v[54:57]
	v_mfma_f32_16x16x32_bf16 v[50:53], v[150:153], v[182:185], v[50:53]
	v_mfma_f32_16x16x32_bf16 v[38:41], v[142:145], v[190:193], v[38:41]
	v_mfma_f32_16x16x32_bf16 v[34:37], v[150:153], v[190:193], v[34:37]
	v_mfma_f32_16x16x32_bf16 v[22:25], v[142:145], v[210:213], v[22:25]
	v_mfma_f32_16x16x32_bf16 v[18:21], v[150:153], v[210:213], v[18:21]
	v_mfma_f32_16x16x32_bf16 v[62:65], v[146:149], v[178:181], v[62:65]
	v_mfma_f32_16x16x32_bf16 v[58:61], v[154:157], v[178:181], v[58:61]
	v_mfma_f32_16x16x32_bf16 v[54:57], v[146:149], v[186:189], v[54:57]
	v_mfma_f32_16x16x32_bf16 v[50:53], v[154:157], v[186:189], v[50:53]
	v_mfma_f32_16x16x32_bf16 v[38:41], v[146:149], v[206:209], v[38:41]
	v_mfma_f32_16x16x32_bf16 v[34:37], v[154:157], v[206:209], v[34:37]
	v_mfma_f32_16x16x32_bf16 v[22:25], v[146:149], v[214:217], v[22:25]
	v_mfma_f32_16x16x32_bf16 v[18:21], v[154:157], v[214:217], v[18:21]
	s_setprio 0
	s_setprio 1
	v_mfma_f32_16x16x32_bf16 v[46:49], v[158:161], v[174:177], v[46:49]
	v_mfma_f32_16x16x32_bf16 v[42:45], v[166:169], v[174:177], v[42:45]
	v_mfma_f32_16x16x32_bf16 v[30:33], v[158:161], v[182:185], v[30:33]
	v_mfma_f32_16x16x32_bf16 v[26:29], v[166:169], v[182:185], v[26:29]
	v_mfma_f32_16x16x32_bf16 v[14:17], v[158:161], v[190:193], v[14:17]
	v_mfma_f32_16x16x32_bf16 v[10:13], v[166:169], v[190:193], v[10:13]
	v_mfma_f32_16x16x32_bf16 v[6:9], v[158:161], v[210:213], v[6:9]
	v_mfma_f32_16x16x32_bf16 v[2:5], v[166:169], v[210:213], v[2:5]
	v_mfma_f32_16x16x32_bf16 v[46:49], v[162:165], v[178:181], v[46:49]
	v_mfma_f32_16x16x32_bf16 v[42:45], v[170:173], v[178:181], v[42:45]
	v_mfma_f32_16x16x32_bf16 v[30:33], v[162:165], v[186:189], v[30:33]
	v_mfma_f32_16x16x32_bf16 v[26:29], v[170:173], v[186:189], v[26:29]
	v_mfma_f32_16x16x32_bf16 v[14:17], v[162:165], v[206:209], v[14:17]
	v_mfma_f32_16x16x32_bf16 v[10:13], v[170:173], v[206:209], v[10:13]
	v_mfma_f32_16x16x32_bf16 v[6:9], v[162:165], v[214:217], v[6:9]
	v_mfma_f32_16x16x32_bf16 v[2:5], v[170:173], v[214:217], v[2:5]
	s_setprio 0
	s_barrier
	s_andn2_b64 vcc, exec, s[40:41]
	s_mov_b64 s[42:43], -1
	s_mov_b64 s[40:41], 0
	s_mov_b64 s[44:45], 0x100
	s_cbranch_vccnz .Lpeel_exit_pp
.LBB0_799:
	s_add_u32 s52, s14, s44
	s_addc_u32 s53, s15, s45
	s_add_u32 s48, s52, 0x100
	s_addc_u32 s49, s53, 0
	s_and_b64 s[46:47], s[42:43], exec
	s_cselect_b32 s47, s19, s49
	s_cselect_b32 s46, s77, s48
	s_add_u32 s44, s12, s44
	s_addc_u32 s45, s13, s45
	s_add_u32 s44, s44, 0x100
	s_addc_u32 s45, s45, 0
	s_add_i32 s96, 0, 0x10000
	s_and_b64 s[42:43], s[42:43], exec
	s_cselect_b32 s49, s17, s45
	s_cselect_b32 s48, s79, s44
	s_add_i32 s43, 0, 0x14000
	s_add_u32 s82, s52, 0x10080
	s_addc_u32 s83, s53, 0
	s_add_i32 s93, s96, s68
	s_add_i32 m0, s69, 0xc000
	s_add_i32 vcc_lo, s69, 0xe000
	s_add_i32 s88, s93, 0x2000
	v_add_u32_e32 v141, s96, v138
	s_add_u32 s52, s48, 0x10000
	ds_read_b128 v[142:145], v141
	ds_read_b128 v[146:149], v141 offset:1024
	ds_read_b128 v[150:153], v141 offset:2048
	ds_read_b128 v[154:157], v141 offset:3072
	v_add_u32_e32 v141, s43, v138
	s_addc_u32 s53, s49, 0
	s_add_i32 s92, s43, s68
	ds_read_b128 v[158:161], v141
	ds_read_b128 v[162:165], v141 offset:1024
	ds_read_b128 v[166:169], v141 offset:2048
	ds_read_b128 v[170:173], v141 offset:3072
	s_add_i32 s89, s92, 0x2000
	s_add_i32 s85, 0, 0x18000
	s_add_i32 s84, 0, 0x1c000
	s_add_u32 s44, s46, 0x10000
	s_addc_u32 s45, s47, 0
	s_add_i32 s81, s85, s68
	s_add_i32 s80, s81, 0x2000
	s_add_u32 s42, s48, 0x10080
	s_addc_u32 s43, s49, 0
	s_add_i32 s97, s84, s68
	s_add_i32 s96, s97, 0x2000
	v_lshl_add_u64 v[226:227], s[82:83], 0, v[130:131]
	ds_read_b128 v[174:177], v140
	ds_read_b128 v[178:181], v140 offset:1024
	ds_read_b128 v[182:185], v140 offset:2048
	ds_read_b128 v[186:189], v140 offset:3072
	ds_read_b128 v[190:193], v140 offset:4096
	ds_read_b128 v[206:209], v140 offset:5120
	ds_read_b128 v[210:213], v140 offset:6144
	ds_read_b128 v[214:217], v140 offset:7168
	global_load_lds_dwordx4 v[226:227], off
	v_lshl_add_u64 v[226:227], s[82:83], 0, v[134:135]
	s_mov_b32 m0, vcc_lo
	s_nop 0
	global_load_lds_dwordx4 v[226:227], off
	s_waitcnt vmcnt(8)
	s_waitcnt lgkmcnt(0)
	s_barrier
; #define PG8_STAGE(bufoff, gbase, voff) do { _Pragma("unroll") for (int _i = 0; _i < 2; ++_i) \
;         __builtin_amdgcn_global_load_lds((const unsigned*)((const char*)(gbase) + (voff)[_i]), (PG8_LAS unsigned*)(lds + (bufoff) + ldsw + _i * 8192), 16, 0, 0); } while (0)
; #define PG8_LDA(dst, b, h) do { _Pragma("unroll") for (int m = 0; m < 4; ++m) _Pragma("unroll") for (int k = 0; k < 2; ++k) dst[m][k] = *(const PG8_LAS bf16x8*)(lds + PG8_SA(b, h) + aoff + m * 2048 + k * 1024); } while (0)
; #define PG8_WAIT_V(n) asm volatile("s_waitcnt vmcnt(" #n ")" ::: "memory")
; #define PG8_WAIT_L(n) asm volatile("s_waitcnt lgkmcnt(" #n ")" ::: "memory")
; #define PG8_BAR __builtin_amdgcn_s_barrier()
; template <class Epi, class Sched, bool ALIGN_EPI = false, bool SP2 = false>
; __device__ __forceinline__ void gemm_phase(PG8_LAS unsigned char* lds, const Gemm g, const Sched& S, const Epi& E, const int wave_id) {
;     ...
;         for (int t = 0; t < nt; t += 2) {
;             const bool last = (t == nt - 2);
;             const char* a1 = cA + (size_t)(t + 1) * kstep;
;             const char* a2 = last ? nA : cA + (size_t)(t + 2) * kstep; const char* b2 = last ? nB : cB + (size_t)(t + 2) * kstep;
;             const char* a3 = a2 + kstep; const char* b3 = b2 + kstep;
;             if (last && has_next) S.a_ready(nxt);
;             if constexpr (SP2) {
;             PG8_LDB(B0, 0, 0); PG8_LDB(B1, 0, 1); PG8_SCHED; PG8_LDA(At, 0, 0); PG8_STAGE(PG8_SA(1, 1), a1 + hstep, voffA);
;             PG8_WAIT_V(8); PG8_WAIT_L(0); PG8_BAR; PG8_MMA(0, 0, At, B0); PG8_MMA(0, 1, At, B1); PG8_BAR; PG8_SCHED;
;             PG8_LDA(At, 0, 1); PG8_STAGE(PG8_SB(0, 0), b2, voffB); PG8_STAGE(PG8_SB(0, 1), b2 + hstep, voffB); PG8_STAGE(PG8_SA(0, 0), a2, voffA);
;             PG8_WAIT_V(8); PG8_WAIT_L(0); PG8_BAR; PG8_MMA(1, 0, At, B0); PG8_MMA(1, 1, At, B1); PG8_BAR; PG8_SCHED;
;             PG8_LDB(B0, 1, 0); PG8_LDB(B1, 1, 1); PG8_SCHED; PG8_LDA(At, 1, 0); PG8_STAGE(PG8_SA(0, 1), a2 + hstep, voffA);
;             PG8_WAIT_V(8); PG8_WAIT_L(0); PG8_BAR; PG8_MMA(0, 0, At, B0); PG8_MMA(0, 1, At, B1); PG8_BAR; PG8_SCHED;
;             PG8_LDA(At, 1, 1); PG8_STAGE(PG8_SB(1, 0), b3, voffB); PG8_STAGE(PG8_SB(1, 1), b3 + hstep, voffB); PG8_STAGE(PG8_SA(1, 0), a3, voffA);
;             PG8_WAIT_V(8); PG8_WAIT_L(0); PG8_BAR; PG8_MMA(1, 0, At, B0); PG8_MMA(1, 1, At, B1); PG8_BAR; PG8_SCHED;
	s_setprio 1
	s_waitcnt lgkmcnt(0)
	v_mfma_f32_16x16x32_bf16 v[126:129], v[142:145], v[174:177], v[126:129]
	v_mfma_f32_16x16x32_bf16 v[122:125], v[150:153], v[174:177], v[122:125]
	v_mfma_f32_16x16x32_bf16 v[118:121], v[142:145], v[182:185], v[118:121]
	v_mfma_f32_16x16x32_bf16 v[114:117], v[150:153], v[182:185], v[114:117]
	v_mfma_f32_16x16x32_bf16 v[102:105], v[142:145], v[190:193], v[102:105]
	v_mfma_f32_16x16x32_bf16 v[98:101], v[150:153], v[190:193], v[98:101]
	v_mfma_f32_16x16x32_bf16 v[86:89], v[142:145], v[210:213], v[86:89]
	v_mfma_f32_16x16x32_bf16 v[82:85], v[150:153], v[210:213], v[82:85]
	v_mfma_f32_16x16x32_bf16 v[126:129], v[146:149], v[178:181], v[126:129]
	v_mfma_f32_16x16x32_bf16 v[122:125], v[154:157], v[178:181], v[122:125]
	v_mfma_f32_16x16x32_bf16 v[118:121], v[146:149], v[186:189], v[118:121]
	v_mfma_f32_16x16x32_bf16 v[114:117], v[154:157], v[186:189], v[114:117]
	v_mfma_f32_16x16x32_bf16 v[102:105], v[146:149], v[206:209], v[102:105]
	v_mfma_f32_16x16x32_bf16 v[98:101], v[154:157], v[206:209], v[98:101]
	v_mfma_f32_16x16x32_bf16 v[86:89], v[146:149], v[214:217], v[86:89]
	v_mfma_f32_16x16x32_bf16 v[82:85], v[154:157], v[214:217], v[82:85]
	s_setprio 0
	s_setprio 1
	v_mfma_f32_16x16x32_bf16 v[110:113], v[158:161], v[174:177], v[110:113]
	v_mfma_f32_16x16x32_bf16 v[106:109], v[166:169], v[174:177], v[106:109]
	v_mfma_f32_16x16x32_bf16 v[94:97], v[158:161], v[182:185], v[94:97]
	v_mfma_f32_16x16x32_bf16 v[90:93], v[166:169], v[182:185], v[90:93]
	v_mfma_f32_16x16x32_bf16 v[78:81], v[158:161], v[190:193], v[78:81]
	v_mfma_f32_16x16x32_bf16 v[74:77], v[166:169], v[190:193], v[74:77]
	v_mfma_f32_16x16x32_bf16 v[70:73], v[158:161], v[210:213], v[70:73]
	v_mfma_f32_16x16x32_bf16 v[66:69], v[166:169], v[210:213], v[66:69]
	v_mfma_f32_16x16x32_bf16 v[110:113], v[162:165], v[178:181], v[110:113]
	v_mfma_f32_16x16x32_bf16 v[106:109], v[170:173], v[178:181], v[106:109]
	v_mfma_f32_16x16x32_bf16 v[94:97], v[162:165], v[186:189], v[94:97]
	v_mfma_f32_16x16x32_bf16 v[90:93], v[170:173], v[186:189], v[90:93]
	v_mfma_f32_16x16x32_bf16 v[78:81], v[162:165], v[206:209], v[78:81]
	v_mfma_f32_16x16x32_bf16 v[74:77], v[170:173], v[206:209], v[74:77]
	v_mfma_f32_16x16x32_bf16 v[70:73], v[162:165], v[214:217], v[70:73]
	v_mfma_f32_16x16x32_bf16 v[66:69], v[170:173], v[214:217], v[66:69]
	s_setprio 0
	s_barrier
	s_mov_b32 m0, s93
	v_lshl_add_u64 v[226:227], s[48:49], 0, v[132:133]
	ds_read_b128 v[174:177], v140 offset:16384
	ds_read_b128 v[178:181], v140 offset:17408
	ds_read_b128 v[182:185], v140 offset:18432
	ds_read_b128 v[186:189], v140 offset:19456
	ds_read_b128 v[190:193], v140 offset:20480
	ds_read_b128 v[206:209], v140 offset:21504
	ds_read_b128 v[210:213], v140 offset:22528
	ds_read_b128 v[214:217], v140 offset:23552
	global_load_lds_dwordx4 v[226:227], off
	v_lshl_add_u64 v[228:229], s[48:49], 0, v[136:137]
	s_mov_b32 m0, s88
	v_lshl_add_u64 v[230:231], s[52:53], 0, v[132:133]
	global_load_lds_dwordx4 v[228:229], off
	s_mov_b32 m0, s92
	v_lshl_add_u64 v[234:235], s[46:47], 0, v[134:135]
	global_load_lds_dwordx4 v[230:231], off
	v_lshl_add_u64 v[230:231], s[52:53], 0, v[136:137]
	s_mov_b32 m0, s89
	s_nop 0
	global_load_lds_dwordx4 v[230:231], off
	v_lshl_add_u64 v[230:231], s[46:47], 0, v[130:131]
	s_mov_b32 m0, s69
	s_nop 0
	global_load_lds_dwordx4 v[230:231], off
	s_mov_b32 m0, s70
	s_nop 0
	global_load_lds_dwordx4 v[234:235], off
	s_waitcnt vmcnt(8)
	s_waitcnt lgkmcnt(0)
	s_barrier
	s_setprio 1
	s_waitcnt lgkmcnt(0)
	v_mfma_f32_16x16x32_bf16 v[62:65], v[142:145], v[174:177], v[62:65]
	v_mfma_f32_16x16x32_bf16 v[58:61], v[150:153], v[174:177], v[58:61]
	v_mfma_f32_16x16x32_bf16 v[54:57], v[142:145], v[182:185], v[54:57]
	v_mfma_f32_16x16x32_bf16 v[50:53], v[150:153], v[182:185], v[50:53]
	v_mfma_f32_16x16x32_bf16 v[38:41], v[142:145], v[190:193], v[38:41]
	v_mfma_f32_16x16x32_bf16 v[34:37], v[150:153], v[190:193], v[34:37]
	v_mfma_f32_16x16x32_bf16 v[22:25], v[142:145], v[210:213], v[22:25]
	v_mfma_f32_16x16x32_bf16 v[18:21], v[150:153], v[210:213], v[18:21]
	v_mfma_f32_16x16x32_bf16 v[62:65], v[146:149], v[178:181], v[62:65]
	v_mfma_f32_16x16x32_bf16 v[58:61], v[154:157], v[178:181], v[58:61]
	v_mfma_f32_16x16x32_bf16 v[54:57], v[146:149], v[186:189], v[54:57]
	v_mfma_f32_16x16x32_bf16 v[50:53], v[154:157], v[186:189], v[50:53]
	v_mfma_f32_16x16x32_bf16 v[38:41], v[146:149], v[206:209], v[38:41]
	v_mfma_f32_16x16x32_bf16 v[34:37], v[154:157], v[206:209], v[34:37]
	v_mfma_f32_16x16x32_bf16 v[22:25], v[146:149], v[214:217], v[22:25]
	v_mfma_f32_16x16x32_bf16 v[18:21], v[154:157], v[214:217], v[18:21]
	s_setprio 0
	s_setprio 1
	v_mfma_f32_16x16x32_bf16 v[46:49], v[158:161], v[174:177], v[46:49]
	v_mfma_f32_16x16x32_bf16 v[42:45], v[166:169], v[174:177], v[42:45]
	v_mfma_f32_16x16x32_bf16 v[30:33], v[158:161], v[182:185], v[30:33]
	v_mfma_f32_16x16x32_bf16 v[26:29], v[166:169], v[182:185], v[26:29]
	v_mfma_f32_16x16x32_bf16 v[14:17], v[158:161], v[190:193], v[14:17]
	v_mfma_f32_16x16x32_bf16 v[10:13], v[166:169], v[190:193], v[10:13]
	v_mfma_f32_16x16x32_bf16 v[6:9], v[158:161], v[210:213], v[6:9]
	v_mfma_f32_16x16x32_bf16 v[2:5], v[166:169], v[210:213], v[2:5]
	v_mfma_f32_16x16x32_bf16 v[46:49], v[162:165], v[178:181], v[46:49]
	v_mfma_f32_16x16x32_bf16 v[42:45], v[170:173], v[178:181], v[42:45]
	v_mfma_f32_16x16x32_bf16 v[30:33], v[162:165], v[186:189], v[30:33]
	v_mfma_f32_16x16x32_bf16 v[26:29], v[170:173], v[186:189], v[26:29]
	v_mfma_f32_16x16x32_bf16 v[14:17], v[162:165], v[206:209], v[14:17]
	v_mfma_f32_16x16x32_bf16 v[10:13], v[170:173], v[206:209], v[10:13]
	v_mfma_f32_16x16x32_bf16 v[6:9], v[162:165], v[214:217], v[6:9]
	v_mfma_f32_16x16x32_bf16 v[2:5], v[170:173], v[214:217], v[2:5]
	s_setprio 0
	s_barrier
; #define PG8_STAGE(bufoff, gbase, voff) do { _Pragma("unroll") for (int _i = 0; _i < 2; ++_i) \
;         __builtin_amdgcn_global_load_lds((const unsigned*)((const char*)(gbase) + (voff)[_i]), (PG8_LAS unsigned*)(lds + (bufoff) + ldsw + _i * 8192), 16, 0, 0); } while (0)
; #define PG8_LDA(dst, b, h) do { _Pragma("unroll") for (int m = 0; m < 4; ++m) _Pragma("unroll") for (int k = 0; k < 2; ++k) dst[m][k] = *(const PG8_LAS bf16x8*)(lds + PG8_SA(b, h) + aoff + m * 2048 + k * 1024); } while (0)
; #define PG8_WAIT_V(n) asm volatile("s_waitcnt vmcnt(" #n ")" ::: "memory")
; #define PG8_WAIT_L(n) asm volatile("s_waitcnt lgkmcnt(" #n ")" ::: "memory")
; #define PG8_BAR __builtin_amdgcn_s_barrier()
; template <class Epi, class Sched, bool ALIGN_EPI = false, bool SP2 = false>
; __device__ __forceinline__ void gemm_phase(PG8_LAS unsigned char* lds, const Gemm g, const Sched& S, const Epi& E, const int wave_id) {
;     ...
;         for (int t = 0; t < nt; t += 2) {
;             const bool last = (t == nt - 2);
;             const char* a1 = cA + (size_t)(t + 1) * kstep;
;             const char* a2 = last ? nA : cA + (size_t)(t + 2) * kstep; const char* b2 = last ? nB : cB + (size_t)(t + 2) * kstep;
;             const char* a3 = a2 + kstep; const char* b3 = b2 + kstep;
;             if (last && has_next) S.a_ready(nxt);
;             if constexpr (SP2) {
;             PG8_LDB(B0, 0, 0); PG8_LDB(B1, 0, 1); PG8_SCHED; PG8_LDA(At, 0, 0); PG8_STAGE(PG8_SA(1, 1), a1 + hstep, voffA);
;             PG8_WAIT_V(8); PG8_WAIT_L(0); PG8_BAR; PG8_MMA(0, 0, At, B0); PG8_MMA(0, 1, At, B1); PG8_BAR; PG8_SCHED;
;             PG8_LDA(At, 0, 1); PG8_STAGE(PG8_SB(0, 0), b2, voffB); PG8_STAGE(PG8_SB(0, 1), b2 + hstep, voffB); PG8_STAGE(PG8_SA(0, 0), a2, voffA);
;             PG8_WAIT_V(8); PG8_WAIT_L(0); PG8_BAR; PG8_MMA(1, 0, At, B0); PG8_MMA(1, 1, At, B1); PG8_BAR; PG8_SCHED;
;             PG8_LDB(B0, 1, 0); PG8_LDB(B1, 1, 1); PG8_SCHED; PG8_LDA(At, 1, 0); PG8_STAGE(PG8_SA(0, 1), a2 + hstep, voffA);
;             PG8_WAIT_V(8); PG8_WAIT_L(0); PG8_BAR; PG8_MMA(0, 0, At, B0); PG8_MMA(0, 1, At, B1); PG8_BAR; PG8_SCHED;
;             PG8_LDA(At, 1, 1); PG8_STAGE(PG8_SB(1, 0), b3, voffB); PG8_STAGE(PG8_SB(1, 1), b3 + hstep, voffB); PG8_STAGE(PG8_SA(1, 0), a3, voffA);
;             PG8_WAIT_V(8); PG8_WAIT_L(0); PG8_BAR; PG8_MMA(1, 0, At, B0); PG8_MMA(1, 1, At, B1); PG8_BAR; PG8_SCHED;
	v_add_u32_e32 v141, s85, v138
	ds_read_b128 v[142:145], v141
	ds_read_b128 v[146:149], v141 offset:1024
	ds_read_b128 v[150:153], v141 offset:2048
	ds_read_b128 v[154:157], v141 offset:3072
	v_add_u32_e32 v141, s84, v138
	ds_read_b128 v[158:161], v141
	ds_read_b128 v[162:165], v141 offset:1024
	ds_read_b128 v[166:169], v141 offset:2048
	ds_read_b128 v[170:173], v141 offset:3072
	s_mov_b32 m0, s71
	v_lshl_add_u64 v[236:237], s[44:45], 0, v[130:131]
	ds_read_b128 v[174:177], v140 offset:32768
	ds_read_b128 v[178:181], v140 offset:33792
	ds_read_b128 v[182:185], v140 offset:34816
	ds_read_b128 v[186:189], v140 offset:35840
	ds_read_b128 v[190:193], v140 offset:36864
	ds_read_b128 v[206:209], v140 offset:37888
	ds_read_b128 v[210:213], v140 offset:38912
	ds_read_b128 v[214:217], v140 offset:39936
	global_load_lds_dwordx4 v[236:237], off
	v_lshl_add_u64 v[236:237], s[44:45], 0, v[134:135]
	s_mov_b32 m0, s72
	s_nop 0
	global_load_lds_dwordx4 v[236:237], off
	s_waitcnt vmcnt(8)
	s_waitcnt lgkmcnt(0)
	s_barrier
	s_setprio 1
	s_waitcnt lgkmcnt(0)
	v_mfma_f32_16x16x32_bf16 v[126:129], v[142:145], v[174:177], v[126:129]
	v_mfma_f32_16x16x32_bf16 v[122:125], v[150:153], v[174:177], v[122:125]
	v_mfma_f32_16x16x32_bf16 v[118:121], v[142:145], v[182:185], v[118:121]
	v_mfma_f32_16x16x32_bf16 v[114:117], v[150:153], v[182:185], v[114:117]
	v_mfma_f32_16x16x32_bf16 v[102:105], v[142:145], v[190:193], v[102:105]
	v_mfma_f32_16x16x32_bf16 v[98:101], v[150:153], v[190:193], v[98:101]
	v_mfma_f32_16x16x32_bf16 v[86:89], v[142:145], v[210:213], v[86:89]
	v_mfma_f32_16x16x32_bf16 v[82:85], v[150:153], v[210:213], v[82:85]
	v_mfma_f32_16x16x32_bf16 v[126:129], v[146:149], v[178:181], v[126:129]
	v_mfma_f32_16x16x32_bf16 v[122:125], v[154:157], v[178:181], v[122:125]
	v_mfma_f32_16x16x32_bf16 v[118:121], v[146:149], v[186:189], v[118:121]
	v_mfma_f32_16x16x32_bf16 v[114:117], v[154:157], v[186:189], v[114:117]
	v_mfma_f32_16x16x32_bf16 v[102:105], v[146:149], v[206:209], v[102:105]
	v_mfma_f32_16x16x32_bf16 v[98:101], v[154:157], v[206:209], v[98:101]
	v_mfma_f32_16x16x32_bf16 v[86:89], v[146:149], v[214:217], v[86:89]
	v_mfma_f32_16x16x32_bf16 v[82:85], v[154:157], v[214:217], v[82:85]
	s_setprio 0
	s_setprio 1
	v_mfma_f32_16x16x32_bf16 v[110:113], v[158:161], v[174:177], v[110:113]
	v_mfma_f32_16x16x32_bf16 v[106:109], v[166:169], v[174:177], v[106:109]
	v_mfma_f32_16x16x32_bf16 v[94:97], v[158:161], v[182:185], v[94:97]
	v_mfma_f32_16x16x32_bf16 v[90:93], v[166:169], v[182:185], v[90:93]
	v_mfma_f32_16x16x32_bf16 v[78:81], v[158:161], v[190:193], v[78:81]
	v_mfma_f32_16x16x32_bf16 v[74:77], v[166:169], v[190:193], v[74:77]
	v_mfma_f32_16x16x32_bf16 v[70:73], v[158:161], v[210:213], v[70:73]
	v_mfma_f32_16x16x32_bf16 v[66:69], v[166:169], v[210:213], v[66:69]
	v_mfma_f32_16x16x32_bf16 v[110:113], v[162:165], v[178:181], v[110:113]
	v_mfma_f32_16x16x32_bf16 v[106:109], v[170:173], v[178:181], v[106:109]
	v_mfma_f32_16x16x32_bf16 v[94:97], v[162:165], v[186:189], v[94:97]
	v_mfma_f32_16x16x32_bf16 v[90:93], v[170:173], v[186:189], v[90:93]
	v_mfma_f32_16x16x32_bf16 v[78:81], v[162:165], v[206:209], v[78:81]
	v_mfma_f32_16x16x32_bf16 v[74:77], v[170:173], v[206:209], v[74:77]
	v_mfma_f32_16x16x32_bf16 v[70:73], v[162:165], v[214:217], v[70:73]
	v_mfma_f32_16x16x32_bf16 v[66:69], v[170:173], v[214:217], v[66:69]
	s_setprio 0
	s_barrier
	s_mov_b32 m0, s81
	v_lshl_add_u64 v[226:227], v[226:227], 0, s[30:31]
	ds_read_b128 v[174:177], v140 offset:49152
	ds_read_b128 v[178:181], v140 offset:50176
	ds_read_b128 v[182:185], v140 offset:51200
	ds_read_b128 v[186:189], v140 offset:52224
	ds_read_b128 v[190:193], v140 offset:53248
	ds_read_b128 v[206:209], v140 offset:54272
	ds_read_b128 v[210:213], v140 offset:55296
	ds_read_b128 v[214:217], v140 offset:56320
	global_load_lds_dwordx4 v[226:227], off
	v_lshl_add_u64 v[226:227], v[228:229], 0, s[30:31]
	s_mov_b32 m0, s80
	s_nop 0
	global_load_lds_dwordx4 v[226:227], off
	v_lshl_add_u64 v[226:227], s[42:43], 0, v[132:133]
	s_mov_b32 m0, s97
	s_nop 0
	global_load_lds_dwordx4 v[226:227], off
	v_lshl_add_u64 v[226:227], s[42:43], 0, v[136:137]
	s_mov_b32 m0, s96
	s_nop 0
	global_load_lds_dwordx4 v[226:227], off
	v_lshl_add_u64 v[226:227], v[230:231], 0, s[30:31]
	s_mov_b32 m0, s73
	s_nop 0
	global_load_lds_dwordx4 v[226:227], off
	v_lshl_add_u64 v[226:227], v[234:235], 0, s[30:31]
	s_mov_b32 m0, s74
	s_nop 0
	global_load_lds_dwordx4 v[226:227], off
	s_waitcnt vmcnt(8)
	s_waitcnt lgkmcnt(0)
	s_barrier
	s_setprio 1
	s_waitcnt lgkmcnt(0)
	v_mfma_f32_16x16x32_bf16 v[62:65], v[142:145], v[174:177], v[62:65]
	v_mfma_f32_16x16x32_bf16 v[58:61], v[150:153], v[174:177], v[58:61]
	v_mfma_f32_16x16x32_bf16 v[54:57], v[142:145], v[182:185], v[54:57]
	v_mfma_f32_16x16x32_bf16 v[50:53], v[150:153], v[182:185], v[50:53]
	v_mfma_f32_16x16x32_bf16 v[38:41], v[142:145], v[190:193], v[38:41]
	v_mfma_f32_16x16x32_bf16 v[34:37], v[150:153], v[190:193], v[34:37]
	v_mfma_f32_16x16x32_bf16 v[22:25], v[142:145], v[210:213], v[22:25]
	v_mfma_f32_16x16x32_bf16 v[18:21], v[150:153], v[210:213], v[18:21]
	v_mfma_f32_16x16x32_bf16 v[62:65], v[146:149], v[178:181], v[62:65]
	v_mfma_f32_16x16x32_bf16 v[58:61], v[154:157], v[178:181], v[58:61]
	v_mfma_f32_16x16x32_bf16 v[54:57], v[146:149], v[186:189], v[54:57]
	v_mfma_f32_16x16x32_bf16 v[50:53], v[154:157], v[186:189], v[50:53]
	v_mfma_f32_16x16x32_bf16 v[38:41], v[146:149], v[206:209], v[38:41]
	v_mfma_f32_16x16x32_bf16 v[34:37], v[154:157], v[206:209], v[34:37]
	v_mfma_f32_16x16x32_bf16 v[22:25], v[146:149], v[214:217], v[22:25]
	v_mfma_f32_16x16x32_bf16 v[18:21], v[154:157], v[214:217], v[18:21]
	s_setprio 0
	s_setprio 1
	v_mfma_f32_16x16x32_bf16 v[46:49], v[158:161], v[174:177], v[46:49]
	v_mfma_f32_16x16x32_bf16 v[42:45], v[166:169], v[174:177], v[42:45]
	v_mfma_f32_16x16x32_bf16 v[30:33], v[158:161], v[182:185], v[30:33]
	v_mfma_f32_16x16x32_bf16 v[26:29], v[166:169], v[182:185], v[26:29]
	v_mfma_f32_16x16x32_bf16 v[14:17], v[158:161], v[190:193], v[14:17]
	v_mfma_f32_16x16x32_bf16 v[10:13], v[166:169], v[190:193], v[10:13]
	v_mfma_f32_16x16x32_bf16 v[6:9], v[158:161], v[210:213], v[6:9]
	v_mfma_f32_16x16x32_bf16 v[2:5], v[166:169], v[210:213], v[2:5]
	v_mfma_f32_16x16x32_bf16 v[46:49], v[162:165], v[178:181], v[46:49]
	v_mfma_f32_16x16x32_bf16 v[42:45], v[170:173], v[178:181], v[42:45]
	v_mfma_f32_16x16x32_bf16 v[30:33], v[162:165], v[186:189], v[30:33]
	v_mfma_f32_16x16x32_bf16 v[26:29], v[170:173], v[186:189], v[26:29]
	v_mfma_f32_16x16x32_bf16 v[14:17], v[162:165], v[206:209], v[14:17]
	v_mfma_f32_16x16x32_bf16 v[10:13], v[170:173], v[206:209], v[10:13]
	v_mfma_f32_16x16x32_bf16 v[6:9], v[162:165], v[214:217], v[6:9]
	v_mfma_f32_16x16x32_bf16 v[2:5], v[170:173], v[214:217], v[2:5]
	s_setprio 0
	s_barrier
	s_andn2_b64 vcc, exec, s[40:41]
	s_mov_b64 s[42:43], -1
	s_mov_b64 s[40:41], 0
	s_mov_b64 s[44:45], 0x100
	s_cbranch_vccz .LBB0_799

;     __host__ __device__ bool next(int i, Unit& u) const { const bool ok = StaticOrder::next(i, u); u.lm = 0; u.ln = 0; return ok; }
; #define PG8_STAGE(bufoff, gbase, voff) do { _Pragma("unroll") for (int _i = 0; _i < 2; ++_i) \
;         __builtin_amdgcn_global_load_lds((const unsigned*)((const char*)(gbase) + (voff)[_i]), (PG8_LAS unsigned*)(lds + (bufoff) + ldsw + _i * 8192), 16, 0, 0); } while (0)
; #define PG8_LDA(dst, b, h) do { _Pragma("unroll") for (int m = 0; m < 4; ++m) _Pragma("unroll") for (int k = 0; k < 2; ++k) dst[m][k] = *(const PG8_LAS bf16x8*)(lds + PG8_SA(b, h) + aoff + m * 2048 + k * 1024); } while (0)
; #define PG8_LDB(dst, b, h) do { _Pragma("unroll") for (int n = 0; n < 2; ++n) _Pragma("unroll") for (int k = 0; k < 2; ++k) dst[n][k] = *(const PG8_LAS bf16x8*)(lds + PG8_SB(b, h) + boff + n * 2048 + k * 1024); } while (0)
; #define PG8_WAIT_V(n) asm volatile("s_waitcnt vmcnt(" #n ")" ::: "memory")
; #define PG8_BAR __builtin_amdgcn_s_barrier()
; template <class Epi, class Sched, bool ALIGN_EPI = false, bool SP2 = false>
; __device__ __forceinline__ void gemm_phase(PG8_LAS unsigned char* lds, const Gemm g, const Sched& S, const Epi& E, const int wave_id) {
;     ...
;         const bool has_next = S.next(ui + 1, nxt);
;         const char* nA = has_next ? (const char*)g.A + (size_t)nxt.lm * tstep : cA; const char* nB = has_next ? (const char*)g.Bt + (size_t)nxt.ln * tstep : cB;
; #pragma unroll 1
;         for (int t = 0; t < nt; t += 2) {
;             const bool last = (t == nt - 2);
;             const char* a1 = cA + (size_t)(t + 1) * kstep;
;             const char* a2 = last ? nA : cA + (size_t)(t + 2) * kstep; const char* b2 = last ? nB : cB + (size_t)(t + 2) * kstep;
;             const char* a3 = a2 + kstep; const char* b3 = b2 + kstep;
;             if (last && has_next) S.a_ready(nxt);
;             if constexpr (SP2) {
;             PG8_LDB(B0, 0, 0); PG8_LDB(B1, 0, 1); PG8_SCHED; PG8_LDA(At, 0, 0); PG8_STAGE(PG8_SA(1, 1), a1 + hstep, voffA);
;             PG8_WAIT_V(8); PG8_WAIT_L(0); PG8_BAR; PG8_MMA(0, 0, At, B0); PG8_MMA(0, 1, At, B1); PG8_BAR; PG8_SCHED;
;             PG8_LDA(At, 0, 1); PG8_STAGE(PG8_SB(0, 0), b2, voffB); PG8_STAGE(PG8_SB(0, 1), b2 + hstep, voffB); PG8_STAGE(PG8_SA(0, 0), a2, voffA);
;             PG8_WAIT_V(8); PG8_WAIT_L(0); PG8_BAR; PG8_MMA(1, 0, At, B0); PG8_MMA(1, 1, At, B1); PG8_BAR; PG8_SCHED;
.LBB0_903:
	s_ashr_i32 s21, s20, 31
	s_lshl_b64 s[42:43], s[20:21], 20
	s_add_u32 s42, s8, s42
	s_addc_u32 s43, s9, s43
	s_and_b64 s[44:45], s[40:41], exec
	s_cselect_b32 s21, s43, s47
	s_cselect_b32 s49, s42, s46
	s_ashr_i32 s19, s18, 31
	s_lshl_b64 s[44:45], s[18:19], 20
	s_add_u32 s44, s65, s44
	s_addc_u32 s45, s68, s45
	s_and_b64 s[80:81], s[40:41], exec
	s_cselect_b32 s19, s45, s53
	s_cselect_b32 s79, s44, s52
	s_add_u32 s46, s46, 0x80080
	s_addc_u32 s47, s47, 0
	s_add_u32 s80, s52, 0x100
	s_addc_u32 s81, s53, 0
	s_mov_b32 s84, -2
	v_add_u32_e32 v226, 0x10000, v237
	s_add_u32 s52, s46, 0xfff80080
	s_addc_u32 s53, s47, -1
	s_add_i32 s85, 0, 0x10000
	s_cmp_eq_u32 s84, 28
	s_cselect_b32 s83, s21, s53
	s_cselect_b32 s82, s49, s52
	s_cselect_b32 s53, s19, s81
	s_cselect_b32 s52, s79, s80
	s_add_i32 s92, 0, 0x14000
	s_add_i32 m0, s70, 0xc000
	s_nop 0
	global_load_lds_dwordx4 v214, s[46:47]
	ds_read_b128 v[114:117], v226
	ds_read_b128 v[118:121], v226 offset:1024
	ds_read_b128 v[130:133], v226 offset:2048
	ds_read_b128 v[134:137], v226 offset:3072
	ds_read_b128 v[138:141], v226 offset:16384
	ds_read_b128 v[142:145], v226 offset:17408
	ds_read_b128 v[146:149], v226 offset:18432
	ds_read_b128 v[150:153], v226 offset:19456
	s_add_i32 m0, s70, 0xe000
	s_nop 0
	global_load_lds_dwordx4 v216, s[46:47]
	ds_read_b128 v[162:165], v244
	ds_read_b128 v[166:169], v244 offset:1024
	ds_read_b128 v[170:173], v244 offset:2048
	ds_read_b128 v[174:177], v244 offset:3072
	ds_read_b128 v[178:181], v244 offset:4096
	ds_read_b128 v[182:185], v244 offset:5120
	ds_read_b128 v[186:189], v244 offset:6144
	ds_read_b128 v[190:193], v244 offset:7168
	s_waitcnt vmcnt(8)
	s_waitcnt lgkmcnt(0)
	s_barrier
	s_setprio 1
	s_waitcnt lgkmcnt(0)
	v_mfma_f32_16x16x32_bf16 v[158:161], v[114:117], v[162:165], 0
	v_mfma_f32_16x16x32_bf16 v[154:157], v[130:133], v[162:165], 0
	v_mfma_f32_16x16x32_bf16 v[110:113], v[114:117], v[170:173], 0
	v_mfma_f32_16x16x32_bf16 v[106:109], v[130:133], v[170:173], 0
	v_mfma_f32_16x16x32_bf16 v[94:97], v[114:117], v[178:181], 0
	v_mfma_f32_16x16x32_bf16 v[90:93], v[130:133], v[178:181], 0
	v_mfma_f32_16x16x32_bf16 v[78:81], v[114:117], v[186:189], 0
	v_mfma_f32_16x16x32_bf16 v[74:77], v[130:133], v[186:189], 0
	v_mfma_f32_16x16x32_bf16 v[158:161], v[118:121], v[166:169], v[158:161]
	v_mfma_f32_16x16x32_bf16 v[154:157], v[134:137], v[166:169], v[154:157]
	v_mfma_f32_16x16x32_bf16 v[110:113], v[118:121], v[174:177], v[110:113]
	v_mfma_f32_16x16x32_bf16 v[106:109], v[134:137], v[174:177], v[106:109]
	v_mfma_f32_16x16x32_bf16 v[94:97], v[118:121], v[182:185], v[94:97]
	v_mfma_f32_16x16x32_bf16 v[90:93], v[134:137], v[182:185], v[90:93]
	v_mfma_f32_16x16x32_bf16 v[78:81], v[118:121], v[190:193], v[78:81]
	v_mfma_f32_16x16x32_bf16 v[74:77], v[134:137], v[190:193], v[74:77]
	s_setprio 0
	s_setprio 1
	v_mfma_f32_16x16x32_bf16 v[126:129], v[138:141], v[162:165], 0
	v_mfma_f32_16x16x32_bf16 v[122:125], v[146:149], v[162:165], 0
	v_mfma_f32_16x16x32_bf16 v[102:105], v[138:141], v[170:173], 0
	v_mfma_f32_16x16x32_bf16 v[98:101], v[146:149], v[170:173], 0
	v_mfma_f32_16x16x32_bf16 v[86:89], v[138:141], v[178:181], 0
	v_mfma_f32_16x16x32_bf16 v[82:85], v[146:149], v[178:181], 0
	v_mfma_f32_16x16x32_bf16 v[70:73], v[138:141], v[186:189], 0
	v_mfma_f32_16x16x32_bf16 v[66:69], v[146:149], v[186:189], 0
	v_mfma_f32_16x16x32_bf16 v[126:129], v[142:145], v[166:169], v[126:129]
	v_mfma_f32_16x16x32_bf16 v[122:125], v[150:153], v[166:169], v[122:125]
	v_mfma_f32_16x16x32_bf16 v[102:105], v[142:145], v[174:177], v[102:105]
	v_mfma_f32_16x16x32_bf16 v[98:101], v[150:153], v[174:177], v[98:101]
	v_mfma_f32_16x16x32_bf16 v[86:89], v[142:145], v[182:185], v[86:89]
	v_mfma_f32_16x16x32_bf16 v[82:85], v[150:153], v[182:185], v[82:85]
	v_mfma_f32_16x16x32_bf16 v[70:73], v[142:145], v[190:193], v[70:73]
	v_mfma_f32_16x16x32_bf16 v[66:69], v[150:153], v[190:193], v[66:69]
	s_setprio 0
	s_barrier
	s_add_i32 s85, s85, s69
	s_mov_b32 m0, s85
	s_nop 0
	global_load_lds_dwordx4 v208, s[52:53]
	ds_read_b128 v[162:165], v244 offset:16384
	ds_read_b128 v[166:169], v244 offset:17408
	s_add_i32 m0, s85, 0x2000
	s_add_u32 s88, s52, 0x80000
	s_addc_u32 s89, s53, 0
	s_add_i32 s85, s92, s69
	global_load_lds_dwordx4 v212, s[52:53]
	ds_read_b128 v[170:173], v244 offset:18432
	ds_read_b128 v[174:177], v244 offset:19456
	s_mov_b32 m0, s85
	s_nop 0
	global_load_lds_dwordx4 v208, s[88:89]
	ds_read_b128 v[178:181], v244 offset:20480
	ds_read_b128 v[182:185], v244 offset:21504
	s_add_i32 m0, s85, 0x2000
	s_nop 0
	global_load_lds_dwordx4 v212, s[88:89]
	ds_read_b128 v[186:189], v244 offset:22528
	ds_read_b128 v[190:193], v244 offset:23552
	s_mov_b32 m0, s70
	s_nop 0
	global_load_lds_dwordx4 v206, s[82:83]
	s_mov_b32 m0, s71
	s_nop 0
	global_load_lds_dwordx4 v210, s[82:83]
	s_waitcnt vmcnt(8)
	s_waitcnt lgkmcnt(0)
	s_barrier
; #define PG8_STAGE(bufoff, gbase, voff) do { _Pragma("unroll") for (int _i = 0; _i < 2; ++_i) \
;         __builtin_amdgcn_global_load_lds((const unsigned*)((const char*)(gbase) + (voff)[_i]), (PG8_LAS unsigned*)(lds + (bufoff) + ldsw + _i * 8192), 16, 0, 0); } while (0)
; #define PG8_LDA(dst, b, h) do { _Pragma("unroll") for (int m = 0; m < 4; ++m) _Pragma("unroll") for (int k = 0; k < 2; ++k) dst[m][k] = *(const PG8_LAS bf16x8*)(lds + PG8_SA(b, h) + aoff + m * 2048 + k * 1024); } while (0)
; #define PG8_LDB(dst, b, h) do { _Pragma("unroll") for (int n = 0; n < 2; ++n) _Pragma("unroll") for (int k = 0; k < 2; ++k) dst[n][k] = *(const PG8_LAS bf16x8*)(lds + PG8_SB(b, h) + boff + n * 2048 + k * 1024); } while (0)
; #define PG8_MMA(ai, bj, At, Bt) do { __builtin_amdgcn_s_setprio(1); _Pragma("unroll") for (int m = 0; m < 4; ++m) _Pragma("unroll") for (int n = 0; n < 2; ++n) _Pragma("unroll") for (int k = 0; k < 2; ++k) \
;         acc[ai][bj][m][n] = __builtin_amdgcn_mfma_f32_16x16x32_bf16(Bt[n][k], At[m][k], acc[ai][bj][m][n], 0, 0, 0); __builtin_amdgcn_s_setprio(0); } while (0)
; #define PG8_WAIT_V(n) asm volatile("s_waitcnt vmcnt(" #n ")" ::: "memory")
; #define PG8_WAIT_L(n) asm volatile("s_waitcnt lgkmcnt(" #n ")" ::: "memory")
; #define PG8_BAR __builtin_amdgcn_s_barrier()
; #define PG8_SCHED __builtin_amdgcn_sched_barrier(0)
; template <class Epi, class Sched, bool ALIGN_EPI = false, bool SP2 = false>
; __device__ __forceinline__ void gemm_phase(PG8_LAS unsigned char* lds, const Gemm g, const Sched& S, const Epi& E, const int wave_id) {
;     ...
;             PG8_WAIT_V(8); PG8_WAIT_L(0); PG8_BAR; PG8_MMA(1, 0, At, B0); PG8_MMA(1, 1, At, B1); PG8_BAR; PG8_SCHED;
;             PG8_LDB(B0, 1, 0); PG8_LDB(B1, 1, 1); PG8_SCHED; PG8_LDA(At, 1, 0); PG8_STAGE(PG8_SA(0, 1), a2 + hstep, voffA);
;             PG8_WAIT_V(8); PG8_WAIT_L(0); PG8_BAR; PG8_MMA(0, 0, At, B0); PG8_MMA(0, 1, At, B1); PG8_BAR; PG8_SCHED;
;             PG8_LDA(At, 1, 1); PG8_STAGE(PG8_SB(1, 0), b3, voffB); PG8_STAGE(PG8_SB(1, 1), b3 + hstep, voffB); PG8_STAGE(PG8_SA(1, 0), a3, voffA);
;             PG8_WAIT_V(8); PG8_WAIT_L(0); PG8_BAR; PG8_MMA(1, 0, At, B0); PG8_MMA(1, 1, At, B1); PG8_BAR; PG8_SCHED;
	s_setprio 1
	s_waitcnt lgkmcnt(0)
	v_mfma_f32_16x16x32_bf16 v[62:65], v[114:117], v[162:165], 0
	v_mfma_f32_16x16x32_bf16 v[58:61], v[130:133], v[162:165], 0
	v_mfma_f32_16x16x32_bf16 v[46:49], v[114:117], v[170:173], 0
	v_mfma_f32_16x16x32_bf16 v[42:45], v[130:133], v[170:173], 0
	v_mfma_f32_16x16x32_bf16 v[30:33], v[114:117], v[178:181], 0
	v_mfma_f32_16x16x32_bf16 v[26:29], v[130:133], v[178:181], 0
	v_mfma_f32_16x16x32_bf16 v[14:17], v[114:117], v[186:189], 0
	v_mfma_f32_16x16x32_bf16 v[10:13], v[130:133], v[186:189], 0
	v_mfma_f32_16x16x32_bf16 v[62:65], v[118:121], v[166:169], v[62:65]
	v_mfma_f32_16x16x32_bf16 v[58:61], v[134:137], v[166:169], v[58:61]
	v_mfma_f32_16x16x32_bf16 v[46:49], v[118:121], v[174:177], v[46:49]
	v_mfma_f32_16x16x32_bf16 v[42:45], v[134:137], v[174:177], v[42:45]
	v_mfma_f32_16x16x32_bf16 v[30:33], v[118:121], v[182:185], v[30:33]
	v_mfma_f32_16x16x32_bf16 v[26:29], v[134:137], v[182:185], v[26:29]
	v_mfma_f32_16x16x32_bf16 v[14:17], v[118:121], v[190:193], v[14:17]
	v_mfma_f32_16x16x32_bf16 v[10:13], v[134:137], v[190:193], v[10:13]
	s_setprio 0
	s_setprio 1
	v_mfma_f32_16x16x32_bf16 v[54:57], v[138:141], v[162:165], 0
	v_mfma_f32_16x16x32_bf16 v[50:53], v[146:149], v[162:165], 0
	v_mfma_f32_16x16x32_bf16 v[38:41], v[138:141], v[170:173], 0
	v_mfma_f32_16x16x32_bf16 v[34:37], v[146:149], v[170:173], 0
	v_mfma_f32_16x16x32_bf16 v[22:25], v[138:141], v[178:181], 0
	v_mfma_f32_16x16x32_bf16 v[18:21], v[146:149], v[178:181], 0
	v_mfma_f32_16x16x32_bf16 v[6:9], v[138:141], v[186:189], 0
	v_mfma_f32_16x16x32_bf16 v[2:5], v[146:149], v[186:189], 0
	v_mfma_f32_16x16x32_bf16 v[54:57], v[142:145], v[166:169], v[54:57]
	v_mfma_f32_16x16x32_bf16 v[50:53], v[150:153], v[166:169], v[50:53]
	v_mfma_f32_16x16x32_bf16 v[38:41], v[142:145], v[174:177], v[38:41]
	v_mfma_f32_16x16x32_bf16 v[34:37], v[150:153], v[174:177], v[34:37]
	v_mfma_f32_16x16x32_bf16 v[22:25], v[142:145], v[182:185], v[22:25]
	v_mfma_f32_16x16x32_bf16 v[18:21], v[150:153], v[182:185], v[18:21]
	v_mfma_f32_16x16x32_bf16 v[6:9], v[142:145], v[190:193], v[6:9]
	v_mfma_f32_16x16x32_bf16 v[2:5], v[150:153], v[190:193], v[2:5]
	s_setprio 0
	s_barrier
	s_add_i32 s85, 0, 0x18000
	s_add_i32 s88, 0, 0x1c000
	s_add_u32 s82, s82, 0x80000
	s_addc_u32 s83, s83, 0
	s_mov_b32 m0, s72
	s_nop 0
	global_load_lds_dwordx4 v206, s[82:83]
	ds_read_b128 v[114:117], v226 offset:32768
	ds_read_b128 v[118:121], v226 offset:33792
	ds_read_b128 v[130:133], v226 offset:34816
	ds_read_b128 v[134:137], v226 offset:35840
	ds_read_b128 v[138:141], v226 offset:49152
	ds_read_b128 v[142:145], v226 offset:50176
	ds_read_b128 v[146:149], v226 offset:51200
	ds_read_b128 v[150:153], v226 offset:52224
	s_mov_b32 m0, s73
	s_nop 0
	global_load_lds_dwordx4 v210, s[82:83]
	ds_read_b128 v[162:165], v244 offset:32768
	ds_read_b128 v[166:169], v244 offset:33792
	ds_read_b128 v[170:173], v244 offset:34816
	ds_read_b128 v[174:177], v244 offset:35840
	ds_read_b128 v[178:181], v244 offset:36864
	ds_read_b128 v[182:185], v244 offset:37888
	ds_read_b128 v[186:189], v244 offset:38912
	ds_read_b128 v[190:193], v244 offset:39936
	s_waitcnt vmcnt(8)
	s_waitcnt lgkmcnt(0)
	s_barrier
	s_setprio 1
	s_waitcnt lgkmcnt(0)
	v_mfma_f32_16x16x32_bf16 v[158:161], v[114:117], v[162:165], v[158:161]
	v_mfma_f32_16x16x32_bf16 v[154:157], v[130:133], v[162:165], v[154:157]
	v_mfma_f32_16x16x32_bf16 v[110:113], v[114:117], v[170:173], v[110:113]
	v_mfma_f32_16x16x32_bf16 v[106:109], v[130:133], v[170:173], v[106:109]
	v_mfma_f32_16x16x32_bf16 v[94:97], v[114:117], v[178:181], v[94:97]
	v_mfma_f32_16x16x32_bf16 v[90:93], v[130:133], v[178:181], v[90:93]
	v_mfma_f32_16x16x32_bf16 v[78:81], v[114:117], v[186:189], v[78:81]
	v_mfma_f32_16x16x32_bf16 v[74:77], v[130:133], v[186:189], v[74:77]
	v_mfma_f32_16x16x32_bf16 v[158:161], v[118:121], v[166:169], v[158:161]
	v_mfma_f32_16x16x32_bf16 v[154:157], v[134:137], v[166:169], v[154:157]
	v_mfma_f32_16x16x32_bf16 v[110:113], v[118:121], v[174:177], v[110:113]
	v_mfma_f32_16x16x32_bf16 v[106:109], v[134:137], v[174:177], v[106:109]
	v_mfma_f32_16x16x32_bf16 v[94:97], v[118:121], v[182:185], v[94:97]
	v_mfma_f32_16x16x32_bf16 v[90:93], v[134:137], v[182:185], v[90:93]
	v_mfma_f32_16x16x32_bf16 v[78:81], v[118:121], v[190:193], v[78:81]
	v_mfma_f32_16x16x32_bf16 v[74:77], v[134:137], v[190:193], v[74:77]
	s_setprio 0
	s_setprio 1
	v_mfma_f32_16x16x32_bf16 v[126:129], v[138:141], v[162:165], v[126:129]
	v_mfma_f32_16x16x32_bf16 v[122:125], v[146:149], v[162:165], v[122:125]
	v_mfma_f32_16x16x32_bf16 v[102:105], v[138:141], v[170:173], v[102:105]
	v_mfma_f32_16x16x32_bf16 v[98:101], v[146:149], v[170:173], v[98:101]
	v_mfma_f32_16x16x32_bf16 v[86:89], v[138:141], v[178:181], v[86:89]
	v_mfma_f32_16x16x32_bf16 v[82:85], v[146:149], v[178:181], v[82:85]
	v_mfma_f32_16x16x32_bf16 v[70:73], v[138:141], v[186:189], v[70:73]
	v_mfma_f32_16x16x32_bf16 v[66:69], v[146:149], v[186:189], v[66:69]
	v_mfma_f32_16x16x32_bf16 v[126:129], v[142:145], v[166:169], v[126:129]
	v_mfma_f32_16x16x32_bf16 v[122:125], v[150:153], v[166:169], v[122:125]
	v_mfma_f32_16x16x32_bf16 v[102:105], v[142:145], v[174:177], v[102:105]
	v_mfma_f32_16x16x32_bf16 v[98:101], v[150:153], v[174:177], v[98:101]
	v_mfma_f32_16x16x32_bf16 v[86:89], v[142:145], v[182:185], v[86:89]
	v_mfma_f32_16x16x32_bf16 v[82:85], v[150:153], v[182:185], v[82:85]
	v_mfma_f32_16x16x32_bf16 v[70:73], v[142:145], v[190:193], v[70:73]
	v_mfma_f32_16x16x32_bf16 v[66:69], v[150:153], v[190:193], v[66:69]
	s_setprio 0
	s_barrier
; #define PG8_STAGE(bufoff, gbase, voff) do { _Pragma("unroll") for (int _i = 0; _i < 2; ++_i) \
;         __builtin_amdgcn_global_load_lds((const unsigned*)((const char*)(gbase) + (voff)[_i]), (PG8_LAS unsigned*)(lds + (bufoff) + ldsw + _i * 8192), 16, 0, 0); } while (0)
; #define PG8_LDA(dst, b, h) do { _Pragma("unroll") for (int m = 0; m < 4; ++m) _Pragma("unroll") for (int k = 0; k < 2; ++k) dst[m][k] = *(const PG8_LAS bf16x8*)(lds + PG8_SA(b, h) + aoff + m * 2048 + k * 1024); } while (0)
; #define PG8_LDB(dst, b, h) do { _Pragma("unroll") for (int n = 0; n < 2; ++n) _Pragma("unroll") for (int k = 0; k < 2; ++k) dst[n][k] = *(const PG8_LAS bf16x8*)(lds + PG8_SB(b, h) + boff + n * 2048 + k * 1024); } while (0)
; #define PG8_MMA(ai, bj, At, Bt) do { __builtin_amdgcn_s_setprio(1); _Pragma("unroll") for (int m = 0; m < 4; ++m) _Pragma("unroll") for (int n = 0; n < 2; ++n) _Pragma("unroll") for (int k = 0; k < 2; ++k) \
;         acc[ai][bj][m][n] = __builtin_amdgcn_mfma_f32_16x16x32_bf16(Bt[n][k], At[m][k], acc[ai][bj][m][n], 0, 0, 0); __builtin_amdgcn_s_setprio(0); } while (0)
; #define PG8_BAR __builtin_amdgcn_s_barrier()
; template <class Epi, class Sched, bool ALIGN_EPI = false, bool SP2 = false>
; __device__ __forceinline__ void gemm_phase(PG8_LAS unsigned char* lds, const Gemm g, const Sched& S, const Epi& E, const int wave_id) {
;     ...
;             PG8_LDB(B0, 0, 0); PG8_LDB(B1, 0, 1); PG8_SCHED; PG8_LDA(At, 0, 0); PG8_STAGE(PG8_SA(1, 1), a1 + hstep, voffA);
;             PG8_WAIT_V(8); PG8_WAIT_L(0); PG8_BAR; PG8_MMA(0, 0, At, B0); PG8_MMA(0, 1, At, B1); PG8_BAR; PG8_SCHED;
;             PG8_LDA(At, 0, 1); PG8_STAGE(PG8_SB(0, 0), b2, voffB); PG8_STAGE(PG8_SB(0, 1), b2 + hstep, voffB); PG8_STAGE(PG8_SA(0, 0), a2, voffA);
;             PG8_WAIT_V(8); PG8_WAIT_L(0); PG8_BAR; PG8_MMA(1, 0, At, B0); PG8_MMA(1, 1, At, B1); PG8_BAR; PG8_SCHED;
;             PG8_LDB(B0, 1, 0); PG8_LDB(B1, 1, 1); PG8_SCHED; PG8_LDA(At, 1, 0); PG8_STAGE(PG8_SA(0, 1), a2 + hstep, voffA);
;             PG8_WAIT_V(8); PG8_WAIT_L(0); PG8_BAR; PG8_MMA(0, 0, At, B0); PG8_MMA(0, 1, At, B1); PG8_BAR; PG8_SCHED;
;             PG8_LDA(At, 1, 1); PG8_STAGE(PG8_SB(1, 0), b3, voffB); PG8_STAGE(PG8_SB(1, 1), b3 + hstep, voffB); PG8_STAGE(PG8_SA(1, 0), a3, voffA);
;             PG8_WAIT_V(8); PG8_WAIT_L(0); PG8_BAR; PG8_MMA(1, 0, At, B0); PG8_MMA(1, 1, At, B1); PG8_BAR; PG8_SCHED;
	s_add_u32 vcc_lo, s82, 0xfff80080
	s_addc_u32 vcc_hi, s83, -1
	s_mov_b32 m0, s76
	s_nop 0
	global_load_lds_dwordx4 v206, vcc
	ds_read_b128 v[162:165], v244 offset:49152
	ds_read_b128 v[166:169], v244 offset:50176
	s_mov_b32 m0, s77
	s_add_i32 s82, s85, s69
	global_load_lds_dwordx4 v210, vcc
	ds_read_b128 v[170:173], v244 offset:51200
	ds_read_b128 v[174:177], v244 offset:52224
	s_add_u32 vcc_lo, s52, 0x80
	s_addc_u32 vcc_hi, s53, 0
	s_mov_b32 m0, s82
	s_nop 0
	global_load_lds_dwordx4 v208, vcc
	ds_read_b128 v[178:181], v244 offset:53248
	ds_read_b128 v[182:185], v244 offset:54272
	s_add_i32 m0, s82, 0x2000
	s_add_u32 s52, s52, 0x80080
	s_addc_u32 s53, s53, 0
	global_load_lds_dwordx4 v212, vcc
	ds_read_b128 v[186:189], v244 offset:55296
	ds_read_b128 v[190:193], v244 offset:56320
	s_add_i32 s82, s88, s69
	s_mov_b32 m0, s82
	s_nop 0
	global_load_lds_dwordx4 v208, s[52:53]
	s_add_i32 m0, s82, 0x2000
	s_nop 0
	global_load_lds_dwordx4 v212, s[52:53]
	s_waitcnt vmcnt(8)
	s_waitcnt lgkmcnt(0)
	s_barrier
	s_setprio 1
	s_waitcnt lgkmcnt(0)
	v_mfma_f32_16x16x32_bf16 v[62:65], v[114:117], v[162:165], v[62:65]
	v_mfma_f32_16x16x32_bf16 v[58:61], v[130:133], v[162:165], v[58:61]
	v_mfma_f32_16x16x32_bf16 v[46:49], v[114:117], v[170:173], v[46:49]
	v_mfma_f32_16x16x32_bf16 v[42:45], v[130:133], v[170:173], v[42:45]
	v_mfma_f32_16x16x32_bf16 v[30:33], v[114:117], v[178:181], v[30:33]
	v_mfma_f32_16x16x32_bf16 v[26:29], v[130:133], v[178:181], v[26:29]
	v_mfma_f32_16x16x32_bf16 v[14:17], v[114:117], v[186:189], v[14:17]
	v_mfma_f32_16x16x32_bf16 v[10:13], v[130:133], v[186:189], v[10:13]
	v_mfma_f32_16x16x32_bf16 v[62:65], v[118:121], v[166:169], v[62:65]
	v_mfma_f32_16x16x32_bf16 v[58:61], v[134:137], v[166:169], v[58:61]
	v_mfma_f32_16x16x32_bf16 v[46:49], v[118:121], v[174:177], v[46:49]
	v_mfma_f32_16x16x32_bf16 v[42:45], v[134:137], v[174:177], v[42:45]
	v_mfma_f32_16x16x32_bf16 v[30:33], v[118:121], v[182:185], v[30:33]
	v_mfma_f32_16x16x32_bf16 v[26:29], v[134:137], v[182:185], v[26:29]
	v_mfma_f32_16x16x32_bf16 v[14:17], v[118:121], v[190:193], v[14:17]
	v_mfma_f32_16x16x32_bf16 v[10:13], v[134:137], v[190:193], v[10:13]
	s_setprio 0
	s_setprio 1
	v_mfma_f32_16x16x32_bf16 v[54:57], v[138:141], v[162:165], v[54:57]
	v_mfma_f32_16x16x32_bf16 v[50:53], v[146:149], v[162:165], v[50:53]
	v_mfma_f32_16x16x32_bf16 v[38:41], v[138:141], v[170:173], v[38:41]
	v_mfma_f32_16x16x32_bf16 v[34:37], v[146:149], v[170:173], v[34:37]
	v_mfma_f32_16x16x32_bf16 v[22:25], v[138:141], v[178:181], v[22:25]
	v_mfma_f32_16x16x32_bf16 v[18:21], v[146:149], v[178:181], v[18:21]
	v_mfma_f32_16x16x32_bf16 v[6:9], v[138:141], v[186:189], v[6:9]
	v_mfma_f32_16x16x32_bf16 v[2:5], v[146:149], v[186:189], v[2:5]
	v_mfma_f32_16x16x32_bf16 v[54:57], v[142:145], v[166:169], v[54:57]
	v_mfma_f32_16x16x32_bf16 v[50:53], v[150:153], v[166:169], v[50:53]
	v_mfma_f32_16x16x32_bf16 v[38:41], v[142:145], v[174:177], v[38:41]
	v_mfma_f32_16x16x32_bf16 v[34:37], v[150:153], v[174:177], v[34:37]
	v_mfma_f32_16x16x32_bf16 v[22:25], v[142:145], v[182:185], v[22:25]
	v_mfma_f32_16x16x32_bf16 v[18:21], v[150:153], v[182:185], v[18:21]
	v_mfma_f32_16x16x32_bf16 v[6:9], v[142:145], v[190:193], v[6:9]
	v_mfma_f32_16x16x32_bf16 v[2:5], v[150:153], v[190:193], v[2:5]
	s_setprio 0
	s_barrier
	s_add_i32 s84, s84, 2
	s_add_u32 s46, s46, 0x100
	s_addc_u32 s47, s47, 0
	s_add_u32 s80, s80, 0x100
	s_addc_u32 s81, s81, 0
	s_cmp_gt_u32 s84, 29
	s_cbranch_scc1 .Lpeel_exit_g5
.LBB0_904:
	s_add_u32 s52, s46, 0xfff80080
	s_addc_u32 s53, s47, -1
	s_add_i32 s85, 0, 0x10000
	s_cmp_eq_u32 s84, 28
	s_cselect_b32 s83, s21, s53
	s_cselect_b32 s82, s49, s52
	s_cselect_b32 s53, s19, s81
	s_cselect_b32 s52, s79, s80
	s_add_i32 s92, 0, 0x14000
	s_add_i32 m0, s70, 0xc000
	s_nop 0
	global_load_lds_dwordx4 v214, s[46:47]
	ds_read_b128 v[114:117], v226
	ds_read_b128 v[118:121], v226 offset:1024
	ds_read_b128 v[130:133], v226 offset:2048
	ds_read_b128 v[134:137], v226 offset:3072
	ds_read_b128 v[138:141], v226 offset:16384
	ds_read_b128 v[142:145], v226 offset:17408
	ds_read_b128 v[146:149], v226 offset:18432
	ds_read_b128 v[150:153], v226 offset:19456
	s_add_i32 m0, s70, 0xe000
	s_nop 0
	global_load_lds_dwordx4 v216, s[46:47]
	ds_read_b128 v[162:165], v244
	ds_read_b128 v[166:169], v244 offset:1024
	ds_read_b128 v[170:173], v244 offset:2048
	ds_read_b128 v[174:177], v244 offset:3072
	ds_read_b128 v[178:181], v244 offset:4096
	ds_read_b128 v[182:185], v244 offset:5120
	ds_read_b128 v[186:189], v244 offset:6144
	ds_read_b128 v[190:193], v244 offset:7168
	s_waitcnt vmcnt(8)
	s_waitcnt lgkmcnt(0)
	s_barrier
; #define PG8_STAGE(bufoff, gbase, voff) do { _Pragma("unroll") for (int _i = 0; _i < 2; ++_i) \
;         __builtin_amdgcn_global_load_lds((const unsigned*)((const char*)(gbase) + (voff)[_i]), (PG8_LAS unsigned*)(lds + (bufoff) + ldsw + _i * 8192), 16, 0, 0); } while (0)
; #define PG8_LDA(dst, b, h) do { _Pragma("unroll") for (int m = 0; m < 4; ++m) _Pragma("unroll") for (int k = 0; k < 2; ++k) dst[m][k] = *(const PG8_LAS bf16x8*)(lds + PG8_SA(b, h) + aoff + m * 2048 + k * 1024); } while (0)
; #define PG8_LDB(dst, b, h) do { _Pragma("unroll") for (int n = 0; n < 2; ++n) _Pragma("unroll") for (int k = 0; k < 2; ++k) dst[n][k] = *(const PG8_LAS bf16x8*)(lds + PG8_SB(b, h) + boff + n * 2048 + k * 1024); } while (0)
; #define PG8_MMA(ai, bj, At, Bt) do { __builtin_amdgcn_s_setprio(1); _Pragma("unroll") for (int m = 0; m < 4; ++m) _Pragma("unroll") for (int n = 0; n < 2; ++n) _Pragma("unroll") for (int k = 0; k < 2; ++k) \
;         acc[ai][bj][m][n] = __builtin_amdgcn_mfma_f32_16x16x32_bf16(Bt[n][k], At[m][k], acc[ai][bj][m][n], 0, 0, 0); __builtin_amdgcn_s_setprio(0); } while (0)
; #define PG8_WAIT_V(n) asm volatile("s_waitcnt vmcnt(" #n ")" ::: "memory")
; #define PG8_WAIT_L(n) asm volatile("s_waitcnt lgkmcnt(" #n ")" ::: "memory")
; #define PG8_BAR __builtin_amdgcn_s_barrier()
; #define PG8_SCHED __builtin_amdgcn_sched_barrier(0)
; template <class Epi, class Sched, bool ALIGN_EPI = false, bool SP2 = false>
; __device__ __forceinline__ void gemm_phase(PG8_LAS unsigned char* lds, const Gemm g, const Sched& S, const Epi& E, const int wave_id) {
;     ...
;             PG8_LDB(B0, 0, 0); PG8_LDB(B1, 0, 1); PG8_SCHED; PG8_LDA(At, 0, 0); PG8_STAGE(PG8_SA(1, 1), a1 + hstep, voffA);
;             PG8_WAIT_V(8); PG8_WAIT_L(0); PG8_BAR; PG8_MMA(0, 0, At, B0); PG8_MMA(0, 1, At, B1); PG8_BAR; PG8_SCHED;
;             PG8_LDA(At, 0, 1); PG8_STAGE(PG8_SB(0, 0), b2, voffB); PG8_STAGE(PG8_SB(0, 1), b2 + hstep, voffB); PG8_STAGE(PG8_SA(0, 0), a2, voffA);
;             PG8_WAIT_V(8); PG8_WAIT_L(0); PG8_BAR; PG8_MMA(1, 0, At, B0); PG8_MMA(1, 1, At, B1); PG8_BAR; PG8_SCHED;
;             PG8_LDB(B0, 1, 0); PG8_LDB(B1, 1, 1); PG8_SCHED; PG8_LDA(At, 1, 0); PG8_STAGE(PG8_SA(0, 1), a2 + hstep, voffA);
;             PG8_WAIT_V(8); PG8_WAIT_L(0); PG8_BAR; PG8_MMA(0, 0, At, B0); PG8_MMA(0, 1, At, B1); PG8_BAR; PG8_SCHED;
	s_setprio 1
	s_waitcnt lgkmcnt(0)
	v_mfma_f32_16x16x32_bf16 v[158:161], v[114:117], v[162:165], v[158:161]
	v_mfma_f32_16x16x32_bf16 v[154:157], v[130:133], v[162:165], v[154:157]
	v_mfma_f32_16x16x32_bf16 v[110:113], v[114:117], v[170:173], v[110:113]
	v_mfma_f32_16x16x32_bf16 v[106:109], v[130:133], v[170:173], v[106:109]
	v_mfma_f32_16x16x32_bf16 v[94:97], v[114:117], v[178:181], v[94:97]
	v_mfma_f32_16x16x32_bf16 v[90:93], v[130:133], v[178:181], v[90:93]
	v_mfma_f32_16x16x32_bf16 v[78:81], v[114:117], v[186:189], v[78:81]
	v_mfma_f32_16x16x32_bf16 v[74:77], v[130:133], v[186:189], v[74:77]
	v_mfma_f32_16x16x32_bf16 v[158:161], v[118:121], v[166:169], v[158:161]
	v_mfma_f32_16x16x32_bf16 v[154:157], v[134:137], v[166:169], v[154:157]
	v_mfma_f32_16x16x32_bf16 v[110:113], v[118:121], v[174:177], v[110:113]
	v_mfma_f32_16x16x32_bf16 v[106:109], v[134:137], v[174:177], v[106:109]
	v_mfma_f32_16x16x32_bf16 v[94:97], v[118:121], v[182:185], v[94:97]
	v_mfma_f32_16x16x32_bf16 v[90:93], v[134:137], v[182:185], v[90:93]
	v_mfma_f32_16x16x32_bf16 v[78:81], v[118:121], v[190:193], v[78:81]
	v_mfma_f32_16x16x32_bf16 v[74:77], v[134:137], v[190:193], v[74:77]
	s_setprio 0
	s_setprio 1
	v_mfma_f32_16x16x32_bf16 v[126:129], v[138:141], v[162:165], v[126:129]
	v_mfma_f32_16x16x32_bf16 v[122:125], v[146:149], v[162:165], v[122:125]
	v_mfma_f32_16x16x32_bf16 v[102:105], v[138:141], v[170:173], v[102:105]
	v_mfma_f32_16x16x32_bf16 v[98:101], v[146:149], v[170:173], v[98:101]
	v_mfma_f32_16x16x32_bf16 v[86:89], v[138:141], v[178:181], v[86:89]
	v_mfma_f32_16x16x32_bf16 v[82:85], v[146:149], v[178:181], v[82:85]
	v_mfma_f32_16x16x32_bf16 v[70:73], v[138:141], v[186:189], v[70:73]
	v_mfma_f32_16x16x32_bf16 v[66:69], v[146:149], v[186:189], v[66:69]
	v_mfma_f32_16x16x32_bf16 v[126:129], v[142:145], v[166:169], v[126:129]
	v_mfma_f32_16x16x32_bf16 v[122:125], v[150:153], v[166:169], v[122:125]
	v_mfma_f32_16x16x32_bf16 v[102:105], v[142:145], v[174:177], v[102:105]
	v_mfma_f32_16x16x32_bf16 v[98:101], v[150:153], v[174:177], v[98:101]
	v_mfma_f32_16x16x32_bf16 v[86:89], v[142:145], v[182:185], v[86:89]
	v_mfma_f32_16x16x32_bf16 v[82:85], v[150:153], v[182:185], v[82:85]
	v_mfma_f32_16x16x32_bf16 v[70:73], v[142:145], v[190:193], v[70:73]
	v_mfma_f32_16x16x32_bf16 v[66:69], v[150:153], v[190:193], v[66:69]
	s_setprio 0
	s_barrier
	s_add_i32 s85, s85, s69
	s_mov_b32 m0, s85
	s_nop 0
	global_load_lds_dwordx4 v208, s[52:53]
	ds_read_b128 v[162:165], v244 offset:16384
	ds_read_b128 v[166:169], v244 offset:17408
	s_add_i32 m0, s85, 0x2000
	s_add_u32 s88, s52, 0x80000
	s_addc_u32 s89, s53, 0
	s_add_i32 s85, s92, s69
	global_load_lds_dwordx4 v212, s[52:53]
	ds_read_b128 v[170:173], v244 offset:18432
	ds_read_b128 v[174:177], v244 offset:19456
	s_mov_b32 m0, s85
	s_nop 0
	global_load_lds_dwordx4 v208, s[88:89]
	ds_read_b128 v[178:181], v244 offset:20480
	ds_read_b128 v[182:185], v244 offset:21504
	s_add_i32 m0, s85, 0x2000
	s_nop 0
	global_load_lds_dwordx4 v212, s[88:89]
	ds_read_b128 v[186:189], v244 offset:22528
	ds_read_b128 v[190:193], v244 offset:23552
	s_mov_b32 m0, s70
	s_nop 0
	global_load_lds_dwordx4 v206, s[82:83]
	s_mov_b32 m0, s71
	s_nop 0
	global_load_lds_dwordx4 v210, s[82:83]
	s_waitcnt vmcnt(8)
	s_waitcnt lgkmcnt(0)
	s_barrier
	s_setprio 1
	s_waitcnt lgkmcnt(0)
	v_mfma_f32_16x16x32_bf16 v[62:65], v[114:117], v[162:165], v[62:65]
	v_mfma_f32_16x16x32_bf16 v[58:61], v[130:133], v[162:165], v[58:61]
	v_mfma_f32_16x16x32_bf16 v[46:49], v[114:117], v[170:173], v[46:49]
	v_mfma_f32_16x16x32_bf16 v[42:45], v[130:133], v[170:173], v[42:45]
	v_mfma_f32_16x16x32_bf16 v[30:33], v[114:117], v[178:181], v[30:33]
	v_mfma_f32_16x16x32_bf16 v[26:29], v[130:133], v[178:181], v[26:29]
	v_mfma_f32_16x16x32_bf16 v[14:17], v[114:117], v[186:189], v[14:17]
	v_mfma_f32_16x16x32_bf16 v[10:13], v[130:133], v[186:189], v[10:13]
	v_mfma_f32_16x16x32_bf16 v[62:65], v[118:121], v[166:169], v[62:65]
	v_mfma_f32_16x16x32_bf16 v[58:61], v[134:137], v[166:169], v[58:61]
	v_mfma_f32_16x16x32_bf16 v[46:49], v[118:121], v[174:177], v[46:49]
	v_mfma_f32_16x16x32_bf16 v[42:45], v[134:137], v[174:177], v[42:45]
	v_mfma_f32_16x16x32_bf16 v[30:33], v[118:121], v[182:185], v[30:33]
	v_mfma_f32_16x16x32_bf16 v[26:29], v[134:137], v[182:185], v[26:29]
	v_mfma_f32_16x16x32_bf16 v[14:17], v[118:121], v[190:193], v[14:17]
	v_mfma_f32_16x16x32_bf16 v[10:13], v[134:137], v[190:193], v[10:13]
	s_setprio 0
	s_setprio 1
	v_mfma_f32_16x16x32_bf16 v[54:57], v[138:141], v[162:165], v[54:57]
	v_mfma_f32_16x16x32_bf16 v[50:53], v[146:149], v[162:165], v[50:53]
	v_mfma_f32_16x16x32_bf16 v[38:41], v[138:141], v[170:173], v[38:41]
	v_mfma_f32_16x16x32_bf16 v[34:37], v[146:149], v[170:173], v[34:37]
	v_mfma_f32_16x16x32_bf16 v[22:25], v[138:141], v[178:181], v[22:25]
	v_mfma_f32_16x16x32_bf16 v[18:21], v[146:149], v[178:181], v[18:21]
	v_mfma_f32_16x16x32_bf16 v[6:9], v[138:141], v[186:189], v[6:9]
	v_mfma_f32_16x16x32_bf16 v[2:5], v[146:149], v[186:189], v[2:5]
	v_mfma_f32_16x16x32_bf16 v[54:57], v[142:145], v[166:169], v[54:57]
	v_mfma_f32_16x16x32_bf16 v[50:53], v[150:153], v[166:169], v[50:53]
	v_mfma_f32_16x16x32_bf16 v[38:41], v[142:145], v[174:177], v[38:41]
	v_mfma_f32_16x16x32_bf16 v[34:37], v[150:153], v[174:177], v[34:37]
	v_mfma_f32_16x16x32_bf16 v[22:25], v[142:145], v[182:185], v[22:25]
	v_mfma_f32_16x16x32_bf16 v[18:21], v[150:153], v[182:185], v[18:21]
	v_mfma_f32_16x16x32_bf16 v[6:9], v[142:145], v[190:193], v[6:9]
	v_mfma_f32_16x16x32_bf16 v[2:5], v[150:153], v[190:193], v[2:5]
	s_setprio 0
	s_barrier
; #define PG8_STAGE(bufoff, gbase, voff) do { _Pragma("unroll") for (int _i = 0; _i < 2; ++_i) \
;         __builtin_amdgcn_global_load_lds((const unsigned*)((const char*)(gbase) + (voff)[_i]), (PG8_LAS unsigned*)(lds + (bufoff) + ldsw + _i * 8192), 16, 0, 0); } while (0)
; #define PG8_LDA(dst, b, h) do { _Pragma("unroll") for (int m = 0; m < 4; ++m) _Pragma("unroll") for (int k = 0; k < 2; ++k) dst[m][k] = *(const PG8_LAS bf16x8*)(lds + PG8_SA(b, h) + aoff + m * 2048 + k * 1024); } while (0)
; #define PG8_MMA(ai, bj, At, Bt) do { __builtin_amdgcn_s_setprio(1); _Pragma("unroll") for (int m = 0; m < 4; ++m) _Pragma("unroll") for (int n = 0; n < 2; ++n) _Pragma("unroll") for (int k = 0; k < 2; ++k) \
;         acc[ai][bj][m][n] = __builtin_amdgcn_mfma_f32_16x16x32_bf16(Bt[n][k], At[m][k], acc[ai][bj][m][n], 0, 0, 0); __builtin_amdgcn_s_setprio(0); } while (0)
; #define PG8_WAIT_V(n) asm volatile("s_waitcnt vmcnt(" #n ")" ::: "memory")
; #define PG8_WAIT_L(n) asm volatile("s_waitcnt lgkmcnt(" #n ")" ::: "memory")
; #define PG8_BAR __builtin_amdgcn_s_barrier()
; #define PG8_SCHED __builtin_amdgcn_sched_barrier(0)
; template <class Epi, class Sched, bool ALIGN_EPI = false, bool SP2 = false>
; __device__ __forceinline__ void gemm_phase(PG8_LAS unsigned char* lds, const Gemm g, const Sched& S, const Epi& E, const int wave_id) {
;     ...
;             PG8_LDA(At, 1, 1); PG8_STAGE(PG8_SB(1, 0), b3, voffB); PG8_STAGE(PG8_SB(1, 1), b3 + hstep, voffB); PG8_STAGE(PG8_SA(1, 0), a3, voffA);
;             PG8_WAIT_V(8); PG8_WAIT_L(0); PG8_BAR; PG8_MMA(1, 0, At, B0); PG8_MMA(1, 1, At, B1); PG8_BAR; PG8_SCHED;
;     ...
;         if constexpr (ALIGN_EPI) { if (wr == 0) PG8_BAR; }
	s_add_i32 s85, 0, 0x18000
	s_add_i32 s88, 0, 0x1c000
	s_add_u32 s82, s82, 0x80000
	s_addc_u32 s83, s83, 0
	s_mov_b32 m0, s72
	s_nop 0
	global_load_lds_dwordx4 v206, s[82:83]
	ds_read_b128 v[114:117], v226 offset:32768
	ds_read_b128 v[118:121], v226 offset:33792
	ds_read_b128 v[130:133], v226 offset:34816
	ds_read_b128 v[134:137], v226 offset:35840
	ds_read_b128 v[138:141], v226 offset:49152
	ds_read_b128 v[142:145], v226 offset:50176
	ds_read_b128 v[146:149], v226 offset:51200
	ds_read_b128 v[150:153], v226 offset:52224
	s_mov_b32 m0, s73
	s_nop 0
	global_load_lds_dwordx4 v210, s[82:83]
	ds_read_b128 v[162:165], v244 offset:32768
	ds_read_b128 v[166:169], v244 offset:33792
	ds_read_b128 v[170:173], v244 offset:34816
	ds_read_b128 v[174:177], v244 offset:35840
	ds_read_b128 v[178:181], v244 offset:36864
	ds_read_b128 v[182:185], v244 offset:37888
	ds_read_b128 v[186:189], v244 offset:38912
	ds_read_b128 v[190:193], v244 offset:39936
	s_waitcnt vmcnt(8)
	s_waitcnt lgkmcnt(0)
	s_barrier
	s_setprio 1
	s_waitcnt lgkmcnt(0)
	v_mfma_f32_16x16x32_bf16 v[158:161], v[114:117], v[162:165], v[158:161]
	v_mfma_f32_16x16x32_bf16 v[154:157], v[130:133], v[162:165], v[154:157]
	v_mfma_f32_16x16x32_bf16 v[110:113], v[114:117], v[170:173], v[110:113]
	v_mfma_f32_16x16x32_bf16 v[106:109], v[130:133], v[170:173], v[106:109]
	v_mfma_f32_16x16x32_bf16 v[94:97], v[114:117], v[178:181], v[94:97]
	v_mfma_f32_16x16x32_bf16 v[90:93], v[130:133], v[178:181], v[90:93]
	v_mfma_f32_16x16x32_bf16 v[78:81], v[114:117], v[186:189], v[78:81]
	v_mfma_f32_16x16x32_bf16 v[74:77], v[130:133], v[186:189], v[74:77]
	v_mfma_f32_16x16x32_bf16 v[158:161], v[118:121], v[166:169], v[158:161]
	v_mfma_f32_16x16x32_bf16 v[154:157], v[134:137], v[166:169], v[154:157]
	v_mfma_f32_16x16x32_bf16 v[110:113], v[118:121], v[174:177], v[110:113]
	v_mfma_f32_16x16x32_bf16 v[106:109], v[134:137], v[174:177], v[106:109]
	v_mfma_f32_16x16x32_bf16 v[94:97], v[118:121], v[182:185], v[94:97]
	v_mfma_f32_16x16x32_bf16 v[90:93], v[134:137], v[182:185], v[90:93]
	v_mfma_f32_16x16x32_bf16 v[78:81], v[118:121], v[190:193], v[78:81]
	v_mfma_f32_16x16x32_bf16 v[74:77], v[134:137], v[190:193], v[74:77]
	s_setprio 0
	s_setprio 1
	v_mfma_f32_16x16x32_bf16 v[126:129], v[138:141], v[162:165], v[126:129]
	v_mfma_f32_16x16x32_bf16 v[122:125], v[146:149], v[162:165], v[122:125]
	v_mfma_f32_16x16x32_bf16 v[102:105], v[138:141], v[170:173], v[102:105]
	v_mfma_f32_16x16x32_bf16 v[98:101], v[146:149], v[170:173], v[98:101]
	v_mfma_f32_16x16x32_bf16 v[86:89], v[138:141], v[178:181], v[86:89]
	v_mfma_f32_16x16x32_bf16 v[82:85], v[146:149], v[178:181], v[82:85]
	v_mfma_f32_16x16x32_bf16 v[70:73], v[138:141], v[186:189], v[70:73]
	v_mfma_f32_16x16x32_bf16 v[66:69], v[146:149], v[186:189], v[66:69]
	v_mfma_f32_16x16x32_bf16 v[126:129], v[142:145], v[166:169], v[126:129]
	v_mfma_f32_16x16x32_bf16 v[122:125], v[150:153], v[166:169], v[122:125]
	v_mfma_f32_16x16x32_bf16 v[102:105], v[142:145], v[174:177], v[102:105]
	v_mfma_f32_16x16x32_bf16 v[98:101], v[150:153], v[174:177], v[98:101]
	v_mfma_f32_16x16x32_bf16 v[86:89], v[142:145], v[182:185], v[86:89]
	v_mfma_f32_16x16x32_bf16 v[82:85], v[150:153], v[182:185], v[82:85]
	v_mfma_f32_16x16x32_bf16 v[70:73], v[142:145], v[190:193], v[70:73]
	v_mfma_f32_16x16x32_bf16 v[66:69], v[150:153], v[190:193], v[66:69]
	s_setprio 0
	s_barrier
	s_add_u32 vcc_lo, s82, 0xfff80080
	s_addc_u32 vcc_hi, s83, -1
	s_mov_b32 m0, s76
	s_nop 0
	global_load_lds_dwordx4 v206, vcc
	ds_read_b128 v[162:165], v244 offset:49152
	ds_read_b128 v[166:169], v244 offset:50176
	s_mov_b32 m0, s77
	s_add_i32 s82, s85, s69
	global_load_lds_dwordx4 v210, vcc
	ds_read_b128 v[170:173], v244 offset:51200
	ds_read_b128 v[174:177], v244 offset:52224
	s_add_u32 vcc_lo, s52, 0x80
	s_addc_u32 vcc_hi, s53, 0
	s_mov_b32 m0, s82
	s_nop 0
	global_load_lds_dwordx4 v208, vcc
	ds_read_b128 v[178:181], v244 offset:53248
	ds_read_b128 v[182:185], v244 offset:54272
	s_add_i32 m0, s82, 0x2000
	s_add_u32 s52, s52, 0x80080
	s_addc_u32 s53, s53, 0
	global_load_lds_dwordx4 v212, vcc
	ds_read_b128 v[186:189], v244 offset:55296
	ds_read_b128 v[190:193], v244 offset:56320
	s_add_i32 s82, s88, s69
	s_mov_b32 m0, s82
	s_nop 0
	global_load_lds_dwordx4 v208, s[52:53]
	s_add_i32 m0, s82, 0x2000
	s_nop 0
	global_load_lds_dwordx4 v212, s[52:53]
	s_waitcnt vmcnt(8)
	s_waitcnt lgkmcnt(0)
	s_barrier
	s_setprio 1
	s_waitcnt lgkmcnt(0)
	v_mfma_f32_16x16x32_bf16 v[62:65], v[114:117], v[162:165], v[62:65]
	v_mfma_f32_16x16x32_bf16 v[58:61], v[130:133], v[162:165], v[58:61]
	v_mfma_f32_16x16x32_bf16 v[46:49], v[114:117], v[170:173], v[46:49]
	v_mfma_f32_16x16x32_bf16 v[42:45], v[130:133], v[170:173], v[42:45]
	v_mfma_f32_16x16x32_bf16 v[30:33], v[114:117], v[178:181], v[30:33]
	v_mfma_f32_16x16x32_bf16 v[26:29], v[130:133], v[178:181], v[26:29]
	v_mfma_f32_16x16x32_bf16 v[14:17], v[114:117], v[186:189], v[14:17]
	v_mfma_f32_16x16x32_bf16 v[10:13], v[130:133], v[186:189], v[10:13]
	v_mfma_f32_16x16x32_bf16 v[62:65], v[118:121], v[166:169], v[62:65]
	v_mfma_f32_16x16x32_bf16 v[58:61], v[134:137], v[166:169], v[58:61]
	v_mfma_f32_16x16x32_bf16 v[46:49], v[118:121], v[174:177], v[46:49]
	v_mfma_f32_16x16x32_bf16 v[42:45], v[134:137], v[174:177], v[42:45]
	v_mfma_f32_16x16x32_bf16 v[30:33], v[118:121], v[182:185], v[30:33]
	v_mfma_f32_16x16x32_bf16 v[26:29], v[134:137], v[182:185], v[26:29]
	v_mfma_f32_16x16x32_bf16 v[14:17], v[118:121], v[190:193], v[14:17]
	v_mfma_f32_16x16x32_bf16 v[10:13], v[134:137], v[190:193], v[10:13]
	s_setprio 0
	s_setprio 1
	v_mfma_f32_16x16x32_bf16 v[54:57], v[138:141], v[162:165], v[54:57]
	v_mfma_f32_16x16x32_bf16 v[50:53], v[146:149], v[162:165], v[50:53]
	v_mfma_f32_16x16x32_bf16 v[38:41], v[138:141], v[170:173], v[38:41]
	v_mfma_f32_16x16x32_bf16 v[34:37], v[146:149], v[170:173], v[34:37]
	v_mfma_f32_16x16x32_bf16 v[22:25], v[138:141], v[178:181], v[22:25]
	v_mfma_f32_16x16x32_bf16 v[18:21], v[146:149], v[178:181], v[18:21]
	v_mfma_f32_16x16x32_bf16 v[6:9], v[138:141], v[186:189], v[6:9]
	v_mfma_f32_16x16x32_bf16 v[2:5], v[146:149], v[186:189], v[2:5]
	v_mfma_f32_16x16x32_bf16 v[54:57], v[142:145], v[166:169], v[54:57]
	v_mfma_f32_16x16x32_bf16 v[50:53], v[150:153], v[166:169], v[50:53]
	v_mfma_f32_16x16x32_bf16 v[38:41], v[142:145], v[174:177], v[38:41]
	v_mfma_f32_16x16x32_bf16 v[34:37], v[150:153], v[174:177], v[34:37]
	v_mfma_f32_16x16x32_bf16 v[22:25], v[142:145], v[182:185], v[22:25]
	v_mfma_f32_16x16x32_bf16 v[18:21], v[150:153], v[182:185], v[18:21]
	v_mfma_f32_16x16x32_bf16 v[6:9], v[142:145], v[190:193], v[6:9]
	v_mfma_f32_16x16x32_bf16 v[2:5], v[150:153], v[190:193], v[2:5]
	s_setprio 0
	s_barrier
	s_add_i32 s84, s84, 2
	s_add_u32 s46, s46, 0x100
	s_addc_u32 s47, s47, 0
	s_add_u32 s80, s80, 0x100
	s_addc_u32 s81, s81, 0
	s_cmp_gt_u32 s84, 29
	s_cbranch_scc0 .LBB0_904
.Lpeel_exit_g5:
	s_and_b64 vcc, exec, s[16:17]
	s_mov_b32 s50, 0x90000
	s_mov_b32 s51, 0xa0000
	s_mov_b32 s82, 0xb0000
	s_cbranch_vccz .LBB0_907
	s_barrier
